# static s_setprio 1 for waves 4-7 across each GEMM K-loop, per-segment flips removed (on v19)
# speedup vs baseline: 1.0067x; 1.0067x over previous
; #define PG8_STAGE(bufoff, gbase, voff) do { _Pragma("unroll") for (int _i = 0; _i < 2; ++_i) \
;         __builtin_amdgcn_global_load_lds((const unsigned*)((const char*)(gbase) + (voff)[_i]), (PG8_LAS unsigned*)(lds + (bufoff) + ldsw + _i * 8192), 16, 0, 0); } while (0)
; #define PG8_LDA(dst, b, h) do { _Pragma("unroll") for (int m = 0; m < 4; ++m) _Pragma("unroll") for (int k = 0; k < 2; ++k) dst[m][k] = *(const PG8_LAS bf16x8*)(lds + PG8_SA(b, h) + aoff + m * 2048 + k * 1024); } while (0)
; #define PG8_LDB(dst, b, h) do { _Pragma("unroll") for (int n = 0; n < 2; ++n) _Pragma("unroll") for (int k = 0; k < 2; ++k) dst[n][k] = *(const PG8_LAS bf16x8*)(lds + PG8_SB(b, h) + boff + n * 2048 + k * 1024); } while (0)
; #define PG8_WAIT_V(n) asm volatile("s_waitcnt vmcnt(" #n ")" ::: "memory")
; template <class Epi, class Sched, bool ALIGN_EPI = false, bool SP2 = false>
; __device__ __forceinline__ void gemm_phase(PG8_LAS unsigned char* lds, const Gemm g, const Sched& S, const Epi& E) {
;     ...
;         const bool has_next = S.next(ui + 1, nxt);
;         const char* nA = has_next ? (const char*)g.A + (size_t)nxt.pm * tstep : cA; const char* nB = has_next ? (const char*)g.Bt + (size_t)nxt.pn * tstep : cB;
;         constexpr int NSEG = (Epi::MID_T >= 0) ? 2 : 1;
; #pragma unroll 1
;         for (int seg = 0; seg < NSEG; ++seg) {
;         const int t_lo = (seg == 0) ? 0 : Epi::MID_T, t_hi = (NSEG == 2 && seg == 0) ? Epi::MID_T : nt;
;         if constexpr (Epi::MID_T >= 0) { if (seg == 1) E.mid(acc, ui, wr, fr); }
;         for (int t = t_lo; t < t_hi; t += 2) {
;             const bool last = (t == nt - 2);
;             const char* a1 = cA + (size_t)(t + 1) * kstep;
;             const char* a2 = last ? nA : cA + (size_t)(t + 2) * kstep; const char* b2 = last ? nB : cB + (size_t)(t + 2) * kstep;
;             const char* a3 = a2 + kstep; const char* b3 = b2 + kstep;
;             if (last && has_next) S.a_ready_inloop(nxt, ui + 1);
;             if constexpr (SP2) {
;             PG8_LDB(B0, 0, 0); PG8_LDB(B1, 0, 1); PG8_SCHED; PG8_LDA(At, 0, 0); PG8_STAGE(PG8_SA(1, 1), a1 + hstep, voffA);
;             PG8_WAIT_V(8); PG8_WAIT_L(0); PG8_BAR; PG8_MMA(0, 0, At, B0); PG8_MMA(0, 1, At, B1); PG8_BAR; PG8_SCHED;
;             PG8_LDA(At, 0, 1); PG8_STAGE(PG8_SB(0, 0), b2, voffB); PG8_STAGE(PG8_SB(0, 1), b2 + hstep, voffB); PG8_STAGE(PG8_SA(0, 0), a2, voffA);
.LBB0_120:
	s_ashr_i32 s13, s12, 31
	s_lshl_b64 s[16:17], s[12:13], 19
	s_add_u32 s16, s28, s16
	s_addc_u32 s17, s29, s17
	s_and_b64 s[18:19], s[2:3], exec
	s_cselect_b32 s13, s17, s21
	s_cselect_b32 s52, s16, s20
	s_ashr_i32 s15, s14, 31
	s_lshl_b64 s[18:19], s[14:15], 19
	s_add_u32 s18, s30, s18
	s_addc_u32 s19, s31, s19
	s_and_b64 s[24:25], s[2:3], exec
	s_cselect_b32 s15, s19, s23
	s_cselect_b32 s53, s18, s22
	s_add_u32 s20, s20, 0x40080
	s_addc_u32 s21, s21, 0
	s_add_u32 s62, s22, 0x100
	s_addc_u32 s63, s23, 0
	s_mov_b32 s64, -2
	v_readfirstlane_b32 s98, v204
	s_nop 3
	s_cmp_ge_u32 s98, 0x100
	s_cbranch_scc0 .Lprio_skip_0
	s_setprio 1
.Lprio_skip_0:
	s_add_u32 s22, s20, 0xfffc0080
	s_addc_u32 s23, s21, -1
	s_add_i32 s90, 0, 0x10000
	s_cmp_eq_u32 s64, 12
	s_cselect_b32 s25, s13, s23
	s_cselect_b32 s24, s52, s22
	v_add_u32_e32 v158, s90, v160
	s_cselect_b32 s23, s15, s63
	s_cselect_b32 s22, s53, s62
	s_add_u32 s98, s22, s46
	s_addc_u32 s99, s23, s47
	s_add_u32 s100, s24, s46
	s_addc_u32 s101, s25, s47
	s_add_i32 s81, 0, 0x14000
	ds_read_b128 v[164:167], v158
	ds_read_b128 v[168:171], v158 offset:1024
	ds_read_b128 v[172:175], v158 offset:2048
	ds_read_b128 v[176:179], v158 offset:3072
	v_add_u32_e32 v158, s81, v160
	ds_read_b128 v[180:183], v158
	ds_read_b128 v[184:187], v158 offset:1024
	ds_read_b128 v[188:191], v158 offset:2048
	ds_read_b128 v[192:195], v158 offset:3072
	s_add_i32 m0, s35, 0xc000
	ds_read_b128 v[196:199], v163
	ds_read_b128 v[200:203], v163 offset:1024
	ds_read_b128 v[216:219], v163 offset:2048
	ds_read_b128 v[220:223], v163 offset:3072
	ds_read_b128 v[224:227], v163 offset:4096
	ds_read_b128 v[228:231], v163 offset:5120
	ds_read_b128 v[232:235], v163 offset:6144
	ds_read_b128 v[236:239], v163 offset:7168
	global_load_lds_dwordx4 v154, s[20:21]
	s_add_i32 m0, s35, 0xe000
	s_nop 0
	global_load_lds_dwordx4 v156, s[20:21]
	s_waitcnt vmcnt(8) lgkmcnt(0)
	s_barrier
	v_mfma_f32_16x16x32_bf16 v[142:145], v[164:167], v[196:199], 0
	v_mfma_f32_16x16x32_bf16 v[138:141], v[172:175], v[196:199], 0
	v_mfma_f32_16x16x32_bf16 v[126:129], v[164:167], v[216:219], 0
	v_mfma_f32_16x16x32_bf16 v[122:125], v[172:175], v[216:219], 0
	v_mfma_f32_16x16x32_bf16 v[110:113], v[164:167], v[224:227], 0
	v_mfma_f32_16x16x32_bf16 v[106:109], v[172:175], v[224:227], 0
	v_mfma_f32_16x16x32_bf16 v[94:97], v[164:167], v[232:235], 0
	v_mfma_f32_16x16x32_bf16 v[90:93], v[172:175], v[232:235], 0
	v_mfma_f32_16x16x32_bf16 v[142:145], v[168:171], v[200:203], v[142:145]
	v_mfma_f32_16x16x32_bf16 v[138:141], v[176:179], v[200:203], v[138:141]
	v_mfma_f32_16x16x32_bf16 v[126:129], v[168:171], v[220:223], v[126:129]
	v_mfma_f32_16x16x32_bf16 v[122:125], v[176:179], v[220:223], v[122:125]
	v_mfma_f32_16x16x32_bf16 v[110:113], v[168:171], v[228:231], v[110:113]
	v_mfma_f32_16x16x32_bf16 v[106:109], v[176:179], v[228:231], v[106:109]
	v_mfma_f32_16x16x32_bf16 v[94:97], v[168:171], v[236:239], v[94:97]
	v_mfma_f32_16x16x32_bf16 v[90:93], v[176:179], v[236:239], v[90:93]
	v_mfma_f32_16x16x32_bf16 v[134:137], v[180:183], v[196:199], 0
	v_mfma_f32_16x16x32_bf16 v[130:133], v[188:191], v[196:199], 0
	v_mfma_f32_16x16x32_bf16 v[118:121], v[180:183], v[216:219], 0
	v_mfma_f32_16x16x32_bf16 v[114:117], v[188:191], v[216:219], 0
	v_mfma_f32_16x16x32_bf16 v[102:105], v[180:183], v[224:227], 0
	v_mfma_f32_16x16x32_bf16 v[98:101], v[188:191], v[224:227], 0
	v_mfma_f32_16x16x32_bf16 v[86:89], v[180:183], v[232:235], 0
	v_mfma_f32_16x16x32_bf16 v[82:85], v[188:191], v[232:235], 0
	v_mfma_f32_16x16x32_bf16 v[134:137], v[184:187], v[200:203], v[134:137]
	v_mfma_f32_16x16x32_bf16 v[130:133], v[192:195], v[200:203], v[130:133]
	v_mfma_f32_16x16x32_bf16 v[118:121], v[184:187], v[220:223], v[118:121]
	v_mfma_f32_16x16x32_bf16 v[114:117], v[192:195], v[220:223], v[114:117]
	v_mfma_f32_16x16x32_bf16 v[102:105], v[184:187], v[228:231], v[102:105]
	v_mfma_f32_16x16x32_bf16 v[98:101], v[192:195], v[228:231], v[98:101]
	v_mfma_f32_16x16x32_bf16 v[86:89], v[184:187], v[236:239], v[86:89]
	v_mfma_f32_16x16x32_bf16 v[82:85], v[192:195], v[236:239], v[82:85]
	s_barrier
	s_add_i32 s65, s90, s34
	s_mov_b32 m0, s65
	ds_read_b128 v[196:199], v163 offset:16384
	ds_read_b128 v[200:203], v163 offset:17408
	ds_read_b128 v[216:219], v163 offset:18432
	ds_read_b128 v[220:223], v163 offset:19456
	ds_read_b128 v[224:227], v163 offset:20480
	ds_read_b128 v[228:231], v163 offset:21504
	ds_read_b128 v[232:235], v163 offset:22528
	ds_read_b128 v[236:239], v163 offset:23552
	global_load_lds_dwordx4 v148, s[22:23]
	s_add_i32 m0, s65, 0x2000
	s_add_u32 s66, s22, 0x40000
	s_addc_u32 s67, s23, 0
	s_add_i32 s65, s81, s34
	global_load_lds_dwordx4 v152, s[22:23]
	s_mov_b32 m0, s65
	s_nop 0
	global_load_lds_dwordx4 v148, s[66:67]
	s_add_i32 m0, s65, 0x2000
	s_nop 0
	global_load_lds_dwordx4 v152, s[66:67]
	s_mov_b32 m0, s35
	s_nop 0
	global_load_lds_dwordx4 v146, s[24:25]
	s_mov_b32 m0, s36
	s_nop 0
	global_load_lds_dwordx4 v150, s[24:25]
	s_waitcnt vmcnt(8) lgkmcnt(0)
	s_barrier
; #define PG8_STAGE(bufoff, gbase, voff) do { _Pragma("unroll") for (int _i = 0; _i < 2; ++_i) \
;         __builtin_amdgcn_global_load_lds((const unsigned*)((const char*)(gbase) + (voff)[_i]), (PG8_LAS unsigned*)(lds + (bufoff) + ldsw + _i * 8192), 16, 0, 0); } while (0)
; #define PG8_LDA(dst, b, h) do { _Pragma("unroll") for (int m = 0; m < 4; ++m) _Pragma("unroll") for (int k = 0; k < 2; ++k) dst[m][k] = *(const PG8_LAS bf16x8*)(lds + PG8_SA(b, h) + aoff + m * 2048 + k * 1024); } while (0)
; #define PG8_LDB(dst, b, h) do { _Pragma("unroll") for (int n = 0; n < 2; ++n) _Pragma("unroll") for (int k = 0; k < 2; ++k) dst[n][k] = *(const PG8_LAS bf16x8*)(lds + PG8_SB(b, h) + boff + n * 2048 + k * 1024); } while (0)
; #define PG8_MMA(ai, bj, At, Bt) do { __builtin_amdgcn_s_setprio(1); _Pragma("unroll") for (int m = 0; m < 4; ++m) _Pragma("unroll") for (int n = 0; n < 2; ++n) _Pragma("unroll") for (int k = 0; k < 2; ++k) \
;         acc[ai][bj][m][n] = __builtin_amdgcn_mfma_f32_16x16x32_bf16(Bt[n][k], At[m][k], acc[ai][bj][m][n], 0, 0, 0); __builtin_amdgcn_s_setprio(0); } while (0)
; #define PG8_WAIT_V(n) asm volatile("s_waitcnt vmcnt(" #n ")" ::: "memory")
; #define PG8_WAIT_L(n) asm volatile("s_waitcnt lgkmcnt(" #n ")" ::: "memory")
; #define PG8_BAR __builtin_amdgcn_s_barrier()
; #define PG8_SCHED __builtin_amdgcn_sched_barrier(0)
; template <class Epi, class Sched, bool ALIGN_EPI = false, bool SP2 = false>
; __device__ __forceinline__ void gemm_phase(PG8_LAS unsigned char* lds, const Gemm g, const Sched& S, const Epi& E) {
;     ...
;             PG8_WAIT_V(8); PG8_WAIT_L(0); PG8_BAR; PG8_MMA(1, 0, At, B0); PG8_MMA(1, 1, At, B1); PG8_BAR; PG8_SCHED;
;             PG8_LDB(B0, 1, 0); PG8_LDB(B1, 1, 1); PG8_SCHED; PG8_LDA(At, 1, 0); PG8_STAGE(PG8_SA(0, 1), a2 + hstep, voffA);
;             PG8_WAIT_V(8); PG8_WAIT_L(0); PG8_BAR; PG8_MMA(0, 0, At, B0); PG8_MMA(0, 1, At, B1); PG8_BAR; PG8_SCHED;
	v_mfma_f32_16x16x32_bf16 v[78:81], v[164:167], v[196:199], 0
	v_mfma_f32_16x16x32_bf16 v[74:77], v[172:175], v[196:199], 0
	v_mfma_f32_16x16x32_bf16 v[62:65], v[164:167], v[216:219], 0
	v_mfma_f32_16x16x32_bf16 v[58:61], v[172:175], v[216:219], 0
	v_mfma_f32_16x16x32_bf16 v[46:49], v[164:167], v[224:227], 0
	v_mfma_f32_16x16x32_bf16 v[42:45], v[172:175], v[224:227], 0
	v_mfma_f32_16x16x32_bf16 v[30:33], v[164:167], v[232:235], 0
	v_mfma_f32_16x16x32_bf16 v[26:29], v[172:175], v[232:235], 0
	v_mfma_f32_16x16x32_bf16 v[78:81], v[168:171], v[200:203], v[78:81]
	v_mfma_f32_16x16x32_bf16 v[74:77], v[176:179], v[200:203], v[74:77]
	v_mfma_f32_16x16x32_bf16 v[62:65], v[168:171], v[220:223], v[62:65]
	v_mfma_f32_16x16x32_bf16 v[58:61], v[176:179], v[220:223], v[58:61]
	v_mfma_f32_16x16x32_bf16 v[46:49], v[168:171], v[228:231], v[46:49]
	v_mfma_f32_16x16x32_bf16 v[42:45], v[176:179], v[228:231], v[42:45]
	v_mfma_f32_16x16x32_bf16 v[30:33], v[168:171], v[236:239], v[30:33]
	v_mfma_f32_16x16x32_bf16 v[26:29], v[176:179], v[236:239], v[26:29]
	v_mfma_f32_16x16x32_bf16 v[70:73], v[180:183], v[196:199], 0
	v_mfma_f32_16x16x32_bf16 v[66:69], v[188:191], v[196:199], 0
	v_mfma_f32_16x16x32_bf16 v[54:57], v[180:183], v[216:219], 0
	v_mfma_f32_16x16x32_bf16 v[50:53], v[188:191], v[216:219], 0
	v_mfma_f32_16x16x32_bf16 v[38:41], v[180:183], v[224:227], 0
	v_mfma_f32_16x16x32_bf16 v[34:37], v[188:191], v[224:227], 0
	v_mfma_f32_16x16x32_bf16 v[22:25], v[180:183], v[232:235], 0
	v_mfma_f32_16x16x32_bf16 v[18:21], v[188:191], v[232:235], 0
	v_mfma_f32_16x16x32_bf16 v[70:73], v[184:187], v[200:203], v[70:73]
	v_mfma_f32_16x16x32_bf16 v[66:69], v[192:195], v[200:203], v[66:69]
	v_mfma_f32_16x16x32_bf16 v[54:57], v[184:187], v[220:223], v[54:57]
	v_mfma_f32_16x16x32_bf16 v[50:53], v[192:195], v[220:223], v[50:53]
	v_mfma_f32_16x16x32_bf16 v[38:41], v[184:187], v[228:231], v[38:41]
	v_mfma_f32_16x16x32_bf16 v[34:37], v[192:195], v[228:231], v[34:37]
	v_mfma_f32_16x16x32_bf16 v[22:25], v[184:187], v[236:239], v[22:25]
	v_mfma_f32_16x16x32_bf16 v[18:21], v[192:195], v[236:239], v[18:21]
	s_barrier
	s_add_i32 s82, 0, 0x18000
	s_add_i32 s83, 0, 0x1c000
	v_add_u32_e32 v176, s82, v160
	v_add_u32_e32 v192, s83, v160
	ds_read_b128 v[164:167], v176
	ds_read_b128 v[168:171], v176 offset:1024
	ds_read_b128 v[172:175], v176 offset:2048
	ds_read_b128 v[176:179], v176 offset:3072
	ds_read_b128 v[180:183], v192
	ds_read_b128 v[184:187], v192 offset:1024
	ds_read_b128 v[188:191], v192 offset:2048
	ds_read_b128 v[192:195], v192 offset:3072
	s_add_u32 s24, s24, 0x40000
	s_addc_u32 s25, s25, 0
	s_mov_b32 m0, s37
	ds_read_b128 v[196:199], v163 offset:32768
	ds_read_b128 v[200:203], v163 offset:33792
	ds_read_b128 v[216:219], v163 offset:34816
	ds_read_b128 v[220:223], v163 offset:35840
	ds_read_b128 v[224:227], v163 offset:36864
	ds_read_b128 v[228:231], v163 offset:37888
	ds_read_b128 v[232:235], v163 offset:38912
	ds_read_b128 v[236:239], v163 offset:39936
	global_load_lds_dwordx4 v146, s[24:25]
	s_mov_b32 m0, s38
	s_nop 0
	global_load_lds_dwordx4 v150, s[24:25]
	s_waitcnt vmcnt(8) lgkmcnt(0)
	s_barrier
	v_mfma_f32_16x16x32_bf16 v[142:145], v[164:167], v[196:199], v[142:145]
	v_mfma_f32_16x16x32_bf16 v[138:141], v[172:175], v[196:199], v[138:141]
	v_mfma_f32_16x16x32_bf16 v[126:129], v[164:167], v[216:219], v[126:129]
	v_mfma_f32_16x16x32_bf16 v[122:125], v[172:175], v[216:219], v[122:125]
	v_mfma_f32_16x16x32_bf16 v[110:113], v[164:167], v[224:227], v[110:113]
	v_mfma_f32_16x16x32_bf16 v[106:109], v[172:175], v[224:227], v[106:109]
	v_mfma_f32_16x16x32_bf16 v[94:97], v[164:167], v[232:235], v[94:97]
	v_mfma_f32_16x16x32_bf16 v[90:93], v[172:175], v[232:235], v[90:93]
	v_mfma_f32_16x16x32_bf16 v[142:145], v[168:171], v[200:203], v[142:145]
	v_mfma_f32_16x16x32_bf16 v[138:141], v[176:179], v[200:203], v[138:141]
	v_mfma_f32_16x16x32_bf16 v[126:129], v[168:171], v[220:223], v[126:129]
	v_mfma_f32_16x16x32_bf16 v[122:125], v[176:179], v[220:223], v[122:125]
	v_mfma_f32_16x16x32_bf16 v[110:113], v[168:171], v[228:231], v[110:113]
	v_mfma_f32_16x16x32_bf16 v[106:109], v[176:179], v[228:231], v[106:109]
	v_mfma_f32_16x16x32_bf16 v[94:97], v[168:171], v[236:239], v[94:97]
	v_mfma_f32_16x16x32_bf16 v[90:93], v[176:179], v[236:239], v[90:93]
	v_mfma_f32_16x16x32_bf16 v[134:137], v[180:183], v[196:199], v[134:137]
	v_mfma_f32_16x16x32_bf16 v[130:133], v[188:191], v[196:199], v[130:133]
	v_mfma_f32_16x16x32_bf16 v[118:121], v[180:183], v[216:219], v[118:121]
	v_mfma_f32_16x16x32_bf16 v[114:117], v[188:191], v[216:219], v[114:117]
	v_mfma_f32_16x16x32_bf16 v[102:105], v[180:183], v[224:227], v[102:105]
	v_mfma_f32_16x16x32_bf16 v[98:101], v[188:191], v[224:227], v[98:101]
	v_mfma_f32_16x16x32_bf16 v[86:89], v[180:183], v[232:235], v[86:89]
	v_mfma_f32_16x16x32_bf16 v[82:85], v[188:191], v[232:235], v[82:85]
	v_mfma_f32_16x16x32_bf16 v[134:137], v[184:187], v[200:203], v[134:137]
	v_mfma_f32_16x16x32_bf16 v[130:133], v[192:195], v[200:203], v[130:133]
	v_mfma_f32_16x16x32_bf16 v[118:121], v[184:187], v[220:223], v[118:121]
	v_mfma_f32_16x16x32_bf16 v[114:117], v[192:195], v[220:223], v[114:117]
	v_mfma_f32_16x16x32_bf16 v[102:105], v[184:187], v[228:231], v[102:105]
	v_mfma_f32_16x16x32_bf16 v[98:101], v[192:195], v[228:231], v[98:101]
	v_mfma_f32_16x16x32_bf16 v[86:89], v[184:187], v[236:239], v[86:89]
	v_mfma_f32_16x16x32_bf16 v[82:85], v[192:195], v[236:239], v[82:85]
	s_barrier
; #define PG8_STAGE(bufoff, gbase, voff) do { _Pragma("unroll") for (int _i = 0; _i < 2; ++_i) \
;         __builtin_amdgcn_global_load_lds((const unsigned*)((const char*)(gbase) + (voff)[_i]), (PG8_LAS unsigned*)(lds + (bufoff) + ldsw + _i * 8192), 16, 0, 0); } while (0)
; #define PG8_LDA(dst, b, h) do { _Pragma("unroll") for (int m = 0; m < 4; ++m) _Pragma("unroll") for (int k = 0; k < 2; ++k) dst[m][k] = *(const PG8_LAS bf16x8*)(lds + PG8_SA(b, h) + aoff + m * 2048 + k * 1024); } while (0)
; #define PG8_LDB(dst, b, h) do { _Pragma("unroll") for (int n = 0; n < 2; ++n) _Pragma("unroll") for (int k = 0; k < 2; ++k) dst[n][k] = *(const PG8_LAS bf16x8*)(lds + PG8_SB(b, h) + boff + n * 2048 + k * 1024); } while (0)
; #define PG8_MMA(ai, bj, At, Bt) do { __builtin_amdgcn_s_setprio(1); _Pragma("unroll") for (int m = 0; m < 4; ++m) _Pragma("unroll") for (int n = 0; n < 2; ++n) _Pragma("unroll") for (int k = 0; k < 2; ++k) \
;         acc[ai][bj][m][n] = __builtin_amdgcn_mfma_f32_16x16x32_bf16(Bt[n][k], At[m][k], acc[ai][bj][m][n], 0, 0, 0); __builtin_amdgcn_s_setprio(0); } while (0)
; #define PG8_WAIT_V(n) asm volatile("s_waitcnt vmcnt(" #n ")" ::: "memory")
; template <class Epi, class Sched, bool ALIGN_EPI = false, bool SP2 = false>
; __device__ __forceinline__ void gemm_phase(PG8_LAS unsigned char* lds, const Gemm g, const Sched& S, const Epi& E) {
;     ...
;             PG8_LDB(B0, 0, 0); PG8_LDB(B1, 0, 1); PG8_SCHED; PG8_LDA(At, 0, 0); PG8_STAGE(PG8_SA(1, 1), a1 + hstep, voffA);
;             PG8_WAIT_V(8); PG8_WAIT_L(0); PG8_BAR; PG8_MMA(0, 0, At, B0); PG8_MMA(0, 1, At, B1); PG8_BAR; PG8_SCHED;
;             PG8_LDA(At, 0, 1); PG8_STAGE(PG8_SB(0, 0), b2, voffB); PG8_STAGE(PG8_SB(0, 1), b2 + hstep, voffB); PG8_STAGE(PG8_SA(0, 0), a2, voffA);
;             PG8_WAIT_V(8); PG8_WAIT_L(0); PG8_BAR; PG8_MMA(1, 0, At, B0); PG8_MMA(1, 1, At, B1); PG8_BAR; PG8_SCHED;
;             PG8_LDB(B0, 1, 0); PG8_LDB(B1, 1, 1); PG8_SCHED; PG8_LDA(At, 1, 0); PG8_STAGE(PG8_SA(0, 1), a2 + hstep, voffA);
;             PG8_WAIT_V(8); PG8_WAIT_L(0); PG8_BAR; PG8_MMA(0, 0, At, B0); PG8_MMA(0, 1, At, B1); PG8_BAR; PG8_SCHED;
;             PG8_LDA(At, 1, 1); PG8_STAGE(PG8_SB(1, 0), b3, voffB); PG8_STAGE(PG8_SB(1, 1), b3 + hstep, voffB); PG8_STAGE(PG8_SA(1, 0), a3, voffA);
;             PG8_WAIT_V(8); PG8_WAIT_L(0); PG8_BAR; PG8_MMA(1, 0, At, B0); PG8_MMA(1, 1, At, B1); PG8_BAR; PG8_SCHED;
	s_add_i32 s24, s82, s34
	s_mov_b32 m0, s24
	ds_read_b128 v[196:199], v163 offset:49152
	ds_read_b128 v[200:203], v163 offset:50176
	ds_read_b128 v[216:219], v163 offset:51200
	ds_read_b128 v[220:223], v163 offset:52224
	ds_read_b128 v[224:227], v163 offset:53248
	ds_read_b128 v[228:231], v163 offset:54272
	ds_read_b128 v[232:235], v163 offset:55296
	ds_read_b128 v[236:239], v163 offset:56320
	global_load_lds_dwordx4 v148, s[98:99]
	s_add_i32 m0, s24, 0x2000
	s_add_u32 s22, s22, 0x40080
	s_addc_u32 s23, s23, 0
	s_add_i32 s24, s83, s34
	global_load_lds_dwordx4 v152, s[98:99]
	s_mov_b32 m0, s24
	s_nop 0
	global_load_lds_dwordx4 v148, s[22:23]
	s_add_i32 m0, s24, 0x2000
	s_nop 0
	global_load_lds_dwordx4 v152, s[22:23]
	s_mov_b32 m0, s39
	s_nop 0
	global_load_lds_dwordx4 v146, s[100:101]
	s_mov_b32 m0, s42
	s_nop 0
	global_load_lds_dwordx4 v150, s[100:101]
	s_waitcnt vmcnt(8) lgkmcnt(0)
	s_barrier
	v_mfma_f32_16x16x32_bf16 v[78:81], v[164:167], v[196:199], v[78:81]
	v_mfma_f32_16x16x32_bf16 v[74:77], v[172:175], v[196:199], v[74:77]
	v_mfma_f32_16x16x32_bf16 v[62:65], v[164:167], v[216:219], v[62:65]
	v_mfma_f32_16x16x32_bf16 v[58:61], v[172:175], v[216:219], v[58:61]
	v_mfma_f32_16x16x32_bf16 v[46:49], v[164:167], v[224:227], v[46:49]
	v_mfma_f32_16x16x32_bf16 v[42:45], v[172:175], v[224:227], v[42:45]
	v_mfma_f32_16x16x32_bf16 v[30:33], v[164:167], v[232:235], v[30:33]
	v_mfma_f32_16x16x32_bf16 v[26:29], v[172:175], v[232:235], v[26:29]
	v_mfma_f32_16x16x32_bf16 v[78:81], v[168:171], v[200:203], v[78:81]
	v_mfma_f32_16x16x32_bf16 v[74:77], v[176:179], v[200:203], v[74:77]
	v_mfma_f32_16x16x32_bf16 v[62:65], v[168:171], v[220:223], v[62:65]
	v_mfma_f32_16x16x32_bf16 v[58:61], v[176:179], v[220:223], v[58:61]
	v_mfma_f32_16x16x32_bf16 v[46:49], v[168:171], v[228:231], v[46:49]
	v_mfma_f32_16x16x32_bf16 v[42:45], v[176:179], v[228:231], v[42:45]
	v_mfma_f32_16x16x32_bf16 v[30:33], v[168:171], v[236:239], v[30:33]
	v_mfma_f32_16x16x32_bf16 v[26:29], v[176:179], v[236:239], v[26:29]
	v_mfma_f32_16x16x32_bf16 v[70:73], v[180:183], v[196:199], v[70:73]
	v_mfma_f32_16x16x32_bf16 v[66:69], v[188:191], v[196:199], v[66:69]
	v_mfma_f32_16x16x32_bf16 v[54:57], v[180:183], v[216:219], v[54:57]
	v_mfma_f32_16x16x32_bf16 v[50:53], v[188:191], v[216:219], v[50:53]
	v_mfma_f32_16x16x32_bf16 v[38:41], v[180:183], v[224:227], v[38:41]
	v_mfma_f32_16x16x32_bf16 v[34:37], v[188:191], v[224:227], v[34:37]
	v_mfma_f32_16x16x32_bf16 v[22:25], v[180:183], v[232:235], v[22:25]
	v_mfma_f32_16x16x32_bf16 v[18:21], v[188:191], v[232:235], v[18:21]
	v_mfma_f32_16x16x32_bf16 v[70:73], v[184:187], v[200:203], v[70:73]
	v_mfma_f32_16x16x32_bf16 v[66:69], v[192:195], v[200:203], v[66:69]
	v_mfma_f32_16x16x32_bf16 v[54:57], v[184:187], v[220:223], v[54:57]
	v_mfma_f32_16x16x32_bf16 v[50:53], v[192:195], v[220:223], v[50:53]
	v_mfma_f32_16x16x32_bf16 v[38:41], v[184:187], v[228:231], v[38:41]
	v_mfma_f32_16x16x32_bf16 v[34:37], v[192:195], v[228:231], v[34:37]
	v_mfma_f32_16x16x32_bf16 v[22:25], v[184:187], v[236:239], v[22:25]
	v_mfma_f32_16x16x32_bf16 v[18:21], v[192:195], v[236:239], v[18:21]
	s_barrier
	s_add_i32 s64, s64, 2
	s_add_u32 s20, s20, 0x100
	s_addc_u32 s21, s21, 0
	s_add_u32 s62, s62, 0x100
	s_addc_u32 s63, s63, 0
.LBB0_121:
	s_add_u32 s22, s20, 0xfffc0080
	s_addc_u32 s23, s21, -1
	s_add_i32 s90, 0, 0x10000
	s_cmp_eq_u32 s64, 12
	s_cselect_b32 s25, s13, s23
	s_cselect_b32 s24, s52, s22
	v_add_u32_e32 v158, s90, v160
	s_cselect_b32 s23, s15, s63
	s_cselect_b32 s22, s53, s62
	s_add_u32 s98, s22, s46
	s_addc_u32 s99, s23, s47
	s_add_u32 s100, s24, s46
	s_addc_u32 s101, s25, s47
	s_add_i32 s81, 0, 0x14000
	ds_read_b128 v[164:167], v158
	ds_read_b128 v[168:171], v158 offset:1024
	ds_read_b128 v[172:175], v158 offset:2048
	ds_read_b128 v[176:179], v158 offset:3072
	v_add_u32_e32 v158, s81, v160
	ds_read_b128 v[180:183], v158
	ds_read_b128 v[184:187], v158 offset:1024
	ds_read_b128 v[188:191], v158 offset:2048
	ds_read_b128 v[192:195], v158 offset:3072
	s_add_i32 m0, s35, 0xc000
	ds_read_b128 v[196:199], v163
	ds_read_b128 v[200:203], v163 offset:1024
	ds_read_b128 v[216:219], v163 offset:2048
	ds_read_b128 v[220:223], v163 offset:3072
	ds_read_b128 v[224:227], v163 offset:4096
	ds_read_b128 v[228:231], v163 offset:5120
	ds_read_b128 v[232:235], v163 offset:6144
	ds_read_b128 v[236:239], v163 offset:7168
	global_load_lds_dwordx4 v154, s[20:21]
	s_add_i32 m0, s35, 0xe000
	s_nop 0
	global_load_lds_dwordx4 v156, s[20:21]
	s_waitcnt vmcnt(8) lgkmcnt(0)
	s_barrier
; #define PG8_STAGE(bufoff, gbase, voff) do { _Pragma("unroll") for (int _i = 0; _i < 2; ++_i) \
;         __builtin_amdgcn_global_load_lds((const unsigned*)((const char*)(gbase) + (voff)[_i]), (PG8_LAS unsigned*)(lds + (bufoff) + ldsw + _i * 8192), 16, 0, 0); } while (0)
; #define PG8_LDA(dst, b, h) do { _Pragma("unroll") for (int m = 0; m < 4; ++m) _Pragma("unroll") for (int k = 0; k < 2; ++k) dst[m][k] = *(const PG8_LAS bf16x8*)(lds + PG8_SA(b, h) + aoff + m * 2048 + k * 1024); } while (0)
; #define PG8_MMA(ai, bj, At, Bt) do { __builtin_amdgcn_s_setprio(1); _Pragma("unroll") for (int m = 0; m < 4; ++m) _Pragma("unroll") for (int n = 0; n < 2; ++n) _Pragma("unroll") for (int k = 0; k < 2; ++k) \
;         acc[ai][bj][m][n] = __builtin_amdgcn_mfma_f32_16x16x32_bf16(Bt[n][k], At[m][k], acc[ai][bj][m][n], 0, 0, 0); __builtin_amdgcn_s_setprio(0); } while (0)
; #define PG8_WAIT_V(n) asm volatile("s_waitcnt vmcnt(" #n ")" ::: "memory")
; #define PG8_WAIT_L(n) asm volatile("s_waitcnt lgkmcnt(" #n ")" ::: "memory")
; #define PG8_BAR __builtin_amdgcn_s_barrier()
; #define PG8_SCHED __builtin_amdgcn_sched_barrier(0)
; template <class Epi, class Sched, bool ALIGN_EPI = false, bool SP2 = false>
; __device__ __forceinline__ void gemm_phase(PG8_LAS unsigned char* lds, const Gemm g, const Sched& S, const Epi& E) {
;     ...
;             PG8_WAIT_V(8); PG8_WAIT_L(0); PG8_BAR; PG8_MMA(0, 0, At, B0); PG8_MMA(0, 1, At, B1); PG8_BAR; PG8_SCHED;
;             PG8_LDA(At, 0, 1); PG8_STAGE(PG8_SB(0, 0), b2, voffB); PG8_STAGE(PG8_SB(0, 1), b2 + hstep, voffB); PG8_STAGE(PG8_SA(0, 0), a2, voffA);
;             PG8_WAIT_V(8); PG8_WAIT_L(0); PG8_BAR; PG8_MMA(1, 0, At, B0); PG8_MMA(1, 1, At, B1); PG8_BAR; PG8_SCHED;
	v_mfma_f32_16x16x32_bf16 v[142:145], v[164:167], v[196:199], v[142:145]
	v_mfma_f32_16x16x32_bf16 v[138:141], v[172:175], v[196:199], v[138:141]
	v_mfma_f32_16x16x32_bf16 v[126:129], v[164:167], v[216:219], v[126:129]
	v_mfma_f32_16x16x32_bf16 v[122:125], v[172:175], v[216:219], v[122:125]
	v_mfma_f32_16x16x32_bf16 v[110:113], v[164:167], v[224:227], v[110:113]
	v_mfma_f32_16x16x32_bf16 v[106:109], v[172:175], v[224:227], v[106:109]
	v_mfma_f32_16x16x32_bf16 v[94:97], v[164:167], v[232:235], v[94:97]
	v_mfma_f32_16x16x32_bf16 v[90:93], v[172:175], v[232:235], v[90:93]
	v_mfma_f32_16x16x32_bf16 v[142:145], v[168:171], v[200:203], v[142:145]
	v_mfma_f32_16x16x32_bf16 v[138:141], v[176:179], v[200:203], v[138:141]
	v_mfma_f32_16x16x32_bf16 v[126:129], v[168:171], v[220:223], v[126:129]
	v_mfma_f32_16x16x32_bf16 v[122:125], v[176:179], v[220:223], v[122:125]
	v_mfma_f32_16x16x32_bf16 v[110:113], v[168:171], v[228:231], v[110:113]
	v_mfma_f32_16x16x32_bf16 v[106:109], v[176:179], v[228:231], v[106:109]
	v_mfma_f32_16x16x32_bf16 v[94:97], v[168:171], v[236:239], v[94:97]
	v_mfma_f32_16x16x32_bf16 v[90:93], v[176:179], v[236:239], v[90:93]
	v_mfma_f32_16x16x32_bf16 v[134:137], v[180:183], v[196:199], v[134:137]
	v_mfma_f32_16x16x32_bf16 v[130:133], v[188:191], v[196:199], v[130:133]
	v_mfma_f32_16x16x32_bf16 v[118:121], v[180:183], v[216:219], v[118:121]
	v_mfma_f32_16x16x32_bf16 v[114:117], v[188:191], v[216:219], v[114:117]
	v_mfma_f32_16x16x32_bf16 v[102:105], v[180:183], v[224:227], v[102:105]
	v_mfma_f32_16x16x32_bf16 v[98:101], v[188:191], v[224:227], v[98:101]
	v_mfma_f32_16x16x32_bf16 v[86:89], v[180:183], v[232:235], v[86:89]
	v_mfma_f32_16x16x32_bf16 v[82:85], v[188:191], v[232:235], v[82:85]
	v_mfma_f32_16x16x32_bf16 v[134:137], v[184:187], v[200:203], v[134:137]
	v_mfma_f32_16x16x32_bf16 v[130:133], v[192:195], v[200:203], v[130:133]
	v_mfma_f32_16x16x32_bf16 v[118:121], v[184:187], v[220:223], v[118:121]
	v_mfma_f32_16x16x32_bf16 v[114:117], v[192:195], v[220:223], v[114:117]
	v_mfma_f32_16x16x32_bf16 v[102:105], v[184:187], v[228:231], v[102:105]
	v_mfma_f32_16x16x32_bf16 v[98:101], v[192:195], v[228:231], v[98:101]
	v_mfma_f32_16x16x32_bf16 v[86:89], v[184:187], v[236:239], v[86:89]
	v_mfma_f32_16x16x32_bf16 v[82:85], v[192:195], v[236:239], v[82:85]
	s_barrier
	s_add_i32 s65, s90, s34
	s_mov_b32 m0, s65
	ds_read_b128 v[196:199], v163 offset:16384
	ds_read_b128 v[200:203], v163 offset:17408
	ds_read_b128 v[216:219], v163 offset:18432
	ds_read_b128 v[220:223], v163 offset:19456
	ds_read_b128 v[224:227], v163 offset:20480
	ds_read_b128 v[228:231], v163 offset:21504
	ds_read_b128 v[232:235], v163 offset:22528
	ds_read_b128 v[236:239], v163 offset:23552
	global_load_lds_dwordx4 v148, s[22:23]
	s_add_i32 m0, s65, 0x2000
	s_add_u32 s66, s22, 0x40000
	s_addc_u32 s67, s23, 0
	s_add_i32 s65, s81, s34
	global_load_lds_dwordx4 v152, s[22:23]
	s_mov_b32 m0, s65
	s_nop 0
	global_load_lds_dwordx4 v148, s[66:67]
	s_add_i32 m0, s65, 0x2000
	s_nop 0
	global_load_lds_dwordx4 v152, s[66:67]
	s_mov_b32 m0, s35
	s_nop 0
	global_load_lds_dwordx4 v146, s[24:25]
	s_mov_b32 m0, s36
	s_nop 0
	global_load_lds_dwordx4 v150, s[24:25]
	s_waitcnt vmcnt(8) lgkmcnt(0)
	s_barrier
	v_mfma_f32_16x16x32_bf16 v[78:81], v[164:167], v[196:199], v[78:81]
	v_mfma_f32_16x16x32_bf16 v[74:77], v[172:175], v[196:199], v[74:77]
	v_mfma_f32_16x16x32_bf16 v[62:65], v[164:167], v[216:219], v[62:65]
	v_mfma_f32_16x16x32_bf16 v[58:61], v[172:175], v[216:219], v[58:61]
	v_mfma_f32_16x16x32_bf16 v[46:49], v[164:167], v[224:227], v[46:49]
	v_mfma_f32_16x16x32_bf16 v[42:45], v[172:175], v[224:227], v[42:45]
	v_mfma_f32_16x16x32_bf16 v[30:33], v[164:167], v[232:235], v[30:33]
	v_mfma_f32_16x16x32_bf16 v[26:29], v[172:175], v[232:235], v[26:29]
	v_mfma_f32_16x16x32_bf16 v[78:81], v[168:171], v[200:203], v[78:81]
	v_mfma_f32_16x16x32_bf16 v[74:77], v[176:179], v[200:203], v[74:77]
	v_mfma_f32_16x16x32_bf16 v[62:65], v[168:171], v[220:223], v[62:65]
	v_mfma_f32_16x16x32_bf16 v[58:61], v[176:179], v[220:223], v[58:61]
	v_mfma_f32_16x16x32_bf16 v[46:49], v[168:171], v[228:231], v[46:49]
	v_mfma_f32_16x16x32_bf16 v[42:45], v[176:179], v[228:231], v[42:45]
	v_mfma_f32_16x16x32_bf16 v[30:33], v[168:171], v[236:239], v[30:33]
	v_mfma_f32_16x16x32_bf16 v[26:29], v[176:179], v[236:239], v[26:29]
	v_mfma_f32_16x16x32_bf16 v[70:73], v[180:183], v[196:199], v[70:73]
	v_mfma_f32_16x16x32_bf16 v[66:69], v[188:191], v[196:199], v[66:69]
	v_mfma_f32_16x16x32_bf16 v[54:57], v[180:183], v[216:219], v[54:57]
	v_mfma_f32_16x16x32_bf16 v[50:53], v[188:191], v[216:219], v[50:53]
	v_mfma_f32_16x16x32_bf16 v[38:41], v[180:183], v[224:227], v[38:41]
	v_mfma_f32_16x16x32_bf16 v[34:37], v[188:191], v[224:227], v[34:37]
	v_mfma_f32_16x16x32_bf16 v[22:25], v[180:183], v[232:235], v[22:25]
	v_mfma_f32_16x16x32_bf16 v[18:21], v[188:191], v[232:235], v[18:21]
	v_mfma_f32_16x16x32_bf16 v[70:73], v[184:187], v[200:203], v[70:73]
	v_mfma_f32_16x16x32_bf16 v[66:69], v[192:195], v[200:203], v[66:69]
	v_mfma_f32_16x16x32_bf16 v[54:57], v[184:187], v[220:223], v[54:57]
	v_mfma_f32_16x16x32_bf16 v[50:53], v[192:195], v[220:223], v[50:53]
	v_mfma_f32_16x16x32_bf16 v[38:41], v[184:187], v[228:231], v[38:41]
	v_mfma_f32_16x16x32_bf16 v[34:37], v[192:195], v[228:231], v[34:37]
	v_mfma_f32_16x16x32_bf16 v[22:25], v[184:187], v[236:239], v[22:25]
	v_mfma_f32_16x16x32_bf16 v[18:21], v[192:195], v[236:239], v[18:21]
	s_barrier
; #define PG8_STAGE(bufoff, gbase, voff) do { _Pragma("unroll") for (int _i = 0; _i < 2; ++_i) \
;         __builtin_amdgcn_global_load_lds((const unsigned*)((const char*)(gbase) + (voff)[_i]), (PG8_LAS unsigned*)(lds + (bufoff) + ldsw + _i * 8192), 16, 0, 0); } while (0)
; #define PG8_LDA(dst, b, h) do { _Pragma("unroll") for (int m = 0; m < 4; ++m) _Pragma("unroll") for (int k = 0; k < 2; ++k) dst[m][k] = *(const PG8_LAS bf16x8*)(lds + PG8_SA(b, h) + aoff + m * 2048 + k * 1024); } while (0)
; #define PG8_LDB(dst, b, h) do { _Pragma("unroll") for (int n = 0; n < 2; ++n) _Pragma("unroll") for (int k = 0; k < 2; ++k) dst[n][k] = *(const PG8_LAS bf16x8*)(lds + PG8_SB(b, h) + boff + n * 2048 + k * 1024); } while (0)
; #define PG8_MMA(ai, bj, At, Bt) do { __builtin_amdgcn_s_setprio(1); _Pragma("unroll") for (int m = 0; m < 4; ++m) _Pragma("unroll") for (int n = 0; n < 2; ++n) _Pragma("unroll") for (int k = 0; k < 2; ++k) \
;         acc[ai][bj][m][n] = __builtin_amdgcn_mfma_f32_16x16x32_bf16(Bt[n][k], At[m][k], acc[ai][bj][m][n], 0, 0, 0); __builtin_amdgcn_s_setprio(0); } while (0)
; #define PG8_WAIT_V(n) asm volatile("s_waitcnt vmcnt(" #n ")" ::: "memory")
; #define PG8_WAIT_L(n) asm volatile("s_waitcnt lgkmcnt(" #n ")" ::: "memory")
; #define PG8_BAR __builtin_amdgcn_s_barrier()
; #define PG8_SCHED __builtin_amdgcn_sched_barrier(0)
; template <class Epi, class Sched, bool ALIGN_EPI = false, bool SP2 = false>
; __device__ __forceinline__ void gemm_phase(PG8_LAS unsigned char* lds, const Gemm g, const Sched& S, const Epi& E) {
;     ...
;             PG8_LDB(B0, 1, 0); PG8_LDB(B1, 1, 1); PG8_SCHED; PG8_LDA(At, 1, 0); PG8_STAGE(PG8_SA(0, 1), a2 + hstep, voffA);
;             PG8_WAIT_V(8); PG8_WAIT_L(0); PG8_BAR; PG8_MMA(0, 0, At, B0); PG8_MMA(0, 1, At, B1); PG8_BAR; PG8_SCHED;
;             PG8_LDA(At, 1, 1); PG8_STAGE(PG8_SB(1, 0), b3, voffB); PG8_STAGE(PG8_SB(1, 1), b3 + hstep, voffB); PG8_STAGE(PG8_SA(1, 0), a3, voffA);
;             PG8_WAIT_V(8); PG8_WAIT_L(0); PG8_BAR; PG8_MMA(1, 0, At, B0); PG8_MMA(1, 1, At, B1); PG8_BAR; PG8_SCHED;
	s_add_i32 s82, 0, 0x18000
	s_add_i32 s83, 0, 0x1c000
	v_add_u32_e32 v176, s82, v160
	v_add_u32_e32 v192, s83, v160
	ds_read_b128 v[164:167], v176
	ds_read_b128 v[168:171], v176 offset:1024
	ds_read_b128 v[172:175], v176 offset:2048
	ds_read_b128 v[176:179], v176 offset:3072
	ds_read_b128 v[180:183], v192
	ds_read_b128 v[184:187], v192 offset:1024
	ds_read_b128 v[188:191], v192 offset:2048
	ds_read_b128 v[192:195], v192 offset:3072
	s_add_u32 s24, s24, 0x40000
	s_addc_u32 s25, s25, 0
	s_mov_b32 m0, s37
	ds_read_b128 v[196:199], v163 offset:32768
	ds_read_b128 v[200:203], v163 offset:33792
	ds_read_b128 v[216:219], v163 offset:34816
	ds_read_b128 v[220:223], v163 offset:35840
	ds_read_b128 v[224:227], v163 offset:36864
	ds_read_b128 v[228:231], v163 offset:37888
	ds_read_b128 v[232:235], v163 offset:38912
	ds_read_b128 v[236:239], v163 offset:39936
	global_load_lds_dwordx4 v146, s[24:25]
	s_mov_b32 m0, s38
	s_nop 0
	global_load_lds_dwordx4 v150, s[24:25]
	s_waitcnt vmcnt(8) lgkmcnt(0)
	s_barrier
	v_mfma_f32_16x16x32_bf16 v[142:145], v[164:167], v[196:199], v[142:145]
	v_mfma_f32_16x16x32_bf16 v[138:141], v[172:175], v[196:199], v[138:141]
	v_mfma_f32_16x16x32_bf16 v[126:129], v[164:167], v[216:219], v[126:129]
	v_mfma_f32_16x16x32_bf16 v[122:125], v[172:175], v[216:219], v[122:125]
	v_mfma_f32_16x16x32_bf16 v[110:113], v[164:167], v[224:227], v[110:113]
	v_mfma_f32_16x16x32_bf16 v[106:109], v[172:175], v[224:227], v[106:109]
	v_mfma_f32_16x16x32_bf16 v[94:97], v[164:167], v[232:235], v[94:97]
	v_mfma_f32_16x16x32_bf16 v[90:93], v[172:175], v[232:235], v[90:93]
	v_mfma_f32_16x16x32_bf16 v[142:145], v[168:171], v[200:203], v[142:145]
	v_mfma_f32_16x16x32_bf16 v[138:141], v[176:179], v[200:203], v[138:141]
	v_mfma_f32_16x16x32_bf16 v[126:129], v[168:171], v[220:223], v[126:129]
	v_mfma_f32_16x16x32_bf16 v[122:125], v[176:179], v[220:223], v[122:125]
	v_mfma_f32_16x16x32_bf16 v[110:113], v[168:171], v[228:231], v[110:113]
	v_mfma_f32_16x16x32_bf16 v[106:109], v[176:179], v[228:231], v[106:109]
	v_mfma_f32_16x16x32_bf16 v[94:97], v[168:171], v[236:239], v[94:97]
	v_mfma_f32_16x16x32_bf16 v[90:93], v[176:179], v[236:239], v[90:93]
	v_mfma_f32_16x16x32_bf16 v[134:137], v[180:183], v[196:199], v[134:137]
	v_mfma_f32_16x16x32_bf16 v[130:133], v[188:191], v[196:199], v[130:133]
	v_mfma_f32_16x16x32_bf16 v[118:121], v[180:183], v[216:219], v[118:121]
	v_mfma_f32_16x16x32_bf16 v[114:117], v[188:191], v[216:219], v[114:117]
	v_mfma_f32_16x16x32_bf16 v[102:105], v[180:183], v[224:227], v[102:105]
	v_mfma_f32_16x16x32_bf16 v[98:101], v[188:191], v[224:227], v[98:101]
	v_mfma_f32_16x16x32_bf16 v[86:89], v[180:183], v[232:235], v[86:89]
	v_mfma_f32_16x16x32_bf16 v[82:85], v[188:191], v[232:235], v[82:85]
	v_mfma_f32_16x16x32_bf16 v[134:137], v[184:187], v[200:203], v[134:137]
	v_mfma_f32_16x16x32_bf16 v[130:133], v[192:195], v[200:203], v[130:133]
	v_mfma_f32_16x16x32_bf16 v[118:121], v[184:187], v[220:223], v[118:121]
	v_mfma_f32_16x16x32_bf16 v[114:117], v[192:195], v[220:223], v[114:117]
	v_mfma_f32_16x16x32_bf16 v[102:105], v[184:187], v[228:231], v[102:105]
	v_mfma_f32_16x16x32_bf16 v[98:101], v[192:195], v[228:231], v[98:101]
	v_mfma_f32_16x16x32_bf16 v[86:89], v[184:187], v[236:239], v[86:89]
	v_mfma_f32_16x16x32_bf16 v[82:85], v[192:195], v[236:239], v[82:85]
	s_barrier
	s_add_i32 s24, s82, s34
	s_mov_b32 m0, s24
	ds_read_b128 v[196:199], v163 offset:49152
	ds_read_b128 v[200:203], v163 offset:50176
	ds_read_b128 v[216:219], v163 offset:51200
	ds_read_b128 v[220:223], v163 offset:52224
	ds_read_b128 v[224:227], v163 offset:53248
	ds_read_b128 v[228:231], v163 offset:54272
	ds_read_b128 v[232:235], v163 offset:55296
	ds_read_b128 v[236:239], v163 offset:56320
	global_load_lds_dwordx4 v148, s[98:99]
	s_add_i32 m0, s24, 0x2000
	s_add_u32 s22, s22, 0x40080
	s_addc_u32 s23, s23, 0
	s_add_i32 s24, s83, s34
	global_load_lds_dwordx4 v152, s[98:99]
	s_mov_b32 m0, s24
	s_nop 0
	global_load_lds_dwordx4 v148, s[22:23]
	s_add_i32 m0, s24, 0x2000
	s_nop 0
	global_load_lds_dwordx4 v152, s[22:23]
	s_mov_b32 m0, s39
	s_nop 0
	global_load_lds_dwordx4 v146, s[100:101]
	s_mov_b32 m0, s42
	s_nop 0
	global_load_lds_dwordx4 v150, s[100:101]
	s_waitcnt vmcnt(8) lgkmcnt(0)
	s_barrier
	v_mfma_f32_16x16x32_bf16 v[78:81], v[164:167], v[196:199], v[78:81]
	v_mfma_f32_16x16x32_bf16 v[74:77], v[172:175], v[196:199], v[74:77]
	v_mfma_f32_16x16x32_bf16 v[62:65], v[164:167], v[216:219], v[62:65]
	v_mfma_f32_16x16x32_bf16 v[58:61], v[172:175], v[216:219], v[58:61]
	v_mfma_f32_16x16x32_bf16 v[46:49], v[164:167], v[224:227], v[46:49]
	v_mfma_f32_16x16x32_bf16 v[42:45], v[172:175], v[224:227], v[42:45]
	v_mfma_f32_16x16x32_bf16 v[30:33], v[164:167], v[232:235], v[30:33]
	v_mfma_f32_16x16x32_bf16 v[26:29], v[172:175], v[232:235], v[26:29]
	v_mfma_f32_16x16x32_bf16 v[78:81], v[168:171], v[200:203], v[78:81]
	v_mfma_f32_16x16x32_bf16 v[74:77], v[176:179], v[200:203], v[74:77]
	v_mfma_f32_16x16x32_bf16 v[62:65], v[168:171], v[220:223], v[62:65]
	v_mfma_f32_16x16x32_bf16 v[58:61], v[176:179], v[220:223], v[58:61]
	v_mfma_f32_16x16x32_bf16 v[46:49], v[168:171], v[228:231], v[46:49]
	v_mfma_f32_16x16x32_bf16 v[42:45], v[176:179], v[228:231], v[42:45]
	v_mfma_f32_16x16x32_bf16 v[30:33], v[168:171], v[236:239], v[30:33]
	v_mfma_f32_16x16x32_bf16 v[26:29], v[176:179], v[236:239], v[26:29]
	v_mfma_f32_16x16x32_bf16 v[70:73], v[180:183], v[196:199], v[70:73]
	v_mfma_f32_16x16x32_bf16 v[66:69], v[188:191], v[196:199], v[66:69]
	v_mfma_f32_16x16x32_bf16 v[54:57], v[180:183], v[216:219], v[54:57]
	v_mfma_f32_16x16x32_bf16 v[50:53], v[188:191], v[216:219], v[50:53]
	v_mfma_f32_16x16x32_bf16 v[38:41], v[180:183], v[224:227], v[38:41]
	v_mfma_f32_16x16x32_bf16 v[34:37], v[188:191], v[224:227], v[34:37]
	v_mfma_f32_16x16x32_bf16 v[22:25], v[180:183], v[232:235], v[22:25]
	v_mfma_f32_16x16x32_bf16 v[18:21], v[188:191], v[232:235], v[18:21]
	v_mfma_f32_16x16x32_bf16 v[70:73], v[184:187], v[200:203], v[70:73]
	v_mfma_f32_16x16x32_bf16 v[66:69], v[192:195], v[200:203], v[66:69]
	v_mfma_f32_16x16x32_bf16 v[54:57], v[184:187], v[220:223], v[54:57]
	v_mfma_f32_16x16x32_bf16 v[50:53], v[192:195], v[220:223], v[50:53]
	v_mfma_f32_16x16x32_bf16 v[38:41], v[184:187], v[228:231], v[38:41]
	v_mfma_f32_16x16x32_bf16 v[34:37], v[192:195], v[228:231], v[34:37]
	v_mfma_f32_16x16x32_bf16 v[22:25], v[184:187], v[236:239], v[22:25]
	v_mfma_f32_16x16x32_bf16 v[18:21], v[192:195], v[236:239], v[18:21]
	s_barrier
	s_add_i32 s64, s64, 2
	s_add_u32 s20, s20, 0x100
	s_addc_u32 s21, s21, 0
	s_add_u32 s62, s62, 0x100
	s_addc_u32 s63, s63, 0
	s_cmp_gt_u32 s64, 13
	s_cbranch_scc0 .LBB0_121
	s_setprio 0
	s_and_b64 vcc, exec, s[10:11]
	s_cbranch_vccz .LBB0_124
	s_barrier

; #define PG8_STAGE(bufoff, gbase, voff) do { _Pragma("unroll") for (int _i = 0; _i < 2; ++_i) \
;         __builtin_amdgcn_global_load_lds((const unsigned*)((const char*)(gbase) + (voff)[_i]), (PG8_LAS unsigned*)(lds + (bufoff) + ldsw + _i * 8192), 16, 0, 0); } while (0)
; #define PG8_LDA(dst, b, h) do { _Pragma("unroll") for (int m = 0; m < 4; ++m) _Pragma("unroll") for (int k = 0; k < 2; ++k) dst[m][k] = *(const PG8_LAS bf16x8*)(lds + PG8_SA(b, h) + aoff + m * 2048 + k * 1024); } while (0)
; #define PG8_LDB(dst, b, h) do { _Pragma("unroll") for (int n = 0; n < 2; ++n) _Pragma("unroll") for (int k = 0; k < 2; ++k) dst[n][k] = *(const PG8_LAS bf16x8*)(lds + PG8_SB(b, h) + boff + n * 2048 + k * 1024); } while (0)
; #define PG8_WAIT_V(n) asm volatile("s_waitcnt vmcnt(" #n ")" ::: "memory")
; template <class Epi, class Sched, bool ALIGN_EPI = false, bool SP2 = false>
; __device__ __forceinline__ void gemm_phase(PG8_LAS unsigned char* lds, const Gemm g, const Sched& S, const Epi& E) {
;     ...
;         const bool has_next = S.next(ui + 1, nxt);
;         const char* nA = has_next ? (const char*)g.A + (size_t)nxt.pm * tstep : cA; const char* nB = has_next ? (const char*)g.Bt + (size_t)nxt.pn * tstep : cB;
;         constexpr int NSEG = (Epi::MID_T >= 0) ? 2 : 1;
; #pragma unroll 1
;         for (int seg = 0; seg < NSEG; ++seg) {
;         const int t_lo = (seg == 0) ? 0 : Epi::MID_T, t_hi = (NSEG == 2 && seg == 0) ? Epi::MID_T : nt;
;         if constexpr (Epi::MID_T >= 0) { if (seg == 1) E.mid(acc, ui, wr, fr); }
;         for (int t = t_lo; t < t_hi; t += 2) {
;             const bool last = (t == nt - 2);
;             const char* a1 = cA + (size_t)(t + 1) * kstep;
;             const char* a2 = last ? nA : cA + (size_t)(t + 2) * kstep; const char* b2 = last ? nB : cB + (size_t)(t + 2) * kstep;
;             const char* a3 = a2 + kstep; const char* b3 = b2 + kstep;
;             if (last && has_next) S.a_ready_inloop(nxt, ui + 1);
;             if constexpr (SP2) {
;             PG8_LDB(B0, 0, 0); PG8_LDB(B1, 0, 1); PG8_SCHED; PG8_LDA(At, 0, 0); PG8_STAGE(PG8_SA(1, 1), a1 + hstep, voffA);
;             PG8_WAIT_V(8); PG8_WAIT_L(0); PG8_BAR; PG8_MMA(0, 0, At, B0); PG8_MMA(0, 1, At, B1); PG8_BAR; PG8_SCHED;
;             PG8_LDA(At, 0, 1); PG8_STAGE(PG8_SB(0, 0), b2, voffB); PG8_STAGE(PG8_SB(0, 1), b2 + hstep, voffB); PG8_STAGE(PG8_SA(0, 0), a2, voffA);
.LBB0_211:
	s_mov_b64 s[18:19], s[6:7]
	s_mov_b64 s[20:21], s[14:15]
	s_and_b64 s[6:7], s[16:17], exec
	s_cselect_b32 s7, s37, s19
	s_cselect_b32 s6, s36, s18
	s_cselect_b32 s15, s3, s21
	s_cselect_b32 s14, s2, s20
	s_add_u32 s39, s20, 0x100
	s_addc_u32 s42, s21, 0
	s_mov_b32 s44, -2
	v_readfirstlane_b32 s98, v204
	s_nop 3
	s_cmp_ge_u32 s98, 0x100
	s_cbranch_scc0 .Lprio_skip_1
	s_setprio 1
.Lprio_skip_1:
	v_add_u32_e32 v142, s90, v188
	v_add_u32_e32 v172, s81, v188
	ds_read_b128 v[130:133], v142
	ds_read_b128 v[134:137], v142 offset:1024
	ds_read_b128 v[138:141], v142 offset:2048
	ds_read_b128 v[142:145], v142 offset:3072
	ds_read_b128 v[146:149], v172
	ds_read_b128 v[150:153], v172 offset:1024
	ds_read_b128 v[154:157], v172 offset:2048
	ds_read_b128 v[172:175], v172 offset:3072
	s_add_u32 s20, s18, 0x100
	s_addc_u32 s21, s19, 0
	s_cmp_eq_u32 s44, 40
	s_cselect_b32 s25, s7, s21
	s_cselect_b32 s24, s6, s20
	s_cselect_b32 s23, s15, s42
	s_cselect_b32 s22, s14, s39
	s_add_u32 s98, s22, s46
	s_addc_u32 s99, s23, s47
	s_add_u32 s100, s24, s46
	s_addc_u32 s101, s25, s47
	s_add_i32 m0, s27, 0xc000
	ds_read_b128 v[176:179], v189
	ds_read_b128 v[180:183], v189 offset:1024
	ds_read_b128 v[184:187], v189 offset:2048
	ds_read_b128 v[190:193], v189 offset:3072
	ds_read_b128 v[194:197], v189 offset:4096
	ds_read_b128 v[198:201], v189 offset:5120
	ds_read_b128 v[216:219], v189 offset:6144
	ds_read_b128 v[220:223], v189 offset:7168
	global_load_lds_dwordx4 v168, s[18:19]
	s_add_i32 m0, s27, 0xe000
	s_nop 0
	global_load_lds_dwordx4 v170, s[18:19]
	s_waitcnt vmcnt(8) lgkmcnt(0)
	s_barrier
	v_mfma_f32_16x16x32_bf16 v[126:129], v[130:133], v[176:179], 0
	v_mfma_f32_16x16x32_bf16 v[122:125], v[138:141], v[176:179], 0
	v_mfma_f32_16x16x32_bf16 v[110:113], v[130:133], v[184:187], 0
	v_mfma_f32_16x16x32_bf16 v[106:109], v[138:141], v[184:187], 0
	v_mfma_f32_16x16x32_bf16 v[94:97], v[130:133], v[194:197], 0
	v_mfma_f32_16x16x32_bf16 v[90:93], v[138:141], v[194:197], 0
	v_mfma_f32_16x16x32_bf16 v[78:81], v[130:133], v[216:219], 0
	v_mfma_f32_16x16x32_bf16 v[74:77], v[138:141], v[216:219], 0
	v_mfma_f32_16x16x32_bf16 v[126:129], v[134:137], v[180:183], v[126:129]
	v_mfma_f32_16x16x32_bf16 v[122:125], v[142:145], v[180:183], v[122:125]
	v_mfma_f32_16x16x32_bf16 v[110:113], v[134:137], v[190:193], v[110:113]
	v_mfma_f32_16x16x32_bf16 v[106:109], v[142:145], v[190:193], v[106:109]
	v_mfma_f32_16x16x32_bf16 v[94:97], v[134:137], v[198:201], v[94:97]
	v_mfma_f32_16x16x32_bf16 v[90:93], v[142:145], v[198:201], v[90:93]
	v_mfma_f32_16x16x32_bf16 v[78:81], v[134:137], v[220:223], v[78:81]
	v_mfma_f32_16x16x32_bf16 v[74:77], v[142:145], v[220:223], v[74:77]
	v_mfma_f32_16x16x32_bf16 v[118:121], v[146:149], v[176:179], 0
	v_mfma_f32_16x16x32_bf16 v[114:117], v[154:157], v[176:179], 0
	v_mfma_f32_16x16x32_bf16 v[102:105], v[146:149], v[184:187], 0
	v_mfma_f32_16x16x32_bf16 v[98:101], v[154:157], v[184:187], 0
	v_mfma_f32_16x16x32_bf16 v[86:89], v[146:149], v[194:197], 0
	v_mfma_f32_16x16x32_bf16 v[82:85], v[154:157], v[194:197], 0
	v_mfma_f32_16x16x32_bf16 v[70:73], v[146:149], v[216:219], 0
	v_mfma_f32_16x16x32_bf16 v[66:69], v[154:157], v[216:219], 0
	v_mfma_f32_16x16x32_bf16 v[118:121], v[150:153], v[180:183], v[118:121]
	v_mfma_f32_16x16x32_bf16 v[114:117], v[172:175], v[180:183], v[114:117]
	v_mfma_f32_16x16x32_bf16 v[102:105], v[150:153], v[190:193], v[102:105]
	v_mfma_f32_16x16x32_bf16 v[98:101], v[172:175], v[190:193], v[98:101]
	v_mfma_f32_16x16x32_bf16 v[86:89], v[150:153], v[198:201], v[86:89]
	v_mfma_f32_16x16x32_bf16 v[82:85], v[172:175], v[198:201], v[82:85]
	v_mfma_f32_16x16x32_bf16 v[70:73], v[150:153], v[220:223], v[70:73]
	v_mfma_f32_16x16x32_bf16 v[66:69], v[172:175], v[220:223], v[66:69]
	s_barrier
	s_add_i32 s18, s90, s26
	s_mov_b32 m0, s18
	ds_read_b128 v[176:179], v189 offset:16384
	ds_read_b128 v[180:183], v189 offset:17408
	ds_read_b128 v[184:187], v189 offset:18432
	ds_read_b128 v[190:193], v189 offset:19456
	ds_read_b128 v[194:197], v189 offset:20480
	ds_read_b128 v[198:201], v189 offset:21504
	ds_read_b128 v[216:219], v189 offset:22528
	ds_read_b128 v[220:223], v189 offset:23552
	global_load_lds_dwordx4 v160, s[22:23]
	s_add_i32 m0, s18, 0x2000
	s_add_u32 s18, s22, 0xb0000
	s_addc_u32 s19, s23, 0
	s_add_i32 s45, s81, s26
	global_load_lds_dwordx4 v164, s[22:23]
	s_mov_b32 m0, s45
	s_nop 0
	global_load_lds_dwordx4 v160, s[18:19]
	s_add_i32 m0, s45, 0x2000
	s_nop 0
	global_load_lds_dwordx4 v164, s[18:19]
	s_mov_b32 m0, s27
	s_nop 0
	global_load_lds_dwordx4 v158, s[24:25]
	s_mov_b32 m0, s28
	s_nop 0
	global_load_lds_dwordx4 v162, s[24:25]
	s_waitcnt vmcnt(8) lgkmcnt(0)
	s_barrier
; #define PG8_STAGE(bufoff, gbase, voff) do { _Pragma("unroll") for (int _i = 0; _i < 2; ++_i) \
;         __builtin_amdgcn_global_load_lds((const unsigned*)((const char*)(gbase) + (voff)[_i]), (PG8_LAS unsigned*)(lds + (bufoff) + ldsw + _i * 8192), 16, 0, 0); } while (0)
; #define PG8_LDA(dst, b, h) do { _Pragma("unroll") for (int m = 0; m < 4; ++m) _Pragma("unroll") for (int k = 0; k < 2; ++k) dst[m][k] = *(const PG8_LAS bf16x8*)(lds + PG8_SA(b, h) + aoff + m * 2048 + k * 1024); } while (0)
; #define PG8_LDB(dst, b, h) do { _Pragma("unroll") for (int n = 0; n < 2; ++n) _Pragma("unroll") for (int k = 0; k < 2; ++k) dst[n][k] = *(const PG8_LAS bf16x8*)(lds + PG8_SB(b, h) + boff + n * 2048 + k * 1024); } while (0)
; #define PG8_MMA(ai, bj, At, Bt) do { __builtin_amdgcn_s_setprio(1); _Pragma("unroll") for (int m = 0; m < 4; ++m) _Pragma("unroll") for (int n = 0; n < 2; ++n) _Pragma("unroll") for (int k = 0; k < 2; ++k) \
;         acc[ai][bj][m][n] = __builtin_amdgcn_mfma_f32_16x16x32_bf16(Bt[n][k], At[m][k], acc[ai][bj][m][n], 0, 0, 0); __builtin_amdgcn_s_setprio(0); } while (0)
; #define PG8_WAIT_V(n) asm volatile("s_waitcnt vmcnt(" #n ")" ::: "memory")
; #define PG8_WAIT_L(n) asm volatile("s_waitcnt lgkmcnt(" #n ")" ::: "memory")
; #define PG8_BAR __builtin_amdgcn_s_barrier()
; #define PG8_SCHED __builtin_amdgcn_sched_barrier(0)
; template <class Epi, class Sched, bool ALIGN_EPI = false, bool SP2 = false>
; __device__ __forceinline__ void gemm_phase(PG8_LAS unsigned char* lds, const Gemm g, const Sched& S, const Epi& E) {
;     ...
;             PG8_WAIT_V(8); PG8_WAIT_L(0); PG8_BAR; PG8_MMA(1, 0, At, B0); PG8_MMA(1, 1, At, B1); PG8_BAR; PG8_SCHED;
;             PG8_LDB(B0, 1, 0); PG8_LDB(B1, 1, 1); PG8_SCHED; PG8_LDA(At, 1, 0); PG8_STAGE(PG8_SA(0, 1), a2 + hstep, voffA);
;             PG8_WAIT_V(8); PG8_WAIT_L(0); PG8_BAR; PG8_MMA(0, 0, At, B0); PG8_MMA(0, 1, At, B1); PG8_BAR; PG8_SCHED;
	v_mfma_f32_16x16x32_bf16 v[62:65], v[130:133], v[176:179], 0
	v_mfma_f32_16x16x32_bf16 v[58:61], v[138:141], v[176:179], 0
	v_mfma_f32_16x16x32_bf16 v[46:49], v[130:133], v[184:187], 0
	v_mfma_f32_16x16x32_bf16 v[42:45], v[138:141], v[184:187], 0
	v_mfma_f32_16x16x32_bf16 v[30:33], v[130:133], v[194:197], 0
	v_mfma_f32_16x16x32_bf16 v[26:29], v[138:141], v[194:197], 0
	v_mfma_f32_16x16x32_bf16 v[14:17], v[130:133], v[216:219], 0
	v_mfma_f32_16x16x32_bf16 v[10:13], v[138:141], v[216:219], 0
	v_mfma_f32_16x16x32_bf16 v[62:65], v[134:137], v[180:183], v[62:65]
	v_mfma_f32_16x16x32_bf16 v[58:61], v[142:145], v[180:183], v[58:61]
	v_mfma_f32_16x16x32_bf16 v[46:49], v[134:137], v[190:193], v[46:49]
	v_mfma_f32_16x16x32_bf16 v[42:45], v[142:145], v[190:193], v[42:45]
	v_mfma_f32_16x16x32_bf16 v[30:33], v[134:137], v[198:201], v[30:33]
	v_mfma_f32_16x16x32_bf16 v[26:29], v[142:145], v[198:201], v[26:29]
	v_mfma_f32_16x16x32_bf16 v[14:17], v[134:137], v[220:223], v[14:17]
	v_mfma_f32_16x16x32_bf16 v[10:13], v[142:145], v[220:223], v[10:13]
	v_mfma_f32_16x16x32_bf16 v[54:57], v[146:149], v[176:179], 0
	v_mfma_f32_16x16x32_bf16 v[50:53], v[154:157], v[176:179], 0
	v_mfma_f32_16x16x32_bf16 v[38:41], v[146:149], v[184:187], 0
	v_mfma_f32_16x16x32_bf16 v[34:37], v[154:157], v[184:187], 0
	v_mfma_f32_16x16x32_bf16 v[22:25], v[146:149], v[194:197], 0
	v_mfma_f32_16x16x32_bf16 v[18:21], v[154:157], v[194:197], 0
	v_mfma_f32_16x16x32_bf16 v[6:9], v[146:149], v[216:219], 0
	v_mfma_f32_16x16x32_bf16 v[2:5], v[154:157], v[216:219], 0
	v_mfma_f32_16x16x32_bf16 v[54:57], v[150:153], v[180:183], v[54:57]
	v_mfma_f32_16x16x32_bf16 v[50:53], v[172:175], v[180:183], v[50:53]
	v_mfma_f32_16x16x32_bf16 v[38:41], v[150:153], v[190:193], v[38:41]
	v_mfma_f32_16x16x32_bf16 v[34:37], v[172:175], v[190:193], v[34:37]
	v_mfma_f32_16x16x32_bf16 v[22:25], v[150:153], v[198:201], v[22:25]
	v_mfma_f32_16x16x32_bf16 v[18:21], v[172:175], v[198:201], v[18:21]
	v_mfma_f32_16x16x32_bf16 v[6:9], v[150:153], v[220:223], v[6:9]
	v_mfma_f32_16x16x32_bf16 v[2:5], v[172:175], v[220:223], v[2:5]
	s_barrier
	v_add_u32_e32 v142, s82, v188
	v_add_u32_e32 v172, s83, v188
	ds_read_b128 v[130:133], v142
	ds_read_b128 v[134:137], v142 offset:1024
	ds_read_b128 v[138:141], v142 offset:2048
	ds_read_b128 v[142:145], v142 offset:3072
	ds_read_b128 v[146:149], v172
	ds_read_b128 v[150:153], v172 offset:1024
	ds_read_b128 v[154:157], v172 offset:2048
	ds_read_b128 v[172:175], v172 offset:3072
	s_add_u32 s18, s24, 0xb0000
	s_addc_u32 s19, s25, 0
	s_mov_b32 m0, s29
	ds_read_b128 v[176:179], v189 offset:32768
	ds_read_b128 v[180:183], v189 offset:33792
	ds_read_b128 v[184:187], v189 offset:34816
	ds_read_b128 v[190:193], v189 offset:35840
	ds_read_b128 v[194:197], v189 offset:36864
	ds_read_b128 v[198:201], v189 offset:37888
	ds_read_b128 v[216:219], v189 offset:38912
	ds_read_b128 v[220:223], v189 offset:39936
	global_load_lds_dwordx4 v158, s[18:19]
	s_mov_b32 m0, s30
	s_nop 0
	global_load_lds_dwordx4 v162, s[18:19]
	s_waitcnt vmcnt(8) lgkmcnt(0)
	s_barrier
	v_mfma_f32_16x16x32_bf16 v[126:129], v[130:133], v[176:179], v[126:129]
	v_mfma_f32_16x16x32_bf16 v[122:125], v[138:141], v[176:179], v[122:125]
	v_mfma_f32_16x16x32_bf16 v[110:113], v[130:133], v[184:187], v[110:113]
	v_mfma_f32_16x16x32_bf16 v[106:109], v[138:141], v[184:187], v[106:109]
	v_mfma_f32_16x16x32_bf16 v[94:97], v[130:133], v[194:197], v[94:97]
	v_mfma_f32_16x16x32_bf16 v[90:93], v[138:141], v[194:197], v[90:93]
	v_mfma_f32_16x16x32_bf16 v[78:81], v[130:133], v[216:219], v[78:81]
	v_mfma_f32_16x16x32_bf16 v[74:77], v[138:141], v[216:219], v[74:77]
	v_mfma_f32_16x16x32_bf16 v[126:129], v[134:137], v[180:183], v[126:129]
	v_mfma_f32_16x16x32_bf16 v[122:125], v[142:145], v[180:183], v[122:125]
	v_mfma_f32_16x16x32_bf16 v[110:113], v[134:137], v[190:193], v[110:113]
	v_mfma_f32_16x16x32_bf16 v[106:109], v[142:145], v[190:193], v[106:109]
	v_mfma_f32_16x16x32_bf16 v[94:97], v[134:137], v[198:201], v[94:97]
	v_mfma_f32_16x16x32_bf16 v[90:93], v[142:145], v[198:201], v[90:93]
	v_mfma_f32_16x16x32_bf16 v[78:81], v[134:137], v[220:223], v[78:81]
	v_mfma_f32_16x16x32_bf16 v[74:77], v[142:145], v[220:223], v[74:77]
	v_mfma_f32_16x16x32_bf16 v[118:121], v[146:149], v[176:179], v[118:121]
	v_mfma_f32_16x16x32_bf16 v[114:117], v[154:157], v[176:179], v[114:117]
	v_mfma_f32_16x16x32_bf16 v[102:105], v[146:149], v[184:187], v[102:105]
	v_mfma_f32_16x16x32_bf16 v[98:101], v[154:157], v[184:187], v[98:101]
	v_mfma_f32_16x16x32_bf16 v[86:89], v[146:149], v[194:197], v[86:89]
	v_mfma_f32_16x16x32_bf16 v[82:85], v[154:157], v[194:197], v[82:85]
	v_mfma_f32_16x16x32_bf16 v[70:73], v[146:149], v[216:219], v[70:73]
	v_mfma_f32_16x16x32_bf16 v[66:69], v[154:157], v[216:219], v[66:69]
	v_mfma_f32_16x16x32_bf16 v[118:121], v[150:153], v[180:183], v[118:121]
	v_mfma_f32_16x16x32_bf16 v[114:117], v[172:175], v[180:183], v[114:117]
	v_mfma_f32_16x16x32_bf16 v[102:105], v[150:153], v[190:193], v[102:105]
	v_mfma_f32_16x16x32_bf16 v[98:101], v[172:175], v[190:193], v[98:101]
	v_mfma_f32_16x16x32_bf16 v[86:89], v[150:153], v[198:201], v[86:89]
	v_mfma_f32_16x16x32_bf16 v[82:85], v[172:175], v[198:201], v[82:85]
	v_mfma_f32_16x16x32_bf16 v[70:73], v[150:153], v[220:223], v[70:73]
	v_mfma_f32_16x16x32_bf16 v[66:69], v[172:175], v[220:223], v[66:69]
	s_barrier
; #define PG8_STAGE(bufoff, gbase, voff) do { _Pragma("unroll") for (int _i = 0; _i < 2; ++_i) \
;         __builtin_amdgcn_global_load_lds((const unsigned*)((const char*)(gbase) + (voff)[_i]), (PG8_LAS unsigned*)(lds + (bufoff) + ldsw + _i * 8192), 16, 0, 0); } while (0)
; #define PG8_LDA(dst, b, h) do { _Pragma("unroll") for (int m = 0; m < 4; ++m) _Pragma("unroll") for (int k = 0; k < 2; ++k) dst[m][k] = *(const PG8_LAS bf16x8*)(lds + PG8_SA(b, h) + aoff + m * 2048 + k * 1024); } while (0)
; #define PG8_LDB(dst, b, h) do { _Pragma("unroll") for (int n = 0; n < 2; ++n) _Pragma("unroll") for (int k = 0; k < 2; ++k) dst[n][k] = *(const PG8_LAS bf16x8*)(lds + PG8_SB(b, h) + boff + n * 2048 + k * 1024); } while (0)
; #define PG8_MMA(ai, bj, At, Bt) do { __builtin_amdgcn_s_setprio(1); _Pragma("unroll") for (int m = 0; m < 4; ++m) _Pragma("unroll") for (int n = 0; n < 2; ++n) _Pragma("unroll") for (int k = 0; k < 2; ++k) \
;         acc[ai][bj][m][n] = __builtin_amdgcn_mfma_f32_16x16x32_bf16(Bt[n][k], At[m][k], acc[ai][bj][m][n], 0, 0, 0); __builtin_amdgcn_s_setprio(0); } while (0)
; #define PG8_WAIT_V(n) asm volatile("s_waitcnt vmcnt(" #n ")" ::: "memory")
; template <class Epi, class Sched, bool ALIGN_EPI = false, bool SP2 = false>
; __device__ __forceinline__ void gemm_phase(PG8_LAS unsigned char* lds, const Gemm g, const Sched& S, const Epi& E) {
;     ...
;             PG8_LDB(B0, 0, 0); PG8_LDB(B1, 0, 1); PG8_SCHED; PG8_LDA(At, 0, 0); PG8_STAGE(PG8_SA(1, 1), a1 + hstep, voffA);
;             PG8_WAIT_V(8); PG8_WAIT_L(0); PG8_BAR; PG8_MMA(0, 0, At, B0); PG8_MMA(0, 1, At, B1); PG8_BAR; PG8_SCHED;
;             PG8_LDA(At, 0, 1); PG8_STAGE(PG8_SB(0, 0), b2, voffB); PG8_STAGE(PG8_SB(0, 1), b2 + hstep, voffB); PG8_STAGE(PG8_SA(0, 0), a2, voffA);
;             PG8_WAIT_V(8); PG8_WAIT_L(0); PG8_BAR; PG8_MMA(1, 0, At, B0); PG8_MMA(1, 1, At, B1); PG8_BAR; PG8_SCHED;
;             PG8_LDB(B0, 1, 0); PG8_LDB(B1, 1, 1); PG8_SCHED; PG8_LDA(At, 1, 0); PG8_STAGE(PG8_SA(0, 1), a2 + hstep, voffA);
;             PG8_WAIT_V(8); PG8_WAIT_L(0); PG8_BAR; PG8_MMA(0, 0, At, B0); PG8_MMA(0, 1, At, B1); PG8_BAR; PG8_SCHED;
;             PG8_LDA(At, 1, 1); PG8_STAGE(PG8_SB(1, 0), b3, voffB); PG8_STAGE(PG8_SB(1, 1), b3 + hstep, voffB); PG8_STAGE(PG8_SA(1, 0), a3, voffA);
;             PG8_WAIT_V(8); PG8_WAIT_L(0); PG8_BAR; PG8_MMA(1, 0, At, B0); PG8_MMA(1, 1, At, B1); PG8_BAR; PG8_SCHED;
	s_add_i32 s18, s82, s26
	s_mov_b32 m0, s18
	ds_read_b128 v[176:179], v189 offset:49152
	ds_read_b128 v[180:183], v189 offset:50176
	ds_read_b128 v[184:187], v189 offset:51200
	ds_read_b128 v[190:193], v189 offset:52224
	ds_read_b128 v[194:197], v189 offset:53248
	ds_read_b128 v[198:201], v189 offset:54272
	ds_read_b128 v[216:219], v189 offset:55296
	ds_read_b128 v[220:223], v189 offset:56320
	global_load_lds_dwordx4 v160, s[98:99]
	s_add_i32 m0, s18, 0x2000
	s_add_u32 s18, s22, 0xb0080
	s_addc_u32 s19, s23, 0
	s_add_i32 s22, s83, s26
	global_load_lds_dwordx4 v164, s[98:99]
	s_mov_b32 m0, s22
	s_nop 0
	global_load_lds_dwordx4 v160, s[18:19]
	s_add_i32 m0, s22, 0x2000
	s_nop 0
	global_load_lds_dwordx4 v164, s[18:19]
	s_mov_b32 m0, s31
	s_nop 0
	global_load_lds_dwordx4 v158, s[100:101]
	s_mov_b32 m0, s34
	s_nop 0
	global_load_lds_dwordx4 v162, s[100:101]
	s_waitcnt vmcnt(8) lgkmcnt(0)
	s_barrier
	v_mfma_f32_16x16x32_bf16 v[62:65], v[130:133], v[176:179], v[62:65]
	v_mfma_f32_16x16x32_bf16 v[58:61], v[138:141], v[176:179], v[58:61]
	v_mfma_f32_16x16x32_bf16 v[46:49], v[130:133], v[184:187], v[46:49]
	v_mfma_f32_16x16x32_bf16 v[42:45], v[138:141], v[184:187], v[42:45]
	v_mfma_f32_16x16x32_bf16 v[30:33], v[130:133], v[194:197], v[30:33]
	v_mfma_f32_16x16x32_bf16 v[26:29], v[138:141], v[194:197], v[26:29]
	v_mfma_f32_16x16x32_bf16 v[14:17], v[130:133], v[216:219], v[14:17]
	v_mfma_f32_16x16x32_bf16 v[10:13], v[138:141], v[216:219], v[10:13]
	v_mfma_f32_16x16x32_bf16 v[62:65], v[134:137], v[180:183], v[62:65]
	v_mfma_f32_16x16x32_bf16 v[58:61], v[142:145], v[180:183], v[58:61]
	v_mfma_f32_16x16x32_bf16 v[46:49], v[134:137], v[190:193], v[46:49]
	v_mfma_f32_16x16x32_bf16 v[42:45], v[142:145], v[190:193], v[42:45]
	v_mfma_f32_16x16x32_bf16 v[30:33], v[134:137], v[198:201], v[30:33]
	v_mfma_f32_16x16x32_bf16 v[26:29], v[142:145], v[198:201], v[26:29]
	v_mfma_f32_16x16x32_bf16 v[14:17], v[134:137], v[220:223], v[14:17]
	v_mfma_f32_16x16x32_bf16 v[10:13], v[142:145], v[220:223], v[10:13]
	v_mfma_f32_16x16x32_bf16 v[54:57], v[146:149], v[176:179], v[54:57]
	v_mfma_f32_16x16x32_bf16 v[50:53], v[154:157], v[176:179], v[50:53]
	v_mfma_f32_16x16x32_bf16 v[38:41], v[146:149], v[184:187], v[38:41]
	v_mfma_f32_16x16x32_bf16 v[34:37], v[154:157], v[184:187], v[34:37]
	v_mfma_f32_16x16x32_bf16 v[22:25], v[146:149], v[194:197], v[22:25]
	v_mfma_f32_16x16x32_bf16 v[18:21], v[154:157], v[194:197], v[18:21]
	v_mfma_f32_16x16x32_bf16 v[6:9], v[146:149], v[216:219], v[6:9]
	v_mfma_f32_16x16x32_bf16 v[2:5], v[154:157], v[216:219], v[2:5]
	v_mfma_f32_16x16x32_bf16 v[54:57], v[150:153], v[180:183], v[54:57]
	v_mfma_f32_16x16x32_bf16 v[50:53], v[172:175], v[180:183], v[50:53]
	v_mfma_f32_16x16x32_bf16 v[38:41], v[150:153], v[190:193], v[38:41]
	v_mfma_f32_16x16x32_bf16 v[34:37], v[172:175], v[190:193], v[34:37]
	v_mfma_f32_16x16x32_bf16 v[22:25], v[150:153], v[198:201], v[22:25]
	v_mfma_f32_16x16x32_bf16 v[18:21], v[172:175], v[198:201], v[18:21]
	v_mfma_f32_16x16x32_bf16 v[6:9], v[150:153], v[220:223], v[6:9]
	v_mfma_f32_16x16x32_bf16 v[2:5], v[172:175], v[220:223], v[2:5]
	s_barrier
	s_add_i32 s44, s44, 2
	s_add_u32 s39, s39, 0x100
	s_addc_u32 s42, s42, 0
	s_mov_b64 s[18:19], s[20:21]
.LBB0_212:
	v_add_u32_e32 v142, s90, v188
	v_add_u32_e32 v172, s81, v188
	ds_read_b128 v[130:133], v142
	ds_read_b128 v[134:137], v142 offset:1024
	ds_read_b128 v[138:141], v142 offset:2048
	ds_read_b128 v[142:145], v142 offset:3072
	ds_read_b128 v[146:149], v172
	ds_read_b128 v[150:153], v172 offset:1024
	ds_read_b128 v[154:157], v172 offset:2048
	ds_read_b128 v[172:175], v172 offset:3072
	s_add_u32 s20, s18, 0x100
	s_addc_u32 s21, s19, 0
	s_cmp_eq_u32 s44, 40
	s_cselect_b32 s25, s7, s21
	s_cselect_b32 s24, s6, s20
	s_cselect_b32 s23, s15, s42
	s_cselect_b32 s22, s14, s39
	s_add_u32 s98, s22, s46
	s_addc_u32 s99, s23, s47
	s_add_u32 s100, s24, s46
	s_addc_u32 s101, s25, s47
	s_add_i32 m0, s27, 0xc000
	ds_read_b128 v[176:179], v189
	ds_read_b128 v[180:183], v189 offset:1024
	ds_read_b128 v[184:187], v189 offset:2048
	ds_read_b128 v[190:193], v189 offset:3072
	ds_read_b128 v[194:197], v189 offset:4096
	ds_read_b128 v[198:201], v189 offset:5120
	ds_read_b128 v[216:219], v189 offset:6144
	ds_read_b128 v[220:223], v189 offset:7168
	global_load_lds_dwordx4 v168, s[18:19]
	s_add_i32 m0, s27, 0xe000
	s_nop 0
	global_load_lds_dwordx4 v170, s[18:19]
	s_waitcnt vmcnt(8) lgkmcnt(0)
	s_barrier
	v_mfma_f32_16x16x32_bf16 v[126:129], v[130:133], v[176:179], v[126:129]
	v_mfma_f32_16x16x32_bf16 v[122:125], v[138:141], v[176:179], v[122:125]
	v_mfma_f32_16x16x32_bf16 v[110:113], v[130:133], v[184:187], v[110:113]
	v_mfma_f32_16x16x32_bf16 v[106:109], v[138:141], v[184:187], v[106:109]
	v_mfma_f32_16x16x32_bf16 v[94:97], v[130:133], v[194:197], v[94:97]
	v_mfma_f32_16x16x32_bf16 v[90:93], v[138:141], v[194:197], v[90:93]
	v_mfma_f32_16x16x32_bf16 v[78:81], v[130:133], v[216:219], v[78:81]
	v_mfma_f32_16x16x32_bf16 v[74:77], v[138:141], v[216:219], v[74:77]
	v_mfma_f32_16x16x32_bf16 v[126:129], v[134:137], v[180:183], v[126:129]
	v_mfma_f32_16x16x32_bf16 v[122:125], v[142:145], v[180:183], v[122:125]
	v_mfma_f32_16x16x32_bf16 v[110:113], v[134:137], v[190:193], v[110:113]
	v_mfma_f32_16x16x32_bf16 v[106:109], v[142:145], v[190:193], v[106:109]
	v_mfma_f32_16x16x32_bf16 v[94:97], v[134:137], v[198:201], v[94:97]
	v_mfma_f32_16x16x32_bf16 v[90:93], v[142:145], v[198:201], v[90:93]
	v_mfma_f32_16x16x32_bf16 v[78:81], v[134:137], v[220:223], v[78:81]
	v_mfma_f32_16x16x32_bf16 v[74:77], v[142:145], v[220:223], v[74:77]
	v_mfma_f32_16x16x32_bf16 v[118:121], v[146:149], v[176:179], v[118:121]
	v_mfma_f32_16x16x32_bf16 v[114:117], v[154:157], v[176:179], v[114:117]
	v_mfma_f32_16x16x32_bf16 v[102:105], v[146:149], v[184:187], v[102:105]
	v_mfma_f32_16x16x32_bf16 v[98:101], v[154:157], v[184:187], v[98:101]
	v_mfma_f32_16x16x32_bf16 v[86:89], v[146:149], v[194:197], v[86:89]
	v_mfma_f32_16x16x32_bf16 v[82:85], v[154:157], v[194:197], v[82:85]
	v_mfma_f32_16x16x32_bf16 v[70:73], v[146:149], v[216:219], v[70:73]
	v_mfma_f32_16x16x32_bf16 v[66:69], v[154:157], v[216:219], v[66:69]
	v_mfma_f32_16x16x32_bf16 v[118:121], v[150:153], v[180:183], v[118:121]
	v_mfma_f32_16x16x32_bf16 v[114:117], v[172:175], v[180:183], v[114:117]
	v_mfma_f32_16x16x32_bf16 v[102:105], v[150:153], v[190:193], v[102:105]
	v_mfma_f32_16x16x32_bf16 v[98:101], v[172:175], v[190:193], v[98:101]
	v_mfma_f32_16x16x32_bf16 v[86:89], v[150:153], v[198:201], v[86:89]
	v_mfma_f32_16x16x32_bf16 v[82:85], v[172:175], v[198:201], v[82:85]
	v_mfma_f32_16x16x32_bf16 v[70:73], v[150:153], v[220:223], v[70:73]
	v_mfma_f32_16x16x32_bf16 v[66:69], v[172:175], v[220:223], v[66:69]
	s_barrier
; #define PG8_STAGE(bufoff, gbase, voff) do { _Pragma("unroll") for (int _i = 0; _i < 2; ++_i) \
;         __builtin_amdgcn_global_load_lds((const unsigned*)((const char*)(gbase) + (voff)[_i]), (PG8_LAS unsigned*)(lds + (bufoff) + ldsw + _i * 8192), 16, 0, 0); } while (0)
; #define PG8_LDA(dst, b, h) do { _Pragma("unroll") for (int m = 0; m < 4; ++m) _Pragma("unroll") for (int k = 0; k < 2; ++k) dst[m][k] = *(const PG8_LAS bf16x8*)(lds + PG8_SA(b, h) + aoff + m * 2048 + k * 1024); } while (0)
; #define PG8_LDB(dst, b, h) do { _Pragma("unroll") for (int n = 0; n < 2; ++n) _Pragma("unroll") for (int k = 0; k < 2; ++k) dst[n][k] = *(const PG8_LAS bf16x8*)(lds + PG8_SB(b, h) + boff + n * 2048 + k * 1024); } while (0)
; #define PG8_MMA(ai, bj, At, Bt) do { __builtin_amdgcn_s_setprio(1); _Pragma("unroll") for (int m = 0; m < 4; ++m) _Pragma("unroll") for (int n = 0; n < 2; ++n) _Pragma("unroll") for (int k = 0; k < 2; ++k) \
;         acc[ai][bj][m][n] = __builtin_amdgcn_mfma_f32_16x16x32_bf16(Bt[n][k], At[m][k], acc[ai][bj][m][n], 0, 0, 0); __builtin_amdgcn_s_setprio(0); } while (0)
; #define PG8_WAIT_V(n) asm volatile("s_waitcnt vmcnt(" #n ")" ::: "memory")
; #define PG8_WAIT_L(n) asm volatile("s_waitcnt lgkmcnt(" #n ")" ::: "memory")
; #define PG8_BAR __builtin_amdgcn_s_barrier()
; #define PG8_SCHED __builtin_amdgcn_sched_barrier(0)
; template <class Epi, class Sched, bool ALIGN_EPI = false, bool SP2 = false>
; __device__ __forceinline__ void gemm_phase(PG8_LAS unsigned char* lds, const Gemm g, const Sched& S, const Epi& E) {
;     ...
;             PG8_LDA(At, 0, 1); PG8_STAGE(PG8_SB(0, 0), b2, voffB); PG8_STAGE(PG8_SB(0, 1), b2 + hstep, voffB); PG8_STAGE(PG8_SA(0, 0), a2, voffA);
;             PG8_WAIT_V(8); PG8_WAIT_L(0); PG8_BAR; PG8_MMA(1, 0, At, B0); PG8_MMA(1, 1, At, B1); PG8_BAR; PG8_SCHED;
;             PG8_LDB(B0, 1, 0); PG8_LDB(B1, 1, 1); PG8_SCHED; PG8_LDA(At, 1, 0); PG8_STAGE(PG8_SA(0, 1), a2 + hstep, voffA);
	s_add_i32 s18, s90, s26
	s_mov_b32 m0, s18
	ds_read_b128 v[176:179], v189 offset:16384
	ds_read_b128 v[180:183], v189 offset:17408
	ds_read_b128 v[184:187], v189 offset:18432
	ds_read_b128 v[190:193], v189 offset:19456
	ds_read_b128 v[194:197], v189 offset:20480
	ds_read_b128 v[198:201], v189 offset:21504
	ds_read_b128 v[216:219], v189 offset:22528
	ds_read_b128 v[220:223], v189 offset:23552
	global_load_lds_dwordx4 v160, s[22:23]
	s_add_i32 m0, s18, 0x2000
	s_add_u32 s18, s22, 0xb0000
	s_addc_u32 s19, s23, 0
	s_add_i32 s45, s81, s26
	global_load_lds_dwordx4 v164, s[22:23]
	s_mov_b32 m0, s45
	s_nop 0
	global_load_lds_dwordx4 v160, s[18:19]
	s_add_i32 m0, s45, 0x2000
	s_nop 0
	global_load_lds_dwordx4 v164, s[18:19]
	s_mov_b32 m0, s27
	s_nop 0
	global_load_lds_dwordx4 v158, s[24:25]
	s_mov_b32 m0, s28
	s_nop 0
	global_load_lds_dwordx4 v162, s[24:25]
	s_waitcnt vmcnt(8) lgkmcnt(0)
	s_barrier
	v_mfma_f32_16x16x32_bf16 v[62:65], v[130:133], v[176:179], v[62:65]
	v_mfma_f32_16x16x32_bf16 v[58:61], v[138:141], v[176:179], v[58:61]
	v_mfma_f32_16x16x32_bf16 v[46:49], v[130:133], v[184:187], v[46:49]
	v_mfma_f32_16x16x32_bf16 v[42:45], v[138:141], v[184:187], v[42:45]
	v_mfma_f32_16x16x32_bf16 v[30:33], v[130:133], v[194:197], v[30:33]
	v_mfma_f32_16x16x32_bf16 v[26:29], v[138:141], v[194:197], v[26:29]
	v_mfma_f32_16x16x32_bf16 v[14:17], v[130:133], v[216:219], v[14:17]
	v_mfma_f32_16x16x32_bf16 v[10:13], v[138:141], v[216:219], v[10:13]
	v_mfma_f32_16x16x32_bf16 v[62:65], v[134:137], v[180:183], v[62:65]
	v_mfma_f32_16x16x32_bf16 v[58:61], v[142:145], v[180:183], v[58:61]
	v_mfma_f32_16x16x32_bf16 v[46:49], v[134:137], v[190:193], v[46:49]
	v_mfma_f32_16x16x32_bf16 v[42:45], v[142:145], v[190:193], v[42:45]
	v_mfma_f32_16x16x32_bf16 v[30:33], v[134:137], v[198:201], v[30:33]
	v_mfma_f32_16x16x32_bf16 v[26:29], v[142:145], v[198:201], v[26:29]
	v_mfma_f32_16x16x32_bf16 v[14:17], v[134:137], v[220:223], v[14:17]
	v_mfma_f32_16x16x32_bf16 v[10:13], v[142:145], v[220:223], v[10:13]
	v_mfma_f32_16x16x32_bf16 v[54:57], v[146:149], v[176:179], v[54:57]
	v_mfma_f32_16x16x32_bf16 v[50:53], v[154:157], v[176:179], v[50:53]
	v_mfma_f32_16x16x32_bf16 v[38:41], v[146:149], v[184:187], v[38:41]
	v_mfma_f32_16x16x32_bf16 v[34:37], v[154:157], v[184:187], v[34:37]
	v_mfma_f32_16x16x32_bf16 v[22:25], v[146:149], v[194:197], v[22:25]
	v_mfma_f32_16x16x32_bf16 v[18:21], v[154:157], v[194:197], v[18:21]
	v_mfma_f32_16x16x32_bf16 v[6:9], v[146:149], v[216:219], v[6:9]
	v_mfma_f32_16x16x32_bf16 v[2:5], v[154:157], v[216:219], v[2:5]
	v_mfma_f32_16x16x32_bf16 v[54:57], v[150:153], v[180:183], v[54:57]
	v_mfma_f32_16x16x32_bf16 v[50:53], v[172:175], v[180:183], v[50:53]
	v_mfma_f32_16x16x32_bf16 v[38:41], v[150:153], v[190:193], v[38:41]
	v_mfma_f32_16x16x32_bf16 v[34:37], v[172:175], v[190:193], v[34:37]
	v_mfma_f32_16x16x32_bf16 v[22:25], v[150:153], v[198:201], v[22:25]
	v_mfma_f32_16x16x32_bf16 v[18:21], v[172:175], v[198:201], v[18:21]
	v_mfma_f32_16x16x32_bf16 v[6:9], v[150:153], v[220:223], v[6:9]
	v_mfma_f32_16x16x32_bf16 v[2:5], v[172:175], v[220:223], v[2:5]
	s_barrier
	v_add_u32_e32 v142, s82, v188
	v_add_u32_e32 v172, s83, v188
	ds_read_b128 v[130:133], v142
	ds_read_b128 v[134:137], v142 offset:1024
	ds_read_b128 v[138:141], v142 offset:2048
	ds_read_b128 v[142:145], v142 offset:3072
	ds_read_b128 v[146:149], v172
	ds_read_b128 v[150:153], v172 offset:1024
	ds_read_b128 v[154:157], v172 offset:2048
	ds_read_b128 v[172:175], v172 offset:3072
	s_add_u32 s18, s24, 0xb0000
	s_addc_u32 s19, s25, 0
	s_mov_b32 m0, s29
	ds_read_b128 v[176:179], v189 offset:32768
	ds_read_b128 v[180:183], v189 offset:33792
	ds_read_b128 v[184:187], v189 offset:34816
	ds_read_b128 v[190:193], v189 offset:35840
	ds_read_b128 v[194:197], v189 offset:36864
	ds_read_b128 v[198:201], v189 offset:37888
	ds_read_b128 v[216:219], v189 offset:38912
	ds_read_b128 v[220:223], v189 offset:39936
	global_load_lds_dwordx4 v158, s[18:19]
	s_mov_b32 m0, s30
	s_nop 0
	global_load_lds_dwordx4 v162, s[18:19]
	s_waitcnt vmcnt(8) lgkmcnt(0)
	s_barrier
; #define PG8_STAGE(bufoff, gbase, voff) do { _Pragma("unroll") for (int _i = 0; _i < 2; ++_i) \
;         __builtin_amdgcn_global_load_lds((const unsigned*)((const char*)(gbase) + (voff)[_i]), (PG8_LAS unsigned*)(lds + (bufoff) + ldsw + _i * 8192), 16, 0, 0); } while (0)
; #define PG8_LDA(dst, b, h) do { _Pragma("unroll") for (int m = 0; m < 4; ++m) _Pragma("unroll") for (int k = 0; k < 2; ++k) dst[m][k] = *(const PG8_LAS bf16x8*)(lds + PG8_SA(b, h) + aoff + m * 2048 + k * 1024); } while (0)
; #define PG8_MMA(ai, bj, At, Bt) do { __builtin_amdgcn_s_setprio(1); _Pragma("unroll") for (int m = 0; m < 4; ++m) _Pragma("unroll") for (int n = 0; n < 2; ++n) _Pragma("unroll") for (int k = 0; k < 2; ++k) \
;         acc[ai][bj][m][n] = __builtin_amdgcn_mfma_f32_16x16x32_bf16(Bt[n][k], At[m][k], acc[ai][bj][m][n], 0, 0, 0); __builtin_amdgcn_s_setprio(0); } while (0)
; #define PG8_WAIT_V(n) asm volatile("s_waitcnt vmcnt(" #n ")" ::: "memory")
; #define PG8_WAIT_L(n) asm volatile("s_waitcnt lgkmcnt(" #n ")" ::: "memory")
; #define PG8_BAR __builtin_amdgcn_s_barrier()
; #define PG8_SCHED __builtin_amdgcn_sched_barrier(0)
; template <class Epi, class Sched, bool ALIGN_EPI = false, bool SP2 = false>
; __device__ __forceinline__ void gemm_phase(PG8_LAS unsigned char* lds, const Gemm g, const Sched& S, const Epi& E) {
;     ...
;             PG8_WAIT_V(8); PG8_WAIT_L(0); PG8_BAR; PG8_MMA(0, 0, At, B0); PG8_MMA(0, 1, At, B1); PG8_BAR; PG8_SCHED;
;             PG8_LDA(At, 1, 1); PG8_STAGE(PG8_SB(1, 0), b3, voffB); PG8_STAGE(PG8_SB(1, 1), b3 + hstep, voffB); PG8_STAGE(PG8_SA(1, 0), a3, voffA);
;             PG8_WAIT_V(8); PG8_WAIT_L(0); PG8_BAR; PG8_MMA(1, 0, At, B0); PG8_MMA(1, 1, At, B1); PG8_BAR; PG8_SCHED;
	v_mfma_f32_16x16x32_bf16 v[126:129], v[130:133], v[176:179], v[126:129]
	v_mfma_f32_16x16x32_bf16 v[122:125], v[138:141], v[176:179], v[122:125]
	v_mfma_f32_16x16x32_bf16 v[110:113], v[130:133], v[184:187], v[110:113]
	v_mfma_f32_16x16x32_bf16 v[106:109], v[138:141], v[184:187], v[106:109]
	v_mfma_f32_16x16x32_bf16 v[94:97], v[130:133], v[194:197], v[94:97]
	v_mfma_f32_16x16x32_bf16 v[90:93], v[138:141], v[194:197], v[90:93]
	v_mfma_f32_16x16x32_bf16 v[78:81], v[130:133], v[216:219], v[78:81]
	v_mfma_f32_16x16x32_bf16 v[74:77], v[138:141], v[216:219], v[74:77]
	v_mfma_f32_16x16x32_bf16 v[126:129], v[134:137], v[180:183], v[126:129]
	v_mfma_f32_16x16x32_bf16 v[122:125], v[142:145], v[180:183], v[122:125]
	v_mfma_f32_16x16x32_bf16 v[110:113], v[134:137], v[190:193], v[110:113]
	v_mfma_f32_16x16x32_bf16 v[106:109], v[142:145], v[190:193], v[106:109]
	v_mfma_f32_16x16x32_bf16 v[94:97], v[134:137], v[198:201], v[94:97]
	v_mfma_f32_16x16x32_bf16 v[90:93], v[142:145], v[198:201], v[90:93]
	v_mfma_f32_16x16x32_bf16 v[78:81], v[134:137], v[220:223], v[78:81]
	v_mfma_f32_16x16x32_bf16 v[74:77], v[142:145], v[220:223], v[74:77]
	v_mfma_f32_16x16x32_bf16 v[118:121], v[146:149], v[176:179], v[118:121]
	v_mfma_f32_16x16x32_bf16 v[114:117], v[154:157], v[176:179], v[114:117]
	v_mfma_f32_16x16x32_bf16 v[102:105], v[146:149], v[184:187], v[102:105]
	v_mfma_f32_16x16x32_bf16 v[98:101], v[154:157], v[184:187], v[98:101]
	v_mfma_f32_16x16x32_bf16 v[86:89], v[146:149], v[194:197], v[86:89]
	v_mfma_f32_16x16x32_bf16 v[82:85], v[154:157], v[194:197], v[82:85]
	v_mfma_f32_16x16x32_bf16 v[70:73], v[146:149], v[216:219], v[70:73]
	v_mfma_f32_16x16x32_bf16 v[66:69], v[154:157], v[216:219], v[66:69]
	v_mfma_f32_16x16x32_bf16 v[118:121], v[150:153], v[180:183], v[118:121]
	v_mfma_f32_16x16x32_bf16 v[114:117], v[172:175], v[180:183], v[114:117]
	v_mfma_f32_16x16x32_bf16 v[102:105], v[150:153], v[190:193], v[102:105]
	v_mfma_f32_16x16x32_bf16 v[98:101], v[172:175], v[190:193], v[98:101]
	v_mfma_f32_16x16x32_bf16 v[86:89], v[150:153], v[198:201], v[86:89]
	v_mfma_f32_16x16x32_bf16 v[82:85], v[172:175], v[198:201], v[82:85]
	v_mfma_f32_16x16x32_bf16 v[70:73], v[150:153], v[220:223], v[70:73]
	v_mfma_f32_16x16x32_bf16 v[66:69], v[172:175], v[220:223], v[66:69]
	s_barrier
	s_add_i32 s18, s82, s26
	s_mov_b32 m0, s18
	ds_read_b128 v[176:179], v189 offset:49152
	ds_read_b128 v[180:183], v189 offset:50176
	ds_read_b128 v[184:187], v189 offset:51200
	ds_read_b128 v[190:193], v189 offset:52224
	ds_read_b128 v[194:197], v189 offset:53248
	ds_read_b128 v[198:201], v189 offset:54272
	ds_read_b128 v[216:219], v189 offset:55296
	ds_read_b128 v[220:223], v189 offset:56320
	global_load_lds_dwordx4 v160, s[98:99]
	s_add_i32 m0, s18, 0x2000
	s_add_u32 s18, s22, 0xb0080
	s_addc_u32 s19, s23, 0
	s_add_i32 s22, s83, s26
	global_load_lds_dwordx4 v164, s[98:99]
	s_mov_b32 m0, s22
	s_nop 0
	global_load_lds_dwordx4 v160, s[18:19]
	s_add_i32 m0, s22, 0x2000
	s_nop 0
	global_load_lds_dwordx4 v164, s[18:19]
	s_mov_b32 m0, s31
	s_nop 0
	global_load_lds_dwordx4 v158, s[100:101]
	s_mov_b32 m0, s34
	s_nop 0
	global_load_lds_dwordx4 v162, s[100:101]
	s_waitcnt vmcnt(8) lgkmcnt(0)
	s_barrier
	v_mfma_f32_16x16x32_bf16 v[62:65], v[130:133], v[176:179], v[62:65]
	v_mfma_f32_16x16x32_bf16 v[58:61], v[138:141], v[176:179], v[58:61]
	v_mfma_f32_16x16x32_bf16 v[46:49], v[130:133], v[184:187], v[46:49]
	v_mfma_f32_16x16x32_bf16 v[42:45], v[138:141], v[184:187], v[42:45]
	v_mfma_f32_16x16x32_bf16 v[30:33], v[130:133], v[194:197], v[30:33]
	v_mfma_f32_16x16x32_bf16 v[26:29], v[138:141], v[194:197], v[26:29]
	v_mfma_f32_16x16x32_bf16 v[14:17], v[130:133], v[216:219], v[14:17]
	v_mfma_f32_16x16x32_bf16 v[10:13], v[138:141], v[216:219], v[10:13]
	v_mfma_f32_16x16x32_bf16 v[62:65], v[134:137], v[180:183], v[62:65]
	v_mfma_f32_16x16x32_bf16 v[58:61], v[142:145], v[180:183], v[58:61]
	v_mfma_f32_16x16x32_bf16 v[46:49], v[134:137], v[190:193], v[46:49]
	v_mfma_f32_16x16x32_bf16 v[42:45], v[142:145], v[190:193], v[42:45]
	v_mfma_f32_16x16x32_bf16 v[30:33], v[134:137], v[198:201], v[30:33]
	v_mfma_f32_16x16x32_bf16 v[26:29], v[142:145], v[198:201], v[26:29]
	v_mfma_f32_16x16x32_bf16 v[14:17], v[134:137], v[220:223], v[14:17]
	v_mfma_f32_16x16x32_bf16 v[10:13], v[142:145], v[220:223], v[10:13]
	v_mfma_f32_16x16x32_bf16 v[54:57], v[146:149], v[176:179], v[54:57]
	v_mfma_f32_16x16x32_bf16 v[50:53], v[154:157], v[176:179], v[50:53]
	v_mfma_f32_16x16x32_bf16 v[38:41], v[146:149], v[184:187], v[38:41]
	v_mfma_f32_16x16x32_bf16 v[34:37], v[154:157], v[184:187], v[34:37]
	v_mfma_f32_16x16x32_bf16 v[22:25], v[146:149], v[194:197], v[22:25]
	v_mfma_f32_16x16x32_bf16 v[18:21], v[154:157], v[194:197], v[18:21]
	v_mfma_f32_16x16x32_bf16 v[6:9], v[146:149], v[216:219], v[6:9]
	v_mfma_f32_16x16x32_bf16 v[2:5], v[154:157], v[216:219], v[2:5]
	v_mfma_f32_16x16x32_bf16 v[54:57], v[150:153], v[180:183], v[54:57]
	v_mfma_f32_16x16x32_bf16 v[50:53], v[172:175], v[180:183], v[50:53]
	v_mfma_f32_16x16x32_bf16 v[38:41], v[150:153], v[190:193], v[38:41]
	v_mfma_f32_16x16x32_bf16 v[34:37], v[172:175], v[190:193], v[34:37]
	v_mfma_f32_16x16x32_bf16 v[22:25], v[150:153], v[198:201], v[22:25]
	v_mfma_f32_16x16x32_bf16 v[18:21], v[172:175], v[198:201], v[18:21]
	v_mfma_f32_16x16x32_bf16 v[6:9], v[150:153], v[220:223], v[6:9]
	v_mfma_f32_16x16x32_bf16 v[2:5], v[172:175], v[220:223], v[2:5]
	s_barrier
	s_add_i32 s44, s44, 2
	s_add_u32 s39, s39, 0x100
	s_addc_u32 s42, s42, 0
	s_cmp_gt_u32 s44, 41
	s_mov_b64 s[18:19], s[20:21]
	s_cbranch_scc0 .LBB0_212
	s_setprio 0
	s_and_b64 vcc, exec, s[10:11]
	s_cbranch_vccz .LBB0_215
	s_barrier

; #define PG8_STAGE(bufoff, gbase, voff) do { _Pragma("unroll") for (int _i = 0; _i < 2; ++_i) \
;         __builtin_amdgcn_global_load_lds((const unsigned*)((const char*)(gbase) + (voff)[_i]), (PG8_LAS unsigned*)(lds + (bufoff) + ldsw + _i * 8192), 16, 0, 0); } while (0)
; #define PG8_LDA(dst, b, h) do { _Pragma("unroll") for (int m = 0; m < 4; ++m) _Pragma("unroll") for (int k = 0; k < 2; ++k) dst[m][k] = *(const PG8_LAS bf16x8*)(lds + PG8_SA(b, h) + aoff + m * 2048 + k * 1024); } while (0)
; #define PG8_LDB(dst, b, h) do { _Pragma("unroll") for (int n = 0; n < 2; ++n) _Pragma("unroll") for (int k = 0; k < 2; ++k) dst[n][k] = *(const PG8_LAS bf16x8*)(lds + PG8_SB(b, h) + boff + n * 2048 + k * 1024); } while (0)
; #define PG8_WAIT_V(n) asm volatile("s_waitcnt vmcnt(" #n ")" ::: "memory")
; template <class Epi, class Sched, bool ALIGN_EPI = false, bool SP2 = false>
; __device__ __forceinline__ void gemm_phase(PG8_LAS unsigned char* lds, const Gemm g, const Sched& S, const Epi& E) {
;     ...
;         const bool has_next = S.next(ui + 1, nxt);
;         const char* nA = has_next ? (const char*)g.A + (size_t)nxt.pm * tstep : cA; const char* nB = has_next ? (const char*)g.Bt + (size_t)nxt.pn * tstep : cB;
;         constexpr int NSEG = (Epi::MID_T >= 0) ? 2 : 1;
; #pragma unroll 1
;         for (int seg = 0; seg < NSEG; ++seg) {
;         const int t_lo = (seg == 0) ? 0 : Epi::MID_T, t_hi = (NSEG == 2 && seg == 0) ? Epi::MID_T : nt;
;         if constexpr (Epi::MID_T >= 0) { if (seg == 1) E.mid(acc, ui, wr, fr); }
;         for (int t = t_lo; t < t_hi; t += 2) {
;             const bool last = (t == nt - 2);
;             const char* a1 = cA + (size_t)(t + 1) * kstep;
;             const char* a2 = last ? nA : cA + (size_t)(t + 2) * kstep; const char* b2 = last ? nB : cB + (size_t)(t + 2) * kstep;
;             const char* a3 = a2 + kstep; const char* b3 = b2 + kstep;
;             if (last && has_next) S.a_ready_inloop(nxt, ui + 1);
;             if constexpr (SP2) {
;             PG8_LDB(B0, 0, 0); PG8_LDB(B1, 0, 1); PG8_SCHED; PG8_LDA(At, 0, 0); PG8_STAGE(PG8_SA(1, 1), a1 + hstep, voffA);
;             PG8_WAIT_V(8); PG8_WAIT_L(0); PG8_BAR; PG8_MMA(0, 0, At, B0); PG8_MMA(0, 1, At, B1); PG8_BAR; PG8_SCHED;
;             PG8_LDA(At, 0, 1); PG8_STAGE(PG8_SB(0, 0), b2, voffB); PG8_STAGE(PG8_SB(0, 1), b2 + hstep, voffB); PG8_STAGE(PG8_SA(0, 0), a2, voffA);
.LBB0_318:
	s_ashr_i32 s17, s16, 31
	s_lshl_b64 s[20:21], s[16:17], 19
	s_add_u32 s20, s34, s20
	s_addc_u32 s21, s35, s21
	s_and_b64 s[22:23], s[2:3], exec
	s_cselect_b32 s13, s21, s25
	s_cselect_b32 s17, s20, s24
	s_ashr_i32 s19, s18, 31
	s_lshl_b64 s[22:23], s[18:19], 19
	s_add_u32 s22, s36, s22
	s_addc_u32 s23, s37, s23
	s_and_b64 s[28:29], s[2:3], exec
	s_cselect_b32 s19, s23, s27
	s_cselect_b32 s42, s22, s26
	s_add_u32 s24, s24, 0x40080
	s_addc_u32 s25, s25, 0
	s_add_u32 s44, s26, 0x100
	s_addc_u32 s45, s27, 0
	s_mov_b32 s52, -2
	v_readfirstlane_b32 s98, v204
	s_nop 3
	s_cmp_ge_u32 s98, 0x100
	s_cbranch_scc0 .Lprio_skip_2
	s_setprio 1
.Lprio_skip_2:
	v_add_u32_e32 v158, s90, v200
	v_add_u32_e32 v174, s81, v200
	ds_read_b128 v[146:149], v158
	ds_read_b128 v[150:153], v158 offset:1024
	ds_read_b128 v[154:157], v158 offset:2048
	ds_read_b128 v[158:161], v158 offset:3072
	ds_read_b128 v[162:165], v174
	ds_read_b128 v[166:169], v174 offset:1024
	ds_read_b128 v[170:173], v174 offset:2048
	ds_read_b128 v[174:177], v174 offset:3072
	s_add_u32 s26, s24, 0xfffc0080
	s_addc_u32 s27, s25, -1
	s_cmp_eq_u32 s52, 12
	s_cselect_b32 s29, s13, s27
	s_cselect_b32 s28, s17, s26
	s_cselect_b32 s27, s19, s45
	s_cselect_b32 s26, s42, s44
	s_add_u32 s98, s26, s46
	s_addc_u32 s99, s27, s47
	s_add_u32 s100, s28, s46
	s_addc_u32 s101, s29, s47
	s_add_i32 m0, s39, 0xc000
	ds_read_b128 v[216:219], v202
	ds_read_b128 v[220:223], v202 offset:1024
	ds_read_b128 v[224:227], v202 offset:2048
	ds_read_b128 v[228:231], v202 offset:3072
	ds_read_b128 v[232:235], v202 offset:4096
	ds_read_b128 v[236:239], v202 offset:5120
	ds_read_b128 v[240:243], v202 offset:6144
	ds_read_b128 v[244:247], v202 offset:7168
	global_load_lds_dwordx4 v190, s[24:25]
	s_add_i32 m0, s39, 0xe000
	s_nop 0
	global_load_lds_dwordx4 v192, s[24:25]
	s_waitcnt vmcnt(8) lgkmcnt(0)
	s_barrier
	v_mfma_f32_16x16x32_bf16 v[142:145], v[146:149], v[216:219], 0
	v_mfma_f32_16x16x32_bf16 v[138:141], v[154:157], v[216:219], 0
	v_mfma_f32_16x16x32_bf16 v[126:129], v[146:149], v[224:227], 0
	v_mfma_f32_16x16x32_bf16 v[122:125], v[154:157], v[224:227], 0
	v_mfma_f32_16x16x32_bf16 v[110:113], v[146:149], v[232:235], 0
	v_mfma_f32_16x16x32_bf16 v[106:109], v[154:157], v[232:235], 0
	v_mfma_f32_16x16x32_bf16 v[94:97], v[146:149], v[240:243], 0
	v_mfma_f32_16x16x32_bf16 v[90:93], v[154:157], v[240:243], 0
	v_mfma_f32_16x16x32_bf16 v[142:145], v[150:153], v[220:223], v[142:145]
	v_mfma_f32_16x16x32_bf16 v[138:141], v[158:161], v[220:223], v[138:141]
	v_mfma_f32_16x16x32_bf16 v[126:129], v[150:153], v[228:231], v[126:129]
	v_mfma_f32_16x16x32_bf16 v[122:125], v[158:161], v[228:231], v[122:125]
	v_mfma_f32_16x16x32_bf16 v[110:113], v[150:153], v[236:239], v[110:113]
	v_mfma_f32_16x16x32_bf16 v[106:109], v[158:161], v[236:239], v[106:109]
	v_mfma_f32_16x16x32_bf16 v[94:97], v[150:153], v[244:247], v[94:97]
	v_mfma_f32_16x16x32_bf16 v[90:93], v[158:161], v[244:247], v[90:93]
	v_mfma_f32_16x16x32_bf16 v[134:137], v[162:165], v[216:219], 0
	v_mfma_f32_16x16x32_bf16 v[130:133], v[170:173], v[216:219], 0
	v_mfma_f32_16x16x32_bf16 v[118:121], v[162:165], v[224:227], 0
	v_mfma_f32_16x16x32_bf16 v[114:117], v[170:173], v[224:227], 0
	v_mfma_f32_16x16x32_bf16 v[102:105], v[162:165], v[232:235], 0
	v_mfma_f32_16x16x32_bf16 v[98:101], v[170:173], v[232:235], 0
	v_mfma_f32_16x16x32_bf16 v[86:89], v[162:165], v[240:243], 0
	v_mfma_f32_16x16x32_bf16 v[82:85], v[170:173], v[240:243], 0
	v_mfma_f32_16x16x32_bf16 v[134:137], v[166:169], v[220:223], v[134:137]
	v_mfma_f32_16x16x32_bf16 v[130:133], v[174:177], v[220:223], v[130:133]
	v_mfma_f32_16x16x32_bf16 v[118:121], v[166:169], v[228:231], v[118:121]
	v_mfma_f32_16x16x32_bf16 v[114:117], v[174:177], v[228:231], v[114:117]
	v_mfma_f32_16x16x32_bf16 v[102:105], v[166:169], v[236:239], v[102:105]
	v_mfma_f32_16x16x32_bf16 v[98:101], v[174:177], v[236:239], v[98:101]
	v_mfma_f32_16x16x32_bf16 v[86:89], v[166:169], v[244:247], v[86:89]
	v_mfma_f32_16x16x32_bf16 v[82:85], v[174:177], v[244:247], v[82:85]
	s_barrier
	s_add_i32 s53, s90, s38
	s_mov_b32 m0, s53
	ds_read_b128 v[216:219], v202 offset:16384
	ds_read_b128 v[220:223], v202 offset:17408
	ds_read_b128 v[224:227], v202 offset:18432
	ds_read_b128 v[228:231], v202 offset:19456
	ds_read_b128 v[232:235], v202 offset:20480
	ds_read_b128 v[236:239], v202 offset:21504
	ds_read_b128 v[240:243], v202 offset:22528
	ds_read_b128 v[244:247], v202 offset:23552
	global_load_lds_dwordx4 v180, s[26:27]
	s_add_i32 m0, s53, 0x2000
	s_add_u32 vcc_lo, s26, 0x40000
	s_addc_u32 vcc_hi, s27, 0
	s_add_i32 s53, s81, s38
	global_load_lds_dwordx4 v184, s[26:27]
	s_mov_b32 m0, s53
	s_nop 0
	global_load_lds_dwordx4 v180, vcc
	s_add_i32 m0, s53, 0x2000
	s_nop 0
	global_load_lds_dwordx4 v184, vcc
	s_mov_b32 m0, s39
	s_nop 0
	global_load_lds_dwordx4 v178, s[28:29]
	s_mov_b32 m0, s60
	s_nop 0
	global_load_lds_dwordx4 v182, s[28:29]
	s_waitcnt vmcnt(8) lgkmcnt(0)
	s_barrier
; #define PG8_STAGE(bufoff, gbase, voff) do { _Pragma("unroll") for (int _i = 0; _i < 2; ++_i) \
;         __builtin_amdgcn_global_load_lds((const unsigned*)((const char*)(gbase) + (voff)[_i]), (PG8_LAS unsigned*)(lds + (bufoff) + ldsw + _i * 8192), 16, 0, 0); } while (0)
; #define PG8_LDA(dst, b, h) do { _Pragma("unroll") for (int m = 0; m < 4; ++m) _Pragma("unroll") for (int k = 0; k < 2; ++k) dst[m][k] = *(const PG8_LAS bf16x8*)(lds + PG8_SA(b, h) + aoff + m * 2048 + k * 1024); } while (0)
; #define PG8_LDB(dst, b, h) do { _Pragma("unroll") for (int n = 0; n < 2; ++n) _Pragma("unroll") for (int k = 0; k < 2; ++k) dst[n][k] = *(const PG8_LAS bf16x8*)(lds + PG8_SB(b, h) + boff + n * 2048 + k * 1024); } while (0)
; #define PG8_MMA(ai, bj, At, Bt) do { __builtin_amdgcn_s_setprio(1); _Pragma("unroll") for (int m = 0; m < 4; ++m) _Pragma("unroll") for (int n = 0; n < 2; ++n) _Pragma("unroll") for (int k = 0; k < 2; ++k) \
;         acc[ai][bj][m][n] = __builtin_amdgcn_mfma_f32_16x16x32_bf16(Bt[n][k], At[m][k], acc[ai][bj][m][n], 0, 0, 0); __builtin_amdgcn_s_setprio(0); } while (0)
; #define PG8_WAIT_V(n) asm volatile("s_waitcnt vmcnt(" #n ")" ::: "memory")
; #define PG8_WAIT_L(n) asm volatile("s_waitcnt lgkmcnt(" #n ")" ::: "memory")
; #define PG8_BAR __builtin_amdgcn_s_barrier()
; #define PG8_SCHED __builtin_amdgcn_sched_barrier(0)
; template <class Epi, class Sched, bool ALIGN_EPI = false, bool SP2 = false>
; __device__ __forceinline__ void gemm_phase(PG8_LAS unsigned char* lds, const Gemm g, const Sched& S, const Epi& E) {
;     ...
;             PG8_WAIT_V(8); PG8_WAIT_L(0); PG8_BAR; PG8_MMA(1, 0, At, B0); PG8_MMA(1, 1, At, B1); PG8_BAR; PG8_SCHED;
;             PG8_LDB(B0, 1, 0); PG8_LDB(B1, 1, 1); PG8_SCHED; PG8_LDA(At, 1, 0); PG8_STAGE(PG8_SA(0, 1), a2 + hstep, voffA);
;             PG8_WAIT_V(8); PG8_WAIT_L(0); PG8_BAR; PG8_MMA(0, 0, At, B0); PG8_MMA(0, 1, At, B1); PG8_BAR; PG8_SCHED;
	v_mfma_f32_16x16x32_bf16 v[78:81], v[146:149], v[216:219], 0
	v_mfma_f32_16x16x32_bf16 v[74:77], v[154:157], v[216:219], 0
	v_mfma_f32_16x16x32_bf16 v[62:65], v[146:149], v[224:227], 0
	v_mfma_f32_16x16x32_bf16 v[58:61], v[154:157], v[224:227], 0
	v_mfma_f32_16x16x32_bf16 v[46:49], v[146:149], v[232:235], 0
	v_mfma_f32_16x16x32_bf16 v[42:45], v[154:157], v[232:235], 0
	v_mfma_f32_16x16x32_bf16 v[30:33], v[146:149], v[240:243], 0
	v_mfma_f32_16x16x32_bf16 v[26:29], v[154:157], v[240:243], 0
	v_mfma_f32_16x16x32_bf16 v[78:81], v[150:153], v[220:223], v[78:81]
	v_mfma_f32_16x16x32_bf16 v[74:77], v[158:161], v[220:223], v[74:77]
	v_mfma_f32_16x16x32_bf16 v[62:65], v[150:153], v[228:231], v[62:65]
	v_mfma_f32_16x16x32_bf16 v[58:61], v[158:161], v[228:231], v[58:61]
	v_mfma_f32_16x16x32_bf16 v[46:49], v[150:153], v[236:239], v[46:49]
	v_mfma_f32_16x16x32_bf16 v[42:45], v[158:161], v[236:239], v[42:45]
	v_mfma_f32_16x16x32_bf16 v[30:33], v[150:153], v[244:247], v[30:33]
	v_mfma_f32_16x16x32_bf16 v[26:29], v[158:161], v[244:247], v[26:29]
	v_mfma_f32_16x16x32_bf16 v[70:73], v[162:165], v[216:219], 0
	v_mfma_f32_16x16x32_bf16 v[66:69], v[170:173], v[216:219], 0
	v_mfma_f32_16x16x32_bf16 v[54:57], v[162:165], v[224:227], 0
	v_mfma_f32_16x16x32_bf16 v[50:53], v[170:173], v[224:227], 0
	v_mfma_f32_16x16x32_bf16 v[38:41], v[162:165], v[232:235], 0
	v_mfma_f32_16x16x32_bf16 v[34:37], v[170:173], v[232:235], 0
	v_mfma_f32_16x16x32_bf16 v[22:25], v[162:165], v[240:243], 0
	v_mfma_f32_16x16x32_bf16 v[18:21], v[170:173], v[240:243], 0
	v_mfma_f32_16x16x32_bf16 v[70:73], v[166:169], v[220:223], v[70:73]
	v_mfma_f32_16x16x32_bf16 v[66:69], v[174:177], v[220:223], v[66:69]
	v_mfma_f32_16x16x32_bf16 v[54:57], v[166:169], v[228:231], v[54:57]
	v_mfma_f32_16x16x32_bf16 v[50:53], v[174:177], v[228:231], v[50:53]
	v_mfma_f32_16x16x32_bf16 v[38:41], v[166:169], v[236:239], v[38:41]
	v_mfma_f32_16x16x32_bf16 v[34:37], v[174:177], v[236:239], v[34:37]
	v_mfma_f32_16x16x32_bf16 v[22:25], v[166:169], v[244:247], v[22:25]
	v_mfma_f32_16x16x32_bf16 v[18:21], v[174:177], v[244:247], v[18:21]
	s_barrier
	v_add_u32_e32 v158, s82, v200
	v_add_u32_e32 v174, s83, v200
	ds_read_b128 v[146:149], v158
	ds_read_b128 v[150:153], v158 offset:1024
	ds_read_b128 v[154:157], v158 offset:2048
	ds_read_b128 v[158:161], v158 offset:3072
	ds_read_b128 v[162:165], v174
	ds_read_b128 v[166:169], v174 offset:1024
	ds_read_b128 v[170:173], v174 offset:2048
	ds_read_b128 v[174:177], v174 offset:3072
	s_add_u32 s28, s28, 0x40000
	s_addc_u32 s29, s29, 0
	s_mov_b32 m0, s61
	ds_read_b128 v[216:219], v202 offset:32768
	ds_read_b128 v[220:223], v202 offset:33792
	ds_read_b128 v[224:227], v202 offset:34816
	ds_read_b128 v[228:231], v202 offset:35840
	ds_read_b128 v[232:235], v202 offset:36864
	ds_read_b128 v[236:239], v202 offset:37888
	ds_read_b128 v[240:243], v202 offset:38912
	ds_read_b128 v[244:247], v202 offset:39936
	global_load_lds_dwordx4 v178, s[28:29]
	s_mov_b32 m0, s62
	s_nop 0
	global_load_lds_dwordx4 v182, s[28:29]
	s_waitcnt vmcnt(8) lgkmcnt(0)
	s_barrier
	v_mfma_f32_16x16x32_bf16 v[142:145], v[146:149], v[216:219], v[142:145]
	v_mfma_f32_16x16x32_bf16 v[138:141], v[154:157], v[216:219], v[138:141]
	v_mfma_f32_16x16x32_bf16 v[126:129], v[146:149], v[224:227], v[126:129]
	v_mfma_f32_16x16x32_bf16 v[122:125], v[154:157], v[224:227], v[122:125]
	v_mfma_f32_16x16x32_bf16 v[110:113], v[146:149], v[232:235], v[110:113]
	v_mfma_f32_16x16x32_bf16 v[106:109], v[154:157], v[232:235], v[106:109]
	v_mfma_f32_16x16x32_bf16 v[94:97], v[146:149], v[240:243], v[94:97]
	v_mfma_f32_16x16x32_bf16 v[90:93], v[154:157], v[240:243], v[90:93]
	v_mfma_f32_16x16x32_bf16 v[142:145], v[150:153], v[220:223], v[142:145]
	v_mfma_f32_16x16x32_bf16 v[138:141], v[158:161], v[220:223], v[138:141]
	v_mfma_f32_16x16x32_bf16 v[126:129], v[150:153], v[228:231], v[126:129]
	v_mfma_f32_16x16x32_bf16 v[122:125], v[158:161], v[228:231], v[122:125]
	v_mfma_f32_16x16x32_bf16 v[110:113], v[150:153], v[236:239], v[110:113]
	v_mfma_f32_16x16x32_bf16 v[106:109], v[158:161], v[236:239], v[106:109]
	v_mfma_f32_16x16x32_bf16 v[94:97], v[150:153], v[244:247], v[94:97]
	v_mfma_f32_16x16x32_bf16 v[90:93], v[158:161], v[244:247], v[90:93]
	v_mfma_f32_16x16x32_bf16 v[134:137], v[162:165], v[216:219], v[134:137]
	v_mfma_f32_16x16x32_bf16 v[130:133], v[170:173], v[216:219], v[130:133]
	v_mfma_f32_16x16x32_bf16 v[118:121], v[162:165], v[224:227], v[118:121]
	v_mfma_f32_16x16x32_bf16 v[114:117], v[170:173], v[224:227], v[114:117]
	v_mfma_f32_16x16x32_bf16 v[102:105], v[162:165], v[232:235], v[102:105]
	v_mfma_f32_16x16x32_bf16 v[98:101], v[170:173], v[232:235], v[98:101]
	v_mfma_f32_16x16x32_bf16 v[86:89], v[162:165], v[240:243], v[86:89]
	v_mfma_f32_16x16x32_bf16 v[82:85], v[170:173], v[240:243], v[82:85]
	v_mfma_f32_16x16x32_bf16 v[134:137], v[166:169], v[220:223], v[134:137]
	v_mfma_f32_16x16x32_bf16 v[130:133], v[174:177], v[220:223], v[130:133]
	v_mfma_f32_16x16x32_bf16 v[118:121], v[166:169], v[228:231], v[118:121]
	v_mfma_f32_16x16x32_bf16 v[114:117], v[174:177], v[228:231], v[114:117]
	v_mfma_f32_16x16x32_bf16 v[102:105], v[166:169], v[236:239], v[102:105]
	v_mfma_f32_16x16x32_bf16 v[98:101], v[174:177], v[236:239], v[98:101]
	v_mfma_f32_16x16x32_bf16 v[86:89], v[166:169], v[244:247], v[86:89]
	v_mfma_f32_16x16x32_bf16 v[82:85], v[174:177], v[244:247], v[82:85]
	s_barrier
; #define PG8_STAGE(bufoff, gbase, voff) do { _Pragma("unroll") for (int _i = 0; _i < 2; ++_i) \
;         __builtin_amdgcn_global_load_lds((const unsigned*)((const char*)(gbase) + (voff)[_i]), (PG8_LAS unsigned*)(lds + (bufoff) + ldsw + _i * 8192), 16, 0, 0); } while (0)
; #define PG8_LDA(dst, b, h) do { _Pragma("unroll") for (int m = 0; m < 4; ++m) _Pragma("unroll") for (int k = 0; k < 2; ++k) dst[m][k] = *(const PG8_LAS bf16x8*)(lds + PG8_SA(b, h) + aoff + m * 2048 + k * 1024); } while (0)
; #define PG8_LDB(dst, b, h) do { _Pragma("unroll") for (int n = 0; n < 2; ++n) _Pragma("unroll") for (int k = 0; k < 2; ++k) dst[n][k] = *(const PG8_LAS bf16x8*)(lds + PG8_SB(b, h) + boff + n * 2048 + k * 1024); } while (0)
; #define PG8_MMA(ai, bj, At, Bt) do { __builtin_amdgcn_s_setprio(1); _Pragma("unroll") for (int m = 0; m < 4; ++m) _Pragma("unroll") for (int n = 0; n < 2; ++n) _Pragma("unroll") for (int k = 0; k < 2; ++k) \
;         acc[ai][bj][m][n] = __builtin_amdgcn_mfma_f32_16x16x32_bf16(Bt[n][k], At[m][k], acc[ai][bj][m][n], 0, 0, 0); __builtin_amdgcn_s_setprio(0); } while (0)
; #define PG8_WAIT_V(n) asm volatile("s_waitcnt vmcnt(" #n ")" ::: "memory")
; template <class Epi, class Sched, bool ALIGN_EPI = false, bool SP2 = false>
; __device__ __forceinline__ void gemm_phase(PG8_LAS unsigned char* lds, const Gemm g, const Sched& S, const Epi& E) {
;     ...
;             PG8_LDB(B0, 0, 0); PG8_LDB(B1, 0, 1); PG8_SCHED; PG8_LDA(At, 0, 0); PG8_STAGE(PG8_SA(1, 1), a1 + hstep, voffA);
;             PG8_WAIT_V(8); PG8_WAIT_L(0); PG8_BAR; PG8_MMA(0, 0, At, B0); PG8_MMA(0, 1, At, B1); PG8_BAR; PG8_SCHED;
;             PG8_LDA(At, 0, 1); PG8_STAGE(PG8_SB(0, 0), b2, voffB); PG8_STAGE(PG8_SB(0, 1), b2 + hstep, voffB); PG8_STAGE(PG8_SA(0, 0), a2, voffA);
;             PG8_WAIT_V(8); PG8_WAIT_L(0); PG8_BAR; PG8_MMA(1, 0, At, B0); PG8_MMA(1, 1, At, B1); PG8_BAR; PG8_SCHED;
;             PG8_LDB(B0, 1, 0); PG8_LDB(B1, 1, 1); PG8_SCHED; PG8_LDA(At, 1, 0); PG8_STAGE(PG8_SA(0, 1), a2 + hstep, voffA);
;             PG8_WAIT_V(8); PG8_WAIT_L(0); PG8_BAR; PG8_MMA(0, 0, At, B0); PG8_MMA(0, 1, At, B1); PG8_BAR; PG8_SCHED;
;             PG8_LDA(At, 1, 1); PG8_STAGE(PG8_SB(1, 0), b3, voffB); PG8_STAGE(PG8_SB(1, 1), b3 + hstep, voffB); PG8_STAGE(PG8_SA(1, 0), a3, voffA);
;             PG8_WAIT_V(8); PG8_WAIT_L(0); PG8_BAR; PG8_MMA(1, 0, At, B0); PG8_MMA(1, 1, At, B1); PG8_BAR; PG8_SCHED;
	s_add_i32 s28, s82, s38
	s_mov_b32 m0, s28
	ds_read_b128 v[216:219], v202 offset:49152
	ds_read_b128 v[220:223], v202 offset:50176
	ds_read_b128 v[224:227], v202 offset:51200
	ds_read_b128 v[228:231], v202 offset:52224
	ds_read_b128 v[232:235], v202 offset:53248
	ds_read_b128 v[236:239], v202 offset:54272
	ds_read_b128 v[240:243], v202 offset:55296
	ds_read_b128 v[244:247], v202 offset:56320
	global_load_lds_dwordx4 v180, s[98:99]
	s_add_i32 m0, s28, 0x2000
	s_add_u32 s26, s26, 0x40080
	s_addc_u32 s27, s27, 0
	s_add_i32 s28, s83, s38
	global_load_lds_dwordx4 v184, s[98:99]
	s_mov_b32 m0, s28
	s_nop 0
	global_load_lds_dwordx4 v180, s[26:27]
	s_add_i32 m0, s28, 0x2000
	s_nop 0
	global_load_lds_dwordx4 v184, s[26:27]
	s_mov_b32 m0, s63
	s_nop 0
	global_load_lds_dwordx4 v178, s[100:101]
	s_mov_b32 m0, s64
	s_nop 0
	global_load_lds_dwordx4 v182, s[100:101]
	s_waitcnt vmcnt(8) lgkmcnt(0)
	s_barrier
	v_mfma_f32_16x16x32_bf16 v[78:81], v[146:149], v[216:219], v[78:81]
	v_mfma_f32_16x16x32_bf16 v[74:77], v[154:157], v[216:219], v[74:77]
	v_mfma_f32_16x16x32_bf16 v[62:65], v[146:149], v[224:227], v[62:65]
	v_mfma_f32_16x16x32_bf16 v[58:61], v[154:157], v[224:227], v[58:61]
	v_mfma_f32_16x16x32_bf16 v[46:49], v[146:149], v[232:235], v[46:49]
	v_mfma_f32_16x16x32_bf16 v[42:45], v[154:157], v[232:235], v[42:45]
	v_mfma_f32_16x16x32_bf16 v[30:33], v[146:149], v[240:243], v[30:33]
	v_mfma_f32_16x16x32_bf16 v[26:29], v[154:157], v[240:243], v[26:29]
	v_mfma_f32_16x16x32_bf16 v[78:81], v[150:153], v[220:223], v[78:81]
	v_mfma_f32_16x16x32_bf16 v[74:77], v[158:161], v[220:223], v[74:77]
	v_mfma_f32_16x16x32_bf16 v[62:65], v[150:153], v[228:231], v[62:65]
	v_mfma_f32_16x16x32_bf16 v[58:61], v[158:161], v[228:231], v[58:61]
	v_mfma_f32_16x16x32_bf16 v[46:49], v[150:153], v[236:239], v[46:49]
	v_mfma_f32_16x16x32_bf16 v[42:45], v[158:161], v[236:239], v[42:45]
	v_mfma_f32_16x16x32_bf16 v[30:33], v[150:153], v[244:247], v[30:33]
	v_mfma_f32_16x16x32_bf16 v[26:29], v[158:161], v[244:247], v[26:29]
	v_mfma_f32_16x16x32_bf16 v[70:73], v[162:165], v[216:219], v[70:73]
	v_mfma_f32_16x16x32_bf16 v[66:69], v[170:173], v[216:219], v[66:69]
	v_mfma_f32_16x16x32_bf16 v[54:57], v[162:165], v[224:227], v[54:57]
	v_mfma_f32_16x16x32_bf16 v[50:53], v[170:173], v[224:227], v[50:53]
	v_mfma_f32_16x16x32_bf16 v[38:41], v[162:165], v[232:235], v[38:41]
	v_mfma_f32_16x16x32_bf16 v[34:37], v[170:173], v[232:235], v[34:37]
	v_mfma_f32_16x16x32_bf16 v[22:25], v[162:165], v[240:243], v[22:25]
	v_mfma_f32_16x16x32_bf16 v[18:21], v[170:173], v[240:243], v[18:21]
	v_mfma_f32_16x16x32_bf16 v[70:73], v[166:169], v[220:223], v[70:73]
	v_mfma_f32_16x16x32_bf16 v[66:69], v[174:177], v[220:223], v[66:69]
	v_mfma_f32_16x16x32_bf16 v[54:57], v[166:169], v[228:231], v[54:57]
	v_mfma_f32_16x16x32_bf16 v[50:53], v[174:177], v[228:231], v[50:53]
	v_mfma_f32_16x16x32_bf16 v[38:41], v[166:169], v[236:239], v[38:41]
	v_mfma_f32_16x16x32_bf16 v[34:37], v[174:177], v[236:239], v[34:37]
	v_mfma_f32_16x16x32_bf16 v[22:25], v[166:169], v[244:247], v[22:25]
	v_mfma_f32_16x16x32_bf16 v[18:21], v[174:177], v[244:247], v[18:21]
	s_barrier
	s_add_i32 s52, s52, 2
	s_add_u32 s24, s24, 0x100
	s_addc_u32 s25, s25, 0
	s_add_u32 s44, s44, 0x100
	s_addc_u32 s45, s45, 0
.LBB0_319:
	v_add_u32_e32 v158, s90, v200
	v_add_u32_e32 v174, s81, v200
	ds_read_b128 v[146:149], v158
	ds_read_b128 v[150:153], v158 offset:1024
	ds_read_b128 v[154:157], v158 offset:2048
	ds_read_b128 v[158:161], v158 offset:3072
	ds_read_b128 v[162:165], v174
	ds_read_b128 v[166:169], v174 offset:1024
	ds_read_b128 v[170:173], v174 offset:2048
	ds_read_b128 v[174:177], v174 offset:3072
	s_add_u32 s26, s24, 0xfffc0080
	s_addc_u32 s27, s25, -1
	s_cmp_eq_u32 s52, 12
	s_cselect_b32 s29, s13, s27
	s_cselect_b32 s28, s17, s26
	s_cselect_b32 s27, s19, s45
	s_cselect_b32 s26, s42, s44
	s_add_u32 s98, s26, s46
	s_addc_u32 s99, s27, s47
	s_add_u32 s100, s28, s46
	s_addc_u32 s101, s29, s47
	s_add_i32 m0, s39, 0xc000
	ds_read_b128 v[216:219], v202
	ds_read_b128 v[220:223], v202 offset:1024
	ds_read_b128 v[224:227], v202 offset:2048
	ds_read_b128 v[228:231], v202 offset:3072
	ds_read_b128 v[232:235], v202 offset:4096
	ds_read_b128 v[236:239], v202 offset:5120
	ds_read_b128 v[240:243], v202 offset:6144
	ds_read_b128 v[244:247], v202 offset:7168
	global_load_lds_dwordx4 v190, s[24:25]
	s_add_i32 m0, s39, 0xe000
	s_nop 0
	global_load_lds_dwordx4 v192, s[24:25]
	s_waitcnt vmcnt(8) lgkmcnt(0)
	s_barrier
	v_mfma_f32_16x16x32_bf16 v[142:145], v[146:149], v[216:219], v[142:145]
	v_mfma_f32_16x16x32_bf16 v[138:141], v[154:157], v[216:219], v[138:141]
	v_mfma_f32_16x16x32_bf16 v[126:129], v[146:149], v[224:227], v[126:129]
	v_mfma_f32_16x16x32_bf16 v[122:125], v[154:157], v[224:227], v[122:125]
	v_mfma_f32_16x16x32_bf16 v[110:113], v[146:149], v[232:235], v[110:113]
	v_mfma_f32_16x16x32_bf16 v[106:109], v[154:157], v[232:235], v[106:109]
	v_mfma_f32_16x16x32_bf16 v[94:97], v[146:149], v[240:243], v[94:97]
	v_mfma_f32_16x16x32_bf16 v[90:93], v[154:157], v[240:243], v[90:93]
	v_mfma_f32_16x16x32_bf16 v[142:145], v[150:153], v[220:223], v[142:145]
	v_mfma_f32_16x16x32_bf16 v[138:141], v[158:161], v[220:223], v[138:141]
	v_mfma_f32_16x16x32_bf16 v[126:129], v[150:153], v[228:231], v[126:129]
	v_mfma_f32_16x16x32_bf16 v[122:125], v[158:161], v[228:231], v[122:125]
	v_mfma_f32_16x16x32_bf16 v[110:113], v[150:153], v[236:239], v[110:113]
	v_mfma_f32_16x16x32_bf16 v[106:109], v[158:161], v[236:239], v[106:109]
	v_mfma_f32_16x16x32_bf16 v[94:97], v[150:153], v[244:247], v[94:97]
	v_mfma_f32_16x16x32_bf16 v[90:93], v[158:161], v[244:247], v[90:93]
	v_mfma_f32_16x16x32_bf16 v[134:137], v[162:165], v[216:219], v[134:137]
	v_mfma_f32_16x16x32_bf16 v[130:133], v[170:173], v[216:219], v[130:133]
	v_mfma_f32_16x16x32_bf16 v[118:121], v[162:165], v[224:227], v[118:121]
	v_mfma_f32_16x16x32_bf16 v[114:117], v[170:173], v[224:227], v[114:117]
	v_mfma_f32_16x16x32_bf16 v[102:105], v[162:165], v[232:235], v[102:105]
	v_mfma_f32_16x16x32_bf16 v[98:101], v[170:173], v[232:235], v[98:101]
	v_mfma_f32_16x16x32_bf16 v[86:89], v[162:165], v[240:243], v[86:89]
	v_mfma_f32_16x16x32_bf16 v[82:85], v[170:173], v[240:243], v[82:85]
	v_mfma_f32_16x16x32_bf16 v[134:137], v[166:169], v[220:223], v[134:137]
	v_mfma_f32_16x16x32_bf16 v[130:133], v[174:177], v[220:223], v[130:133]
	v_mfma_f32_16x16x32_bf16 v[118:121], v[166:169], v[228:231], v[118:121]
	v_mfma_f32_16x16x32_bf16 v[114:117], v[174:177], v[228:231], v[114:117]
	v_mfma_f32_16x16x32_bf16 v[102:105], v[166:169], v[236:239], v[102:105]
	v_mfma_f32_16x16x32_bf16 v[98:101], v[174:177], v[236:239], v[98:101]
	v_mfma_f32_16x16x32_bf16 v[86:89], v[166:169], v[244:247], v[86:89]
	v_mfma_f32_16x16x32_bf16 v[82:85], v[174:177], v[244:247], v[82:85]
	s_barrier
; #define PG8_STAGE(bufoff, gbase, voff) do { _Pragma("unroll") for (int _i = 0; _i < 2; ++_i) \
;         __builtin_amdgcn_global_load_lds((const unsigned*)((const char*)(gbase) + (voff)[_i]), (PG8_LAS unsigned*)(lds + (bufoff) + ldsw + _i * 8192), 16, 0, 0); } while (0)
; #define PG8_LDA(dst, b, h) do { _Pragma("unroll") for (int m = 0; m < 4; ++m) _Pragma("unroll") for (int k = 0; k < 2; ++k) dst[m][k] = *(const PG8_LAS bf16x8*)(lds + PG8_SA(b, h) + aoff + m * 2048 + k * 1024); } while (0)
; #define PG8_LDB(dst, b, h) do { _Pragma("unroll") for (int n = 0; n < 2; ++n) _Pragma("unroll") for (int k = 0; k < 2; ++k) dst[n][k] = *(const PG8_LAS bf16x8*)(lds + PG8_SB(b, h) + boff + n * 2048 + k * 1024); } while (0)
; #define PG8_MMA(ai, bj, At, Bt) do { __builtin_amdgcn_s_setprio(1); _Pragma("unroll") for (int m = 0; m < 4; ++m) _Pragma("unroll") for (int n = 0; n < 2; ++n) _Pragma("unroll") for (int k = 0; k < 2; ++k) \
;         acc[ai][bj][m][n] = __builtin_amdgcn_mfma_f32_16x16x32_bf16(Bt[n][k], At[m][k], acc[ai][bj][m][n], 0, 0, 0); __builtin_amdgcn_s_setprio(0); } while (0)
; #define PG8_WAIT_V(n) asm volatile("s_waitcnt vmcnt(" #n ")" ::: "memory")
; #define PG8_WAIT_L(n) asm volatile("s_waitcnt lgkmcnt(" #n ")" ::: "memory")
; #define PG8_BAR __builtin_amdgcn_s_barrier()
; #define PG8_SCHED __builtin_amdgcn_sched_barrier(0)
; template <class Epi, class Sched, bool ALIGN_EPI = false, bool SP2 = false>
; __device__ __forceinline__ void gemm_phase(PG8_LAS unsigned char* lds, const Gemm g, const Sched& S, const Epi& E) {
;     ...
;             PG8_LDA(At, 0, 1); PG8_STAGE(PG8_SB(0, 0), b2, voffB); PG8_STAGE(PG8_SB(0, 1), b2 + hstep, voffB); PG8_STAGE(PG8_SA(0, 0), a2, voffA);
;             PG8_WAIT_V(8); PG8_WAIT_L(0); PG8_BAR; PG8_MMA(1, 0, At, B0); PG8_MMA(1, 1, At, B1); PG8_BAR; PG8_SCHED;
;             PG8_LDB(B0, 1, 0); PG8_LDB(B1, 1, 1); PG8_SCHED; PG8_LDA(At, 1, 0); PG8_STAGE(PG8_SA(0, 1), a2 + hstep, voffA);
	s_add_i32 s53, s90, s38
	s_mov_b32 m0, s53
	ds_read_b128 v[216:219], v202 offset:16384
	ds_read_b128 v[220:223], v202 offset:17408
	ds_read_b128 v[224:227], v202 offset:18432
	ds_read_b128 v[228:231], v202 offset:19456
	ds_read_b128 v[232:235], v202 offset:20480
	ds_read_b128 v[236:239], v202 offset:21504
	ds_read_b128 v[240:243], v202 offset:22528
	ds_read_b128 v[244:247], v202 offset:23552
	global_load_lds_dwordx4 v180, s[26:27]
	s_add_i32 m0, s53, 0x2000
	s_add_u32 vcc_lo, s26, 0x40000
	s_addc_u32 vcc_hi, s27, 0
	s_add_i32 s53, s81, s38
	global_load_lds_dwordx4 v184, s[26:27]
	s_mov_b32 m0, s53
	s_nop 0
	global_load_lds_dwordx4 v180, vcc
	s_add_i32 m0, s53, 0x2000
	s_nop 0
	global_load_lds_dwordx4 v184, vcc
	s_mov_b32 m0, s39
	s_nop 0
	global_load_lds_dwordx4 v178, s[28:29]
	s_mov_b32 m0, s60
	s_nop 0
	global_load_lds_dwordx4 v182, s[28:29]
	s_waitcnt vmcnt(8) lgkmcnt(0)
	s_barrier
	v_mfma_f32_16x16x32_bf16 v[78:81], v[146:149], v[216:219], v[78:81]
	v_mfma_f32_16x16x32_bf16 v[74:77], v[154:157], v[216:219], v[74:77]
	v_mfma_f32_16x16x32_bf16 v[62:65], v[146:149], v[224:227], v[62:65]
	v_mfma_f32_16x16x32_bf16 v[58:61], v[154:157], v[224:227], v[58:61]
	v_mfma_f32_16x16x32_bf16 v[46:49], v[146:149], v[232:235], v[46:49]
	v_mfma_f32_16x16x32_bf16 v[42:45], v[154:157], v[232:235], v[42:45]
	v_mfma_f32_16x16x32_bf16 v[30:33], v[146:149], v[240:243], v[30:33]
	v_mfma_f32_16x16x32_bf16 v[26:29], v[154:157], v[240:243], v[26:29]
	v_mfma_f32_16x16x32_bf16 v[78:81], v[150:153], v[220:223], v[78:81]
	v_mfma_f32_16x16x32_bf16 v[74:77], v[158:161], v[220:223], v[74:77]
	v_mfma_f32_16x16x32_bf16 v[62:65], v[150:153], v[228:231], v[62:65]
	v_mfma_f32_16x16x32_bf16 v[58:61], v[158:161], v[228:231], v[58:61]
	v_mfma_f32_16x16x32_bf16 v[46:49], v[150:153], v[236:239], v[46:49]
	v_mfma_f32_16x16x32_bf16 v[42:45], v[158:161], v[236:239], v[42:45]
	v_mfma_f32_16x16x32_bf16 v[30:33], v[150:153], v[244:247], v[30:33]
	v_mfma_f32_16x16x32_bf16 v[26:29], v[158:161], v[244:247], v[26:29]
	v_mfma_f32_16x16x32_bf16 v[70:73], v[162:165], v[216:219], v[70:73]
	v_mfma_f32_16x16x32_bf16 v[66:69], v[170:173], v[216:219], v[66:69]
	v_mfma_f32_16x16x32_bf16 v[54:57], v[162:165], v[224:227], v[54:57]
	v_mfma_f32_16x16x32_bf16 v[50:53], v[170:173], v[224:227], v[50:53]
	v_mfma_f32_16x16x32_bf16 v[38:41], v[162:165], v[232:235], v[38:41]
	v_mfma_f32_16x16x32_bf16 v[34:37], v[170:173], v[232:235], v[34:37]
	v_mfma_f32_16x16x32_bf16 v[22:25], v[162:165], v[240:243], v[22:25]
	v_mfma_f32_16x16x32_bf16 v[18:21], v[170:173], v[240:243], v[18:21]
	v_mfma_f32_16x16x32_bf16 v[70:73], v[166:169], v[220:223], v[70:73]
	v_mfma_f32_16x16x32_bf16 v[66:69], v[174:177], v[220:223], v[66:69]
	v_mfma_f32_16x16x32_bf16 v[54:57], v[166:169], v[228:231], v[54:57]
	v_mfma_f32_16x16x32_bf16 v[50:53], v[174:177], v[228:231], v[50:53]
	v_mfma_f32_16x16x32_bf16 v[38:41], v[166:169], v[236:239], v[38:41]
	v_mfma_f32_16x16x32_bf16 v[34:37], v[174:177], v[236:239], v[34:37]
	v_mfma_f32_16x16x32_bf16 v[22:25], v[166:169], v[244:247], v[22:25]
	v_mfma_f32_16x16x32_bf16 v[18:21], v[174:177], v[244:247], v[18:21]
	s_barrier
	v_add_u32_e32 v158, s82, v200
	v_add_u32_e32 v174, s83, v200
	ds_read_b128 v[146:149], v158
	ds_read_b128 v[150:153], v158 offset:1024
	ds_read_b128 v[154:157], v158 offset:2048
	ds_read_b128 v[158:161], v158 offset:3072
	ds_read_b128 v[162:165], v174
	ds_read_b128 v[166:169], v174 offset:1024
	ds_read_b128 v[170:173], v174 offset:2048
	ds_read_b128 v[174:177], v174 offset:3072
	s_add_u32 s28, s28, 0x40000
	s_addc_u32 s29, s29, 0
	s_mov_b32 m0, s61
	ds_read_b128 v[216:219], v202 offset:32768
	ds_read_b128 v[220:223], v202 offset:33792
	ds_read_b128 v[224:227], v202 offset:34816
	ds_read_b128 v[228:231], v202 offset:35840
	ds_read_b128 v[232:235], v202 offset:36864
	ds_read_b128 v[236:239], v202 offset:37888
	ds_read_b128 v[240:243], v202 offset:38912
	ds_read_b128 v[244:247], v202 offset:39936
	global_load_lds_dwordx4 v178, s[28:29]
	s_mov_b32 m0, s62
	s_nop 0
	global_load_lds_dwordx4 v182, s[28:29]
	s_waitcnt vmcnt(8) lgkmcnt(0)
	s_barrier
; #define PG8_STAGE(bufoff, gbase, voff) do { _Pragma("unroll") for (int _i = 0; _i < 2; ++_i) \
;         __builtin_amdgcn_global_load_lds((const unsigned*)((const char*)(gbase) + (voff)[_i]), (PG8_LAS unsigned*)(lds + (bufoff) + ldsw + _i * 8192), 16, 0, 0); } while (0)
; #define PG8_LDA(dst, b, h) do { _Pragma("unroll") for (int m = 0; m < 4; ++m) _Pragma("unroll") for (int k = 0; k < 2; ++k) dst[m][k] = *(const PG8_LAS bf16x8*)(lds + PG8_SA(b, h) + aoff + m * 2048 + k * 1024); } while (0)
; #define PG8_LDB(dst, b, h) do { _Pragma("unroll") for (int n = 0; n < 2; ++n) _Pragma("unroll") for (int k = 0; k < 2; ++k) dst[n][k] = *(const PG8_LAS bf16x8*)(lds + PG8_SB(b, h) + boff + n * 2048 + k * 1024); } while (0)
; #define PG8_MMA(ai, bj, At, Bt) do { __builtin_amdgcn_s_setprio(1); _Pragma("unroll") for (int m = 0; m < 4; ++m) _Pragma("unroll") for (int n = 0; n < 2; ++n) _Pragma("unroll") for (int k = 0; k < 2; ++k) \
;         acc[ai][bj][m][n] = __builtin_amdgcn_mfma_f32_16x16x32_bf16(Bt[n][k], At[m][k], acc[ai][bj][m][n], 0, 0, 0); __builtin_amdgcn_s_setprio(0); } while (0)
; template <class Epi, class Sched, bool ALIGN_EPI = false, bool SP2 = false>
; __device__ __forceinline__ void gemm_phase(PG8_LAS unsigned char* lds, const Gemm g, const Sched& S, const Epi& E) {
;     ...
;             PG8_LDB(B0, 0, 0); PG8_LDB(B1, 0, 1); PG8_SCHED; PG8_LDA(At, 0, 0); PG8_STAGE(PG8_SA(1, 1), a1 + hstep, voffA);
;             PG8_WAIT_V(8); PG8_WAIT_L(0); PG8_BAR; PG8_MMA(0, 0, At, B0); PG8_MMA(0, 1, At, B1); PG8_BAR; PG8_SCHED;
;             PG8_LDA(At, 0, 1); PG8_STAGE(PG8_SB(0, 0), b2, voffB); PG8_STAGE(PG8_SB(0, 1), b2 + hstep, voffB); PG8_STAGE(PG8_SA(0, 0), a2, voffA);
;             PG8_WAIT_V(8); PG8_WAIT_L(0); PG8_BAR; PG8_MMA(1, 0, At, B0); PG8_MMA(1, 1, At, B1); PG8_BAR; PG8_SCHED;
;             PG8_LDB(B0, 1, 0); PG8_LDB(B1, 1, 1); PG8_SCHED; PG8_LDA(At, 1, 0); PG8_STAGE(PG8_SA(0, 1), a2 + hstep, voffA);
;             PG8_WAIT_V(8); PG8_WAIT_L(0); PG8_BAR; PG8_MMA(0, 0, At, B0); PG8_MMA(0, 1, At, B1); PG8_BAR; PG8_SCHED;
;             PG8_LDA(At, 1, 1); PG8_STAGE(PG8_SB(1, 0), b3, voffB); PG8_STAGE(PG8_SB(1, 1), b3 + hstep, voffB); PG8_STAGE(PG8_SA(1, 0), a3, voffA);
;             PG8_WAIT_V(8); PG8_WAIT_L(0); PG8_BAR; PG8_MMA(1, 0, At, B0); PG8_MMA(1, 1, At, B1); PG8_BAR; PG8_SCHED;
;     ...
;         if constexpr (ALIGN_EPI) { if (wr == 0) PG8_BAR; }
	v_mfma_f32_16x16x32_bf16 v[142:145], v[146:149], v[216:219], v[142:145]
	v_mfma_f32_16x16x32_bf16 v[138:141], v[154:157], v[216:219], v[138:141]
	v_mfma_f32_16x16x32_bf16 v[126:129], v[146:149], v[224:227], v[126:129]
	v_mfma_f32_16x16x32_bf16 v[122:125], v[154:157], v[224:227], v[122:125]
	v_mfma_f32_16x16x32_bf16 v[110:113], v[146:149], v[232:235], v[110:113]
	v_mfma_f32_16x16x32_bf16 v[106:109], v[154:157], v[232:235], v[106:109]
	v_mfma_f32_16x16x32_bf16 v[94:97], v[146:149], v[240:243], v[94:97]
	v_mfma_f32_16x16x32_bf16 v[90:93], v[154:157], v[240:243], v[90:93]
	v_mfma_f32_16x16x32_bf16 v[142:145], v[150:153], v[220:223], v[142:145]
	v_mfma_f32_16x16x32_bf16 v[138:141], v[158:161], v[220:223], v[138:141]
	v_mfma_f32_16x16x32_bf16 v[126:129], v[150:153], v[228:231], v[126:129]
	v_mfma_f32_16x16x32_bf16 v[122:125], v[158:161], v[228:231], v[122:125]
	v_mfma_f32_16x16x32_bf16 v[110:113], v[150:153], v[236:239], v[110:113]
	v_mfma_f32_16x16x32_bf16 v[106:109], v[158:161], v[236:239], v[106:109]
	v_mfma_f32_16x16x32_bf16 v[94:97], v[150:153], v[244:247], v[94:97]
	v_mfma_f32_16x16x32_bf16 v[90:93], v[158:161], v[244:247], v[90:93]
	v_mfma_f32_16x16x32_bf16 v[134:137], v[162:165], v[216:219], v[134:137]
	v_mfma_f32_16x16x32_bf16 v[130:133], v[170:173], v[216:219], v[130:133]
	v_mfma_f32_16x16x32_bf16 v[118:121], v[162:165], v[224:227], v[118:121]
	v_mfma_f32_16x16x32_bf16 v[114:117], v[170:173], v[224:227], v[114:117]
	v_mfma_f32_16x16x32_bf16 v[102:105], v[162:165], v[232:235], v[102:105]
	v_mfma_f32_16x16x32_bf16 v[98:101], v[170:173], v[232:235], v[98:101]
	v_mfma_f32_16x16x32_bf16 v[86:89], v[162:165], v[240:243], v[86:89]
	v_mfma_f32_16x16x32_bf16 v[82:85], v[170:173], v[240:243], v[82:85]
	v_mfma_f32_16x16x32_bf16 v[134:137], v[166:169], v[220:223], v[134:137]
	v_mfma_f32_16x16x32_bf16 v[130:133], v[174:177], v[220:223], v[130:133]
	v_mfma_f32_16x16x32_bf16 v[118:121], v[166:169], v[228:231], v[118:121]
	v_mfma_f32_16x16x32_bf16 v[114:117], v[174:177], v[228:231], v[114:117]
	v_mfma_f32_16x16x32_bf16 v[102:105], v[166:169], v[236:239], v[102:105]
	v_mfma_f32_16x16x32_bf16 v[98:101], v[174:177], v[236:239], v[98:101]
	v_mfma_f32_16x16x32_bf16 v[86:89], v[166:169], v[244:247], v[86:89]
	v_mfma_f32_16x16x32_bf16 v[82:85], v[174:177], v[244:247], v[82:85]
	s_barrier
	s_add_i32 s28, s82, s38
	s_mov_b32 m0, s28
	ds_read_b128 v[216:219], v202 offset:49152
	ds_read_b128 v[220:223], v202 offset:50176
	ds_read_b128 v[224:227], v202 offset:51200
	ds_read_b128 v[228:231], v202 offset:52224
	ds_read_b128 v[232:235], v202 offset:53248
	ds_read_b128 v[236:239], v202 offset:54272
	ds_read_b128 v[240:243], v202 offset:55296
	ds_read_b128 v[244:247], v202 offset:56320
	global_load_lds_dwordx4 v180, s[98:99]
	s_add_i32 m0, s28, 0x2000
	s_add_u32 s26, s26, 0x40080
	s_addc_u32 s27, s27, 0
	s_add_i32 s28, s83, s38
	global_load_lds_dwordx4 v184, s[98:99]
	s_mov_b32 m0, s28
	s_nop 0
	global_load_lds_dwordx4 v180, s[26:27]
	s_add_i32 m0, s28, 0x2000
	s_nop 0
	global_load_lds_dwordx4 v184, s[26:27]
	s_mov_b32 m0, s63
	s_nop 0
	global_load_lds_dwordx4 v178, s[100:101]
	s_mov_b32 m0, s64
	s_nop 0
	global_load_lds_dwordx4 v182, s[100:101]
	s_waitcnt vmcnt(8) lgkmcnt(0)
	s_barrier
	v_mfma_f32_16x16x32_bf16 v[78:81], v[146:149], v[216:219], v[78:81]
	v_mfma_f32_16x16x32_bf16 v[74:77], v[154:157], v[216:219], v[74:77]
	v_mfma_f32_16x16x32_bf16 v[62:65], v[146:149], v[224:227], v[62:65]
	v_mfma_f32_16x16x32_bf16 v[58:61], v[154:157], v[224:227], v[58:61]
	v_mfma_f32_16x16x32_bf16 v[46:49], v[146:149], v[232:235], v[46:49]
	v_mfma_f32_16x16x32_bf16 v[42:45], v[154:157], v[232:235], v[42:45]
	v_mfma_f32_16x16x32_bf16 v[30:33], v[146:149], v[240:243], v[30:33]
	v_mfma_f32_16x16x32_bf16 v[26:29], v[154:157], v[240:243], v[26:29]
	v_mfma_f32_16x16x32_bf16 v[78:81], v[150:153], v[220:223], v[78:81]
	v_mfma_f32_16x16x32_bf16 v[74:77], v[158:161], v[220:223], v[74:77]
	v_mfma_f32_16x16x32_bf16 v[62:65], v[150:153], v[228:231], v[62:65]
	v_mfma_f32_16x16x32_bf16 v[58:61], v[158:161], v[228:231], v[58:61]
	v_mfma_f32_16x16x32_bf16 v[46:49], v[150:153], v[236:239], v[46:49]
	v_mfma_f32_16x16x32_bf16 v[42:45], v[158:161], v[236:239], v[42:45]
	v_mfma_f32_16x16x32_bf16 v[30:33], v[150:153], v[244:247], v[30:33]
	v_mfma_f32_16x16x32_bf16 v[26:29], v[158:161], v[244:247], v[26:29]
	v_mfma_f32_16x16x32_bf16 v[70:73], v[162:165], v[216:219], v[70:73]
	v_mfma_f32_16x16x32_bf16 v[66:69], v[170:173], v[216:219], v[66:69]
	v_mfma_f32_16x16x32_bf16 v[54:57], v[162:165], v[224:227], v[54:57]
	v_mfma_f32_16x16x32_bf16 v[50:53], v[170:173], v[224:227], v[50:53]
	v_mfma_f32_16x16x32_bf16 v[38:41], v[162:165], v[232:235], v[38:41]
	v_mfma_f32_16x16x32_bf16 v[34:37], v[170:173], v[232:235], v[34:37]
	v_mfma_f32_16x16x32_bf16 v[22:25], v[162:165], v[240:243], v[22:25]
	v_mfma_f32_16x16x32_bf16 v[18:21], v[170:173], v[240:243], v[18:21]
	v_mfma_f32_16x16x32_bf16 v[70:73], v[166:169], v[220:223], v[70:73]
	v_mfma_f32_16x16x32_bf16 v[66:69], v[174:177], v[220:223], v[66:69]
	v_mfma_f32_16x16x32_bf16 v[54:57], v[166:169], v[228:231], v[54:57]
	v_mfma_f32_16x16x32_bf16 v[50:53], v[174:177], v[228:231], v[50:53]
	v_mfma_f32_16x16x32_bf16 v[38:41], v[166:169], v[236:239], v[38:41]
	v_mfma_f32_16x16x32_bf16 v[34:37], v[174:177], v[236:239], v[34:37]
	v_mfma_f32_16x16x32_bf16 v[22:25], v[166:169], v[244:247], v[22:25]
	v_mfma_f32_16x16x32_bf16 v[18:21], v[174:177], v[244:247], v[18:21]
	s_barrier
	s_add_i32 s52, s52, 2
	s_add_u32 s24, s24, 0x100
	s_addc_u32 s25, s25, 0
	s_add_u32 s44, s44, 0x100
	s_addc_u32 s45, s45, 0
	s_cmp_gt_u32 s52, 13
	s_cbranch_scc0 .LBB0_319
	s_setprio 0
	s_and_b64 vcc, exec, s[10:11]
	s_cbranch_vccz .LBB0_322
	s_barrier

; #define PG8_STAGE(bufoff, gbase, voff) do { _Pragma("unroll") for (int _i = 0; _i < 2; ++_i) \
;         __builtin_amdgcn_global_load_lds((const unsigned*)((const char*)(gbase) + (voff)[_i]), (PG8_LAS unsigned*)(lds + (bufoff) + ldsw + _i * 8192), 16, 0, 0); } while (0)
; #define PG8_LDA(dst, b, h) do { _Pragma("unroll") for (int m = 0; m < 4; ++m) _Pragma("unroll") for (int k = 0; k < 2; ++k) dst[m][k] = *(const PG8_LAS bf16x8*)(lds + PG8_SA(b, h) + aoff + m * 2048 + k * 1024); } while (0)
; #define PG8_LDB(dst, b, h) do { _Pragma("unroll") for (int n = 0; n < 2; ++n) _Pragma("unroll") for (int k = 0; k < 2; ++k) dst[n][k] = *(const PG8_LAS bf16x8*)(lds + PG8_SB(b, h) + boff + n * 2048 + k * 1024); } while (0)
; #define PG8_MMA(ai, bj, At, Bt) do { __builtin_amdgcn_s_setprio(1); _Pragma("unroll") for (int m = 0; m < 4; ++m) _Pragma("unroll") for (int n = 0; n < 2; ++n) _Pragma("unroll") for (int k = 0; k < 2; ++k) \
;         acc[ai][bj][m][n] = __builtin_amdgcn_mfma_f32_16x16x32_bf16(Bt[n][k], At[m][k], acc[ai][bj][m][n], 0, 0, 0); __builtin_amdgcn_s_setprio(0); } while (0)
; #define PG8_WAIT_V(n) asm volatile("s_waitcnt vmcnt(" #n ")" ::: "memory")
; #define PG8_WAIT_L(n) asm volatile("s_waitcnt lgkmcnt(" #n ")" ::: "memory")
; #define PG8_BAR __builtin_amdgcn_s_barrier()
; #define PG8_SCHED __builtin_amdgcn_sched_barrier(0)
; template <class Epi, class Sched, bool ALIGN_EPI = false, bool SP2 = false>
; __device__ __forceinline__ void gemm_phase(PG8_LAS unsigned char* lds, const Gemm g, const Sched& S, const Epi& E) {
;     ...
;             PG8_LDB(B0, 0, 0); PG8_LDB(B1, 0, 1); PG8_SCHED; PG8_LDA(At, 0, 0); PG8_STAGE(PG8_SA(1, 1), a1 + hstep, voffA);
;             PG8_WAIT_V(8); PG8_WAIT_L(0); PG8_BAR; PG8_MMA(0, 0, At, B0); PG8_MMA(0, 1, At, B1); PG8_BAR; PG8_SCHED;
;             PG8_LDA(At, 0, 1); PG8_STAGE(PG8_SB(0, 0), b2, voffB); PG8_STAGE(PG8_SB(0, 1), b2 + hstep, voffB); PG8_STAGE(PG8_SA(0, 0), a2, voffA);
;             PG8_WAIT_V(8); PG8_WAIT_L(0); PG8_BAR; PG8_MMA(1, 0, At, B0); PG8_MMA(1, 1, At, B1); PG8_BAR; PG8_SCHED;
.Lprio_skip_3:
	v_add_u32_e32 v158, s90, v160
	ds_read_b128 v[164:167], v158
	ds_read_b128 v[168:171], v158 offset:1024
	ds_read_b128 v[172:175], v158 offset:2048
	ds_read_b128 v[176:179], v158 offset:3072
	v_add_u32_e32 v158, s81, v160
	ds_read_b128 v[180:183], v158
	ds_read_b128 v[184:187], v158 offset:1024
	ds_read_b128 v[188:191], v158 offset:2048
	ds_read_b128 v[192:195], v158 offset:3072
	s_add_u32 s22, s20, 0xfffc0080
	s_addc_u32 s23, s21, -1
	s_cmp_eq_u32 s64, 12
	s_cselect_b32 s25, s13, s23
	s_cselect_b32 s24, s52, s22
	s_cselect_b32 s23, s15, s63
	s_cselect_b32 s22, s53, s62
	s_add_u32 s98, s22, s46
	s_addc_u32 s99, s23, s47
	s_add_u32 s100, s24, s46
	s_addc_u32 s101, s25, s47
	s_add_i32 m0, s35, 0xc000
	ds_read_b128 v[196:199], v163
	ds_read_b128 v[200:203], v163 offset:1024
	ds_read_b128 v[216:219], v163 offset:2048
	ds_read_b128 v[220:223], v163 offset:3072
	ds_read_b128 v[224:227], v163 offset:4096
	ds_read_b128 v[228:231], v163 offset:5120
	ds_read_b128 v[232:235], v163 offset:6144
	ds_read_b128 v[236:239], v163 offset:7168
	global_load_lds_dwordx4 v154, s[20:21]
	s_add_i32 m0, s35, 0xe000
	s_nop 0
	global_load_lds_dwordx4 v156, s[20:21]
	s_waitcnt vmcnt(8) lgkmcnt(0)
	s_barrier
	v_mfma_f32_16x16x32_bf16 v[142:145], v[164:167], v[196:199], 0
	v_mfma_f32_16x16x32_bf16 v[138:141], v[172:175], v[196:199], 0
	v_mfma_f32_16x16x32_bf16 v[126:129], v[164:167], v[216:219], 0
	v_mfma_f32_16x16x32_bf16 v[122:125], v[172:175], v[216:219], 0
	v_mfma_f32_16x16x32_bf16 v[110:113], v[164:167], v[224:227], 0
	v_mfma_f32_16x16x32_bf16 v[106:109], v[172:175], v[224:227], 0
	v_mfma_f32_16x16x32_bf16 v[94:97], v[164:167], v[232:235], 0
	v_mfma_f32_16x16x32_bf16 v[90:93], v[172:175], v[232:235], 0
	v_mfma_f32_16x16x32_bf16 v[142:145], v[168:171], v[200:203], v[142:145]
	v_mfma_f32_16x16x32_bf16 v[138:141], v[176:179], v[200:203], v[138:141]
	v_mfma_f32_16x16x32_bf16 v[126:129], v[168:171], v[220:223], v[126:129]
	v_mfma_f32_16x16x32_bf16 v[122:125], v[176:179], v[220:223], v[122:125]
	v_mfma_f32_16x16x32_bf16 v[110:113], v[168:171], v[228:231], v[110:113]
	v_mfma_f32_16x16x32_bf16 v[106:109], v[176:179], v[228:231], v[106:109]
	v_mfma_f32_16x16x32_bf16 v[94:97], v[168:171], v[236:239], v[94:97]
	v_mfma_f32_16x16x32_bf16 v[90:93], v[176:179], v[236:239], v[90:93]
	v_mfma_f32_16x16x32_bf16 v[134:137], v[180:183], v[196:199], 0
	v_mfma_f32_16x16x32_bf16 v[130:133], v[188:191], v[196:199], 0
	v_mfma_f32_16x16x32_bf16 v[118:121], v[180:183], v[216:219], 0
	v_mfma_f32_16x16x32_bf16 v[114:117], v[188:191], v[216:219], 0
	v_mfma_f32_16x16x32_bf16 v[102:105], v[180:183], v[224:227], 0
	v_mfma_f32_16x16x32_bf16 v[98:101], v[188:191], v[224:227], 0
	v_mfma_f32_16x16x32_bf16 v[86:89], v[180:183], v[232:235], 0
	v_mfma_f32_16x16x32_bf16 v[82:85], v[188:191], v[232:235], 0
	v_mfma_f32_16x16x32_bf16 v[134:137], v[184:187], v[200:203], v[134:137]
	v_mfma_f32_16x16x32_bf16 v[130:133], v[192:195], v[200:203], v[130:133]
	v_mfma_f32_16x16x32_bf16 v[118:121], v[184:187], v[220:223], v[118:121]
	v_mfma_f32_16x16x32_bf16 v[114:117], v[192:195], v[220:223], v[114:117]
	v_mfma_f32_16x16x32_bf16 v[102:105], v[184:187], v[228:231], v[102:105]
	v_mfma_f32_16x16x32_bf16 v[98:101], v[192:195], v[228:231], v[98:101]
	v_mfma_f32_16x16x32_bf16 v[86:89], v[184:187], v[236:239], v[86:89]
	v_mfma_f32_16x16x32_bf16 v[82:85], v[192:195], v[236:239], v[82:85]
	s_barrier
	s_add_i32 s65, s90, s34
	s_mov_b32 m0, s65
	ds_read_b128 v[196:199], v163 offset:16384
	ds_read_b128 v[200:203], v163 offset:17408
	ds_read_b128 v[216:219], v163 offset:18432
	ds_read_b128 v[220:223], v163 offset:19456
	ds_read_b128 v[224:227], v163 offset:20480
	ds_read_b128 v[228:231], v163 offset:21504
	ds_read_b128 v[232:235], v163 offset:22528
	ds_read_b128 v[236:239], v163 offset:23552
	global_load_lds_dwordx4 v148, s[22:23]
	s_add_i32 m0, s65, 0x2000
	s_add_u32 s66, s22, 0x40000
	s_addc_u32 s67, s23, 0
	s_add_i32 s65, s81, s34
	global_load_lds_dwordx4 v152, s[22:23]
	s_mov_b32 m0, s65
	s_nop 0
	global_load_lds_dwordx4 v148, s[66:67]
	s_add_i32 m0, s65, 0x2000
	s_nop 0
	global_load_lds_dwordx4 v152, s[66:67]
	s_mov_b32 m0, s35
	s_nop 0
	global_load_lds_dwordx4 v146, s[24:25]
	s_mov_b32 m0, s36
	s_nop 0
	global_load_lds_dwordx4 v150, s[24:25]
	s_waitcnt vmcnt(8) lgkmcnt(0)
	s_barrier
	v_mfma_f32_16x16x32_bf16 v[78:81], v[164:167], v[196:199], 0
	v_mfma_f32_16x16x32_bf16 v[74:77], v[172:175], v[196:199], 0
	v_mfma_f32_16x16x32_bf16 v[62:65], v[164:167], v[216:219], 0
	v_mfma_f32_16x16x32_bf16 v[58:61], v[172:175], v[216:219], 0
	v_mfma_f32_16x16x32_bf16 v[46:49], v[164:167], v[224:227], 0
	v_mfma_f32_16x16x32_bf16 v[42:45], v[172:175], v[224:227], 0
	v_mfma_f32_16x16x32_bf16 v[30:33], v[164:167], v[232:235], 0
	v_mfma_f32_16x16x32_bf16 v[26:29], v[172:175], v[232:235], 0
	v_mfma_f32_16x16x32_bf16 v[78:81], v[168:171], v[200:203], v[78:81]
	v_mfma_f32_16x16x32_bf16 v[74:77], v[176:179], v[200:203], v[74:77]
	v_mfma_f32_16x16x32_bf16 v[62:65], v[168:171], v[220:223], v[62:65]
	v_mfma_f32_16x16x32_bf16 v[58:61], v[176:179], v[220:223], v[58:61]
	v_mfma_f32_16x16x32_bf16 v[46:49], v[168:171], v[228:231], v[46:49]
	v_mfma_f32_16x16x32_bf16 v[42:45], v[176:179], v[228:231], v[42:45]
	v_mfma_f32_16x16x32_bf16 v[30:33], v[168:171], v[236:239], v[30:33]
	v_mfma_f32_16x16x32_bf16 v[26:29], v[176:179], v[236:239], v[26:29]
	v_mfma_f32_16x16x32_bf16 v[70:73], v[180:183], v[196:199], 0
	v_mfma_f32_16x16x32_bf16 v[66:69], v[188:191], v[196:199], 0
	v_mfma_f32_16x16x32_bf16 v[54:57], v[180:183], v[216:219], 0
	v_mfma_f32_16x16x32_bf16 v[50:53], v[188:191], v[216:219], 0
	v_mfma_f32_16x16x32_bf16 v[38:41], v[180:183], v[224:227], 0
	v_mfma_f32_16x16x32_bf16 v[34:37], v[188:191], v[224:227], 0
	v_mfma_f32_16x16x32_bf16 v[22:25], v[180:183], v[232:235], 0
	v_mfma_f32_16x16x32_bf16 v[18:21], v[188:191], v[232:235], 0
	v_mfma_f32_16x16x32_bf16 v[70:73], v[184:187], v[200:203], v[70:73]
	v_mfma_f32_16x16x32_bf16 v[66:69], v[192:195], v[200:203], v[66:69]
	v_mfma_f32_16x16x32_bf16 v[54:57], v[184:187], v[220:223], v[54:57]
	v_mfma_f32_16x16x32_bf16 v[50:53], v[192:195], v[220:223], v[50:53]
	v_mfma_f32_16x16x32_bf16 v[38:41], v[184:187], v[228:231], v[38:41]
	v_mfma_f32_16x16x32_bf16 v[34:37], v[192:195], v[228:231], v[34:37]
	v_mfma_f32_16x16x32_bf16 v[22:25], v[184:187], v[236:239], v[22:25]
	v_mfma_f32_16x16x32_bf16 v[18:21], v[192:195], v[236:239], v[18:21]
	s_barrier
; #define PG8_STAGE(bufoff, gbase, voff) do { _Pragma("unroll") for (int _i = 0; _i < 2; ++_i) \
;         __builtin_amdgcn_global_load_lds((const unsigned*)((const char*)(gbase) + (voff)[_i]), (PG8_LAS unsigned*)(lds + (bufoff) + ldsw + _i * 8192), 16, 0, 0); } while (0)
; #define PG8_LDA(dst, b, h) do { _Pragma("unroll") for (int m = 0; m < 4; ++m) _Pragma("unroll") for (int k = 0; k < 2; ++k) dst[m][k] = *(const PG8_LAS bf16x8*)(lds + PG8_SA(b, h) + aoff + m * 2048 + k * 1024); } while (0)
; #define PG8_LDB(dst, b, h) do { _Pragma("unroll") for (int n = 0; n < 2; ++n) _Pragma("unroll") for (int k = 0; k < 2; ++k) dst[n][k] = *(const PG8_LAS bf16x8*)(lds + PG8_SB(b, h) + boff + n * 2048 + k * 1024); } while (0)
; #define PG8_MMA(ai, bj, At, Bt) do { __builtin_amdgcn_s_setprio(1); _Pragma("unroll") for (int m = 0; m < 4; ++m) _Pragma("unroll") for (int n = 0; n < 2; ++n) _Pragma("unroll") for (int k = 0; k < 2; ++k) \
;         acc[ai][bj][m][n] = __builtin_amdgcn_mfma_f32_16x16x32_bf16(Bt[n][k], At[m][k], acc[ai][bj][m][n], 0, 0, 0); __builtin_amdgcn_s_setprio(0); } while (0)
; #define PG8_WAIT_V(n) asm volatile("s_waitcnt vmcnt(" #n ")" ::: "memory")
; #define PG8_WAIT_L(n) asm volatile("s_waitcnt lgkmcnt(" #n ")" ::: "memory")
; #define PG8_BAR __builtin_amdgcn_s_barrier()
; #define PG8_SCHED __builtin_amdgcn_sched_barrier(0)
; template <class Epi, class Sched, bool ALIGN_EPI = false, bool SP2 = false>
; __device__ __forceinline__ void gemm_phase(PG8_LAS unsigned char* lds, const Gemm g, const Sched& S, const Epi& E) {
;     ...
;             PG8_LDB(B0, 1, 0); PG8_LDB(B1, 1, 1); PG8_SCHED; PG8_LDA(At, 1, 0); PG8_STAGE(PG8_SA(0, 1), a2 + hstep, voffA);
;             PG8_WAIT_V(8); PG8_WAIT_L(0); PG8_BAR; PG8_MMA(0, 0, At, B0); PG8_MMA(0, 1, At, B1); PG8_BAR; PG8_SCHED;
;             PG8_LDA(At, 1, 1); PG8_STAGE(PG8_SB(1, 0), b3, voffB); PG8_STAGE(PG8_SB(1, 1), b3 + hstep, voffB); PG8_STAGE(PG8_SA(1, 0), a3, voffA);
;             PG8_WAIT_V(8); PG8_WAIT_L(0); PG8_BAR; PG8_MMA(1, 0, At, B0); PG8_MMA(1, 1, At, B1); PG8_BAR; PG8_SCHED;
	v_add_u32_e32 v176, s82, v160
	v_add_u32_e32 v192, s83, v160
	ds_read_b128 v[164:167], v176
	ds_read_b128 v[168:171], v176 offset:1024
	ds_read_b128 v[172:175], v176 offset:2048
	ds_read_b128 v[176:179], v176 offset:3072
	ds_read_b128 v[180:183], v192
	ds_read_b128 v[184:187], v192 offset:1024
	ds_read_b128 v[188:191], v192 offset:2048
	ds_read_b128 v[192:195], v192 offset:3072
	s_add_u32 s24, s24, 0x40000
	s_addc_u32 s25, s25, 0
	s_mov_b32 m0, s37
	ds_read_b128 v[196:199], v163 offset:32768
	ds_read_b128 v[200:203], v163 offset:33792
	ds_read_b128 v[216:219], v163 offset:34816
	ds_read_b128 v[220:223], v163 offset:35840
	ds_read_b128 v[224:227], v163 offset:36864
	ds_read_b128 v[228:231], v163 offset:37888
	ds_read_b128 v[232:235], v163 offset:38912
	ds_read_b128 v[236:239], v163 offset:39936
	global_load_lds_dwordx4 v146, s[24:25]
	s_mov_b32 m0, s38
	s_nop 0
	global_load_lds_dwordx4 v150, s[24:25]
	s_waitcnt vmcnt(8) lgkmcnt(0)
	s_barrier
	v_mfma_f32_16x16x32_bf16 v[142:145], v[164:167], v[196:199], v[142:145]
	v_mfma_f32_16x16x32_bf16 v[138:141], v[172:175], v[196:199], v[138:141]
	v_mfma_f32_16x16x32_bf16 v[126:129], v[164:167], v[216:219], v[126:129]
	v_mfma_f32_16x16x32_bf16 v[122:125], v[172:175], v[216:219], v[122:125]
	v_mfma_f32_16x16x32_bf16 v[110:113], v[164:167], v[224:227], v[110:113]
	v_mfma_f32_16x16x32_bf16 v[106:109], v[172:175], v[224:227], v[106:109]
	v_mfma_f32_16x16x32_bf16 v[94:97], v[164:167], v[232:235], v[94:97]
	v_mfma_f32_16x16x32_bf16 v[90:93], v[172:175], v[232:235], v[90:93]
	v_mfma_f32_16x16x32_bf16 v[142:145], v[168:171], v[200:203], v[142:145]
	v_mfma_f32_16x16x32_bf16 v[138:141], v[176:179], v[200:203], v[138:141]
	v_mfma_f32_16x16x32_bf16 v[126:129], v[168:171], v[220:223], v[126:129]
	v_mfma_f32_16x16x32_bf16 v[122:125], v[176:179], v[220:223], v[122:125]
	v_mfma_f32_16x16x32_bf16 v[110:113], v[168:171], v[228:231], v[110:113]
	v_mfma_f32_16x16x32_bf16 v[106:109], v[176:179], v[228:231], v[106:109]
	v_mfma_f32_16x16x32_bf16 v[94:97], v[168:171], v[236:239], v[94:97]
	v_mfma_f32_16x16x32_bf16 v[90:93], v[176:179], v[236:239], v[90:93]
	v_mfma_f32_16x16x32_bf16 v[134:137], v[180:183], v[196:199], v[134:137]
	v_mfma_f32_16x16x32_bf16 v[130:133], v[188:191], v[196:199], v[130:133]
	v_mfma_f32_16x16x32_bf16 v[118:121], v[180:183], v[216:219], v[118:121]
	v_mfma_f32_16x16x32_bf16 v[114:117], v[188:191], v[216:219], v[114:117]
	v_mfma_f32_16x16x32_bf16 v[102:105], v[180:183], v[224:227], v[102:105]
	v_mfma_f32_16x16x32_bf16 v[98:101], v[188:191], v[224:227], v[98:101]
	v_mfma_f32_16x16x32_bf16 v[86:89], v[180:183], v[232:235], v[86:89]
	v_mfma_f32_16x16x32_bf16 v[82:85], v[188:191], v[232:235], v[82:85]
	v_mfma_f32_16x16x32_bf16 v[134:137], v[184:187], v[200:203], v[134:137]
	v_mfma_f32_16x16x32_bf16 v[130:133], v[192:195], v[200:203], v[130:133]
	v_mfma_f32_16x16x32_bf16 v[118:121], v[184:187], v[220:223], v[118:121]
	v_mfma_f32_16x16x32_bf16 v[114:117], v[192:195], v[220:223], v[114:117]
	v_mfma_f32_16x16x32_bf16 v[102:105], v[184:187], v[228:231], v[102:105]
	v_mfma_f32_16x16x32_bf16 v[98:101], v[192:195], v[228:231], v[98:101]
	v_mfma_f32_16x16x32_bf16 v[86:89], v[184:187], v[236:239], v[86:89]
	v_mfma_f32_16x16x32_bf16 v[82:85], v[192:195], v[236:239], v[82:85]
	s_barrier
	s_add_i32 s24, s82, s34
	s_mov_b32 m0, s24
	ds_read_b128 v[196:199], v163 offset:49152
	ds_read_b128 v[200:203], v163 offset:50176
	ds_read_b128 v[216:219], v163 offset:51200
	ds_read_b128 v[220:223], v163 offset:52224
	ds_read_b128 v[224:227], v163 offset:53248
	ds_read_b128 v[228:231], v163 offset:54272
	ds_read_b128 v[232:235], v163 offset:55296
	ds_read_b128 v[236:239], v163 offset:56320
	global_load_lds_dwordx4 v148, s[98:99]
	s_add_i32 m0, s24, 0x2000
	s_add_u32 s22, s22, 0x40080
	s_addc_u32 s23, s23, 0
	s_add_i32 s24, s83, s34
	global_load_lds_dwordx4 v152, s[98:99]
	s_mov_b32 m0, s24
	s_nop 0
	global_load_lds_dwordx4 v148, s[22:23]
	s_add_i32 m0, s24, 0x2000
	s_nop 0
	global_load_lds_dwordx4 v152, s[22:23]
	s_mov_b32 m0, s39
	s_nop 0
	global_load_lds_dwordx4 v146, s[100:101]
	s_mov_b32 m0, s42
	s_nop 0
	global_load_lds_dwordx4 v150, s[100:101]
	s_waitcnt vmcnt(8) lgkmcnt(0)
	s_barrier
	v_mfma_f32_16x16x32_bf16 v[78:81], v[164:167], v[196:199], v[78:81]
	v_mfma_f32_16x16x32_bf16 v[74:77], v[172:175], v[196:199], v[74:77]
	v_mfma_f32_16x16x32_bf16 v[62:65], v[164:167], v[216:219], v[62:65]
	v_mfma_f32_16x16x32_bf16 v[58:61], v[172:175], v[216:219], v[58:61]
	v_mfma_f32_16x16x32_bf16 v[46:49], v[164:167], v[224:227], v[46:49]
	v_mfma_f32_16x16x32_bf16 v[42:45], v[172:175], v[224:227], v[42:45]
	v_mfma_f32_16x16x32_bf16 v[30:33], v[164:167], v[232:235], v[30:33]
	v_mfma_f32_16x16x32_bf16 v[26:29], v[172:175], v[232:235], v[26:29]
	v_mfma_f32_16x16x32_bf16 v[78:81], v[168:171], v[200:203], v[78:81]
	v_mfma_f32_16x16x32_bf16 v[74:77], v[176:179], v[200:203], v[74:77]
	v_mfma_f32_16x16x32_bf16 v[62:65], v[168:171], v[220:223], v[62:65]
	v_mfma_f32_16x16x32_bf16 v[58:61], v[176:179], v[220:223], v[58:61]
	v_mfma_f32_16x16x32_bf16 v[46:49], v[168:171], v[228:231], v[46:49]
	v_mfma_f32_16x16x32_bf16 v[42:45], v[176:179], v[228:231], v[42:45]
	v_mfma_f32_16x16x32_bf16 v[30:33], v[168:171], v[236:239], v[30:33]
	v_mfma_f32_16x16x32_bf16 v[26:29], v[176:179], v[236:239], v[26:29]
	v_mfma_f32_16x16x32_bf16 v[70:73], v[180:183], v[196:199], v[70:73]
	v_mfma_f32_16x16x32_bf16 v[66:69], v[188:191], v[196:199], v[66:69]
	v_mfma_f32_16x16x32_bf16 v[54:57], v[180:183], v[216:219], v[54:57]
	v_mfma_f32_16x16x32_bf16 v[50:53], v[188:191], v[216:219], v[50:53]
	v_mfma_f32_16x16x32_bf16 v[38:41], v[180:183], v[224:227], v[38:41]
	v_mfma_f32_16x16x32_bf16 v[34:37], v[188:191], v[224:227], v[34:37]
	v_mfma_f32_16x16x32_bf16 v[22:25], v[180:183], v[232:235], v[22:25]
	v_mfma_f32_16x16x32_bf16 v[18:21], v[188:191], v[232:235], v[18:21]
	v_mfma_f32_16x16x32_bf16 v[70:73], v[184:187], v[200:203], v[70:73]
	v_mfma_f32_16x16x32_bf16 v[66:69], v[192:195], v[200:203], v[66:69]
	v_mfma_f32_16x16x32_bf16 v[54:57], v[184:187], v[220:223], v[54:57]
	v_mfma_f32_16x16x32_bf16 v[50:53], v[192:195], v[220:223], v[50:53]
	v_mfma_f32_16x16x32_bf16 v[38:41], v[184:187], v[228:231], v[38:41]
	v_mfma_f32_16x16x32_bf16 v[34:37], v[192:195], v[228:231], v[34:37]
	v_mfma_f32_16x16x32_bf16 v[22:25], v[184:187], v[236:239], v[22:25]
	v_mfma_f32_16x16x32_bf16 v[18:21], v[192:195], v[236:239], v[18:21]
	s_barrier
	s_add_i32 s64, s64, 2
	s_add_u32 s20, s20, 0x100
	s_addc_u32 s21, s21, 0
	s_add_u32 s62, s62, 0x100
	s_addc_u32 s63, s63, 0
; #define PG8_STAGE(bufoff, gbase, voff) do { _Pragma("unroll") for (int _i = 0; _i < 2; ++_i) \
;         __builtin_amdgcn_global_load_lds((const unsigned*)((const char*)(gbase) + (voff)[_i]), (PG8_LAS unsigned*)(lds + (bufoff) + ldsw + _i * 8192), 16, 0, 0); } while (0)
; #define PG8_LDA(dst, b, h) do { _Pragma("unroll") for (int m = 0; m < 4; ++m) _Pragma("unroll") for (int k = 0; k < 2; ++k) dst[m][k] = *(const PG8_LAS bf16x8*)(lds + PG8_SA(b, h) + aoff + m * 2048 + k * 1024); } while (0)
; #define PG8_LDB(dst, b, h) do { _Pragma("unroll") for (int n = 0; n < 2; ++n) _Pragma("unroll") for (int k = 0; k < 2; ++k) dst[n][k] = *(const PG8_LAS bf16x8*)(lds + PG8_SB(b, h) + boff + n * 2048 + k * 1024); } while (0)
; #define PG8_MMA(ai, bj, At, Bt) do { __builtin_amdgcn_s_setprio(1); _Pragma("unroll") for (int m = 0; m < 4; ++m) _Pragma("unroll") for (int n = 0; n < 2; ++n) _Pragma("unroll") for (int k = 0; k < 2; ++k) \
;         acc[ai][bj][m][n] = __builtin_amdgcn_mfma_f32_16x16x32_bf16(Bt[n][k], At[m][k], acc[ai][bj][m][n], 0, 0, 0); __builtin_amdgcn_s_setprio(0); } while (0)
; #define PG8_WAIT_V(n) asm volatile("s_waitcnt vmcnt(" #n ")" ::: "memory")
; #define PG8_WAIT_L(n) asm volatile("s_waitcnt lgkmcnt(" #n ")" ::: "memory")
; #define PG8_BAR __builtin_amdgcn_s_barrier()
; #define PG8_SCHED __builtin_amdgcn_sched_barrier(0)
; template <class Epi, class Sched, bool ALIGN_EPI = false, bool SP2 = false>
; __device__ __forceinline__ void gemm_phase(PG8_LAS unsigned char* lds, const Gemm g, const Sched& S, const Epi& E) {
;     ...
;             PG8_LDB(B0, 0, 0); PG8_LDB(B1, 0, 1); PG8_SCHED; PG8_LDA(At, 0, 0); PG8_STAGE(PG8_SA(1, 1), a1 + hstep, voffA);
;             PG8_WAIT_V(8); PG8_WAIT_L(0); PG8_BAR; PG8_MMA(0, 0, At, B0); PG8_MMA(0, 1, At, B1); PG8_BAR; PG8_SCHED;
;             PG8_LDA(At, 0, 1); PG8_STAGE(PG8_SB(0, 0), b2, voffB); PG8_STAGE(PG8_SB(0, 1), b2 + hstep, voffB); PG8_STAGE(PG8_SA(0, 0), a2, voffA);
;             PG8_WAIT_V(8); PG8_WAIT_L(0); PG8_BAR; PG8_MMA(1, 0, At, B0); PG8_MMA(1, 1, At, B1); PG8_BAR; PG8_SCHED;
.LBB0_762:
	v_add_u32_e32 v158, s90, v160
	ds_read_b128 v[164:167], v158
	ds_read_b128 v[168:171], v158 offset:1024
	ds_read_b128 v[172:175], v158 offset:2048
	ds_read_b128 v[176:179], v158 offset:3072
	v_add_u32_e32 v158, s81, v160
	ds_read_b128 v[180:183], v158
	ds_read_b128 v[184:187], v158 offset:1024
	ds_read_b128 v[188:191], v158 offset:2048
	ds_read_b128 v[192:195], v158 offset:3072
	s_add_u32 s22, s20, 0xfffc0080
	s_addc_u32 s23, s21, -1
	s_cmp_eq_u32 s64, 12
	s_cselect_b32 s25, s13, s23
	s_cselect_b32 s24, s52, s22
	s_cselect_b32 s23, s15, s63
	s_cselect_b32 s22, s53, s62
	s_add_u32 s98, s22, s46
	s_addc_u32 s99, s23, s47
	s_add_u32 s100, s24, s46
	s_addc_u32 s101, s25, s47
	s_add_i32 m0, s35, 0xc000
	ds_read_b128 v[196:199], v163
	ds_read_b128 v[200:203], v163 offset:1024
	ds_read_b128 v[216:219], v163 offset:2048
	ds_read_b128 v[220:223], v163 offset:3072
	ds_read_b128 v[224:227], v163 offset:4096
	ds_read_b128 v[228:231], v163 offset:5120
	ds_read_b128 v[232:235], v163 offset:6144
	ds_read_b128 v[236:239], v163 offset:7168
	global_load_lds_dwordx4 v154, s[20:21]
	s_add_i32 m0, s35, 0xe000
	s_nop 0
	global_load_lds_dwordx4 v156, s[20:21]
	s_waitcnt vmcnt(8) lgkmcnt(0)
	s_barrier
	v_mfma_f32_16x16x32_bf16 v[142:145], v[164:167], v[196:199], v[142:145]
	v_mfma_f32_16x16x32_bf16 v[138:141], v[172:175], v[196:199], v[138:141]
	v_mfma_f32_16x16x32_bf16 v[126:129], v[164:167], v[216:219], v[126:129]
	v_mfma_f32_16x16x32_bf16 v[122:125], v[172:175], v[216:219], v[122:125]
	v_mfma_f32_16x16x32_bf16 v[110:113], v[164:167], v[224:227], v[110:113]
	v_mfma_f32_16x16x32_bf16 v[106:109], v[172:175], v[224:227], v[106:109]
	v_mfma_f32_16x16x32_bf16 v[94:97], v[164:167], v[232:235], v[94:97]
	v_mfma_f32_16x16x32_bf16 v[90:93], v[172:175], v[232:235], v[90:93]
	v_mfma_f32_16x16x32_bf16 v[142:145], v[168:171], v[200:203], v[142:145]
	v_mfma_f32_16x16x32_bf16 v[138:141], v[176:179], v[200:203], v[138:141]
	v_mfma_f32_16x16x32_bf16 v[126:129], v[168:171], v[220:223], v[126:129]
	v_mfma_f32_16x16x32_bf16 v[122:125], v[176:179], v[220:223], v[122:125]
	v_mfma_f32_16x16x32_bf16 v[110:113], v[168:171], v[228:231], v[110:113]
	v_mfma_f32_16x16x32_bf16 v[106:109], v[176:179], v[228:231], v[106:109]
	v_mfma_f32_16x16x32_bf16 v[94:97], v[168:171], v[236:239], v[94:97]
	v_mfma_f32_16x16x32_bf16 v[90:93], v[176:179], v[236:239], v[90:93]
	v_mfma_f32_16x16x32_bf16 v[134:137], v[180:183], v[196:199], v[134:137]
	v_mfma_f32_16x16x32_bf16 v[130:133], v[188:191], v[196:199], v[130:133]
	v_mfma_f32_16x16x32_bf16 v[118:121], v[180:183], v[216:219], v[118:121]
	v_mfma_f32_16x16x32_bf16 v[114:117], v[188:191], v[216:219], v[114:117]
	v_mfma_f32_16x16x32_bf16 v[102:105], v[180:183], v[224:227], v[102:105]
	v_mfma_f32_16x16x32_bf16 v[98:101], v[188:191], v[224:227], v[98:101]
	v_mfma_f32_16x16x32_bf16 v[86:89], v[180:183], v[232:235], v[86:89]
	v_mfma_f32_16x16x32_bf16 v[82:85], v[188:191], v[232:235], v[82:85]
	v_mfma_f32_16x16x32_bf16 v[134:137], v[184:187], v[200:203], v[134:137]
	v_mfma_f32_16x16x32_bf16 v[130:133], v[192:195], v[200:203], v[130:133]
	v_mfma_f32_16x16x32_bf16 v[118:121], v[184:187], v[220:223], v[118:121]
	v_mfma_f32_16x16x32_bf16 v[114:117], v[192:195], v[220:223], v[114:117]
	v_mfma_f32_16x16x32_bf16 v[102:105], v[184:187], v[228:231], v[102:105]
	v_mfma_f32_16x16x32_bf16 v[98:101], v[192:195], v[228:231], v[98:101]
	v_mfma_f32_16x16x32_bf16 v[86:89], v[184:187], v[236:239], v[86:89]
	v_mfma_f32_16x16x32_bf16 v[82:85], v[192:195], v[236:239], v[82:85]
	s_barrier
	s_add_i32 s65, s90, s34
	s_mov_b32 m0, s65
	ds_read_b128 v[196:199], v163 offset:16384
	ds_read_b128 v[200:203], v163 offset:17408
	ds_read_b128 v[216:219], v163 offset:18432
	ds_read_b128 v[220:223], v163 offset:19456
	ds_read_b128 v[224:227], v163 offset:20480
	ds_read_b128 v[228:231], v163 offset:21504
	ds_read_b128 v[232:235], v163 offset:22528
	ds_read_b128 v[236:239], v163 offset:23552
	global_load_lds_dwordx4 v148, s[22:23]
	s_add_i32 m0, s65, 0x2000
	s_add_u32 s66, s22, 0x40000
	s_addc_u32 s67, s23, 0
	s_add_i32 s65, s81, s34
	global_load_lds_dwordx4 v152, s[22:23]
	s_mov_b32 m0, s65
	s_nop 0
	global_load_lds_dwordx4 v148, s[66:67]
	s_add_i32 m0, s65, 0x2000
	s_nop 0
	global_load_lds_dwordx4 v152, s[66:67]
	s_mov_b32 m0, s35
	s_nop 0
	global_load_lds_dwordx4 v146, s[24:25]
	s_mov_b32 m0, s36
	s_nop 0
	global_load_lds_dwordx4 v150, s[24:25]
	s_waitcnt vmcnt(8) lgkmcnt(0)
	s_barrier
	v_mfma_f32_16x16x32_bf16 v[78:81], v[164:167], v[196:199], v[78:81]
	v_mfma_f32_16x16x32_bf16 v[74:77], v[172:175], v[196:199], v[74:77]
	v_mfma_f32_16x16x32_bf16 v[62:65], v[164:167], v[216:219], v[62:65]
	v_mfma_f32_16x16x32_bf16 v[58:61], v[172:175], v[216:219], v[58:61]
	v_mfma_f32_16x16x32_bf16 v[46:49], v[164:167], v[224:227], v[46:49]
	v_mfma_f32_16x16x32_bf16 v[42:45], v[172:175], v[224:227], v[42:45]
	v_mfma_f32_16x16x32_bf16 v[30:33], v[164:167], v[232:235], v[30:33]
	v_mfma_f32_16x16x32_bf16 v[26:29], v[172:175], v[232:235], v[26:29]
	v_mfma_f32_16x16x32_bf16 v[78:81], v[168:171], v[200:203], v[78:81]
	v_mfma_f32_16x16x32_bf16 v[74:77], v[176:179], v[200:203], v[74:77]
	v_mfma_f32_16x16x32_bf16 v[62:65], v[168:171], v[220:223], v[62:65]
	v_mfma_f32_16x16x32_bf16 v[58:61], v[176:179], v[220:223], v[58:61]
	v_mfma_f32_16x16x32_bf16 v[46:49], v[168:171], v[228:231], v[46:49]
	v_mfma_f32_16x16x32_bf16 v[42:45], v[176:179], v[228:231], v[42:45]
	v_mfma_f32_16x16x32_bf16 v[30:33], v[168:171], v[236:239], v[30:33]
	v_mfma_f32_16x16x32_bf16 v[26:29], v[176:179], v[236:239], v[26:29]
	v_mfma_f32_16x16x32_bf16 v[70:73], v[180:183], v[196:199], v[70:73]
	v_mfma_f32_16x16x32_bf16 v[66:69], v[188:191], v[196:199], v[66:69]
	v_mfma_f32_16x16x32_bf16 v[54:57], v[180:183], v[216:219], v[54:57]
	v_mfma_f32_16x16x32_bf16 v[50:53], v[188:191], v[216:219], v[50:53]
	v_mfma_f32_16x16x32_bf16 v[38:41], v[180:183], v[224:227], v[38:41]
	v_mfma_f32_16x16x32_bf16 v[34:37], v[188:191], v[224:227], v[34:37]
	v_mfma_f32_16x16x32_bf16 v[22:25], v[180:183], v[232:235], v[22:25]
	v_mfma_f32_16x16x32_bf16 v[18:21], v[188:191], v[232:235], v[18:21]
	v_mfma_f32_16x16x32_bf16 v[70:73], v[184:187], v[200:203], v[70:73]
	v_mfma_f32_16x16x32_bf16 v[66:69], v[192:195], v[200:203], v[66:69]
	v_mfma_f32_16x16x32_bf16 v[54:57], v[184:187], v[220:223], v[54:57]
	v_mfma_f32_16x16x32_bf16 v[50:53], v[192:195], v[220:223], v[50:53]
	v_mfma_f32_16x16x32_bf16 v[38:41], v[184:187], v[228:231], v[38:41]
	v_mfma_f32_16x16x32_bf16 v[34:37], v[192:195], v[228:231], v[34:37]
	v_mfma_f32_16x16x32_bf16 v[22:25], v[184:187], v[236:239], v[22:25]
	v_mfma_f32_16x16x32_bf16 v[18:21], v[192:195], v[236:239], v[18:21]
	s_barrier
; #define PG8_STAGE(bufoff, gbase, voff) do { _Pragma("unroll") for (int _i = 0; _i < 2; ++_i) \
;         __builtin_amdgcn_global_load_lds((const unsigned*)((const char*)(gbase) + (voff)[_i]), (PG8_LAS unsigned*)(lds + (bufoff) + ldsw + _i * 8192), 16, 0, 0); } while (0)
; #define PG8_LDA(dst, b, h) do { _Pragma("unroll") for (int m = 0; m < 4; ++m) _Pragma("unroll") for (int k = 0; k < 2; ++k) dst[m][k] = *(const PG8_LAS bf16x8*)(lds + PG8_SA(b, h) + aoff + m * 2048 + k * 1024); } while (0)
; #define PG8_LDB(dst, b, h) do { _Pragma("unroll") for (int n = 0; n < 2; ++n) _Pragma("unroll") for (int k = 0; k < 2; ++k) dst[n][k] = *(const PG8_LAS bf16x8*)(lds + PG8_SB(b, h) + boff + n * 2048 + k * 1024); } while (0)
; #define PG8_MMA(ai, bj, At, Bt) do { __builtin_amdgcn_s_setprio(1); _Pragma("unroll") for (int m = 0; m < 4; ++m) _Pragma("unroll") for (int n = 0; n < 2; ++n) _Pragma("unroll") for (int k = 0; k < 2; ++k) \
;         acc[ai][bj][m][n] = __builtin_amdgcn_mfma_f32_16x16x32_bf16(Bt[n][k], At[m][k], acc[ai][bj][m][n], 0, 0, 0); __builtin_amdgcn_s_setprio(0); } while (0)
; #define PG8_WAIT_V(n) asm volatile("s_waitcnt vmcnt(" #n ")" ::: "memory")
; #define PG8_WAIT_L(n) asm volatile("s_waitcnt lgkmcnt(" #n ")" ::: "memory")
; #define PG8_BAR __builtin_amdgcn_s_barrier()
; #define PG8_SCHED __builtin_amdgcn_sched_barrier(0)
; template <class Epi, class Sched, bool ALIGN_EPI = false, bool SP2 = false>
; __device__ __forceinline__ void gemm_phase(PG8_LAS unsigned char* lds, const Gemm g, const Sched& S, const Epi& E) {
;     ...
;             PG8_LDB(B0, 1, 0); PG8_LDB(B1, 1, 1); PG8_SCHED; PG8_LDA(At, 1, 0); PG8_STAGE(PG8_SA(0, 1), a2 + hstep, voffA);
;             PG8_WAIT_V(8); PG8_WAIT_L(0); PG8_BAR; PG8_MMA(0, 0, At, B0); PG8_MMA(0, 1, At, B1); PG8_BAR; PG8_SCHED;
;             PG8_LDA(At, 1, 1); PG8_STAGE(PG8_SB(1, 0), b3, voffB); PG8_STAGE(PG8_SB(1, 1), b3 + hstep, voffB); PG8_STAGE(PG8_SA(1, 0), a3, voffA);
;             PG8_WAIT_V(8); PG8_WAIT_L(0); PG8_BAR; PG8_MMA(1, 0, At, B0); PG8_MMA(1, 1, At, B1); PG8_BAR; PG8_SCHED;
;     ...
;         if constexpr (ALIGN_EPI) { if (wr == 0) PG8_BAR; }
	v_add_u32_e32 v176, s82, v160
	v_add_u32_e32 v192, s83, v160
	ds_read_b128 v[164:167], v176
	ds_read_b128 v[168:171], v176 offset:1024
	ds_read_b128 v[172:175], v176 offset:2048
	ds_read_b128 v[176:179], v176 offset:3072
	ds_read_b128 v[180:183], v192
	ds_read_b128 v[184:187], v192 offset:1024
	ds_read_b128 v[188:191], v192 offset:2048
	ds_read_b128 v[192:195], v192 offset:3072
	s_add_u32 s24, s24, 0x40000
	s_addc_u32 s25, s25, 0
	s_mov_b32 m0, s37
	ds_read_b128 v[196:199], v163 offset:32768
	ds_read_b128 v[200:203], v163 offset:33792
	ds_read_b128 v[216:219], v163 offset:34816
	ds_read_b128 v[220:223], v163 offset:35840
	ds_read_b128 v[224:227], v163 offset:36864
	ds_read_b128 v[228:231], v163 offset:37888
	ds_read_b128 v[232:235], v163 offset:38912
	ds_read_b128 v[236:239], v163 offset:39936
	global_load_lds_dwordx4 v146, s[24:25]
	s_mov_b32 m0, s38
	s_nop 0
	global_load_lds_dwordx4 v150, s[24:25]
	s_waitcnt vmcnt(8) lgkmcnt(0)
	s_barrier
	v_mfma_f32_16x16x32_bf16 v[142:145], v[164:167], v[196:199], v[142:145]
	v_mfma_f32_16x16x32_bf16 v[138:141], v[172:175], v[196:199], v[138:141]
	v_mfma_f32_16x16x32_bf16 v[126:129], v[164:167], v[216:219], v[126:129]
	v_mfma_f32_16x16x32_bf16 v[122:125], v[172:175], v[216:219], v[122:125]
	v_mfma_f32_16x16x32_bf16 v[110:113], v[164:167], v[224:227], v[110:113]
	v_mfma_f32_16x16x32_bf16 v[106:109], v[172:175], v[224:227], v[106:109]
	v_mfma_f32_16x16x32_bf16 v[94:97], v[164:167], v[232:235], v[94:97]
	v_mfma_f32_16x16x32_bf16 v[90:93], v[172:175], v[232:235], v[90:93]
	v_mfma_f32_16x16x32_bf16 v[142:145], v[168:171], v[200:203], v[142:145]
	v_mfma_f32_16x16x32_bf16 v[138:141], v[176:179], v[200:203], v[138:141]
	v_mfma_f32_16x16x32_bf16 v[126:129], v[168:171], v[220:223], v[126:129]
	v_mfma_f32_16x16x32_bf16 v[122:125], v[176:179], v[220:223], v[122:125]
	v_mfma_f32_16x16x32_bf16 v[110:113], v[168:171], v[228:231], v[110:113]
	v_mfma_f32_16x16x32_bf16 v[106:109], v[176:179], v[228:231], v[106:109]
	v_mfma_f32_16x16x32_bf16 v[94:97], v[168:171], v[236:239], v[94:97]
	v_mfma_f32_16x16x32_bf16 v[90:93], v[176:179], v[236:239], v[90:93]
	v_mfma_f32_16x16x32_bf16 v[134:137], v[180:183], v[196:199], v[134:137]
	v_mfma_f32_16x16x32_bf16 v[130:133], v[188:191], v[196:199], v[130:133]
	v_mfma_f32_16x16x32_bf16 v[118:121], v[180:183], v[216:219], v[118:121]
	v_mfma_f32_16x16x32_bf16 v[114:117], v[188:191], v[216:219], v[114:117]
	v_mfma_f32_16x16x32_bf16 v[102:105], v[180:183], v[224:227], v[102:105]
	v_mfma_f32_16x16x32_bf16 v[98:101], v[188:191], v[224:227], v[98:101]
	v_mfma_f32_16x16x32_bf16 v[86:89], v[180:183], v[232:235], v[86:89]
	v_mfma_f32_16x16x32_bf16 v[82:85], v[188:191], v[232:235], v[82:85]
	v_mfma_f32_16x16x32_bf16 v[134:137], v[184:187], v[200:203], v[134:137]
	v_mfma_f32_16x16x32_bf16 v[130:133], v[192:195], v[200:203], v[130:133]
	v_mfma_f32_16x16x32_bf16 v[118:121], v[184:187], v[220:223], v[118:121]
	v_mfma_f32_16x16x32_bf16 v[114:117], v[192:195], v[220:223], v[114:117]
	v_mfma_f32_16x16x32_bf16 v[102:105], v[184:187], v[228:231], v[102:105]
	v_mfma_f32_16x16x32_bf16 v[98:101], v[192:195], v[228:231], v[98:101]
	v_mfma_f32_16x16x32_bf16 v[86:89], v[184:187], v[236:239], v[86:89]
	v_mfma_f32_16x16x32_bf16 v[82:85], v[192:195], v[236:239], v[82:85]
	s_barrier
	s_add_i32 s24, s82, s34
	s_mov_b32 m0, s24
	ds_read_b128 v[196:199], v163 offset:49152
	ds_read_b128 v[200:203], v163 offset:50176
	ds_read_b128 v[216:219], v163 offset:51200
	ds_read_b128 v[220:223], v163 offset:52224
	ds_read_b128 v[224:227], v163 offset:53248
	ds_read_b128 v[228:231], v163 offset:54272
	ds_read_b128 v[232:235], v163 offset:55296
	ds_read_b128 v[236:239], v163 offset:56320
	global_load_lds_dwordx4 v148, s[98:99]
	s_add_i32 m0, s24, 0x2000
	s_add_u32 s22, s22, 0x40080
	s_addc_u32 s23, s23, 0
	s_add_i32 s24, s83, s34
	global_load_lds_dwordx4 v152, s[98:99]
	s_mov_b32 m0, s24
	s_nop 0
	global_load_lds_dwordx4 v148, s[22:23]
	s_add_i32 m0, s24, 0x2000
	s_nop 0
	global_load_lds_dwordx4 v152, s[22:23]
	s_mov_b32 m0, s39
	s_nop 0
	global_load_lds_dwordx4 v146, s[100:101]
	s_mov_b32 m0, s42
	s_nop 0
	global_load_lds_dwordx4 v150, s[100:101]
	s_waitcnt vmcnt(8) lgkmcnt(0)
	s_barrier
	v_mfma_f32_16x16x32_bf16 v[78:81], v[164:167], v[196:199], v[78:81]
	v_mfma_f32_16x16x32_bf16 v[74:77], v[172:175], v[196:199], v[74:77]
	v_mfma_f32_16x16x32_bf16 v[62:65], v[164:167], v[216:219], v[62:65]
	v_mfma_f32_16x16x32_bf16 v[58:61], v[172:175], v[216:219], v[58:61]
	v_mfma_f32_16x16x32_bf16 v[46:49], v[164:167], v[224:227], v[46:49]
	v_mfma_f32_16x16x32_bf16 v[42:45], v[172:175], v[224:227], v[42:45]
	v_mfma_f32_16x16x32_bf16 v[30:33], v[164:167], v[232:235], v[30:33]
	v_mfma_f32_16x16x32_bf16 v[26:29], v[172:175], v[232:235], v[26:29]
	v_mfma_f32_16x16x32_bf16 v[78:81], v[168:171], v[200:203], v[78:81]
	v_mfma_f32_16x16x32_bf16 v[74:77], v[176:179], v[200:203], v[74:77]
	v_mfma_f32_16x16x32_bf16 v[62:65], v[168:171], v[220:223], v[62:65]
	v_mfma_f32_16x16x32_bf16 v[58:61], v[176:179], v[220:223], v[58:61]
	v_mfma_f32_16x16x32_bf16 v[46:49], v[168:171], v[228:231], v[46:49]
	v_mfma_f32_16x16x32_bf16 v[42:45], v[176:179], v[228:231], v[42:45]
	v_mfma_f32_16x16x32_bf16 v[30:33], v[168:171], v[236:239], v[30:33]
	v_mfma_f32_16x16x32_bf16 v[26:29], v[176:179], v[236:239], v[26:29]
	v_mfma_f32_16x16x32_bf16 v[70:73], v[180:183], v[196:199], v[70:73]
	v_mfma_f32_16x16x32_bf16 v[66:69], v[188:191], v[196:199], v[66:69]
	v_mfma_f32_16x16x32_bf16 v[54:57], v[180:183], v[216:219], v[54:57]
	v_mfma_f32_16x16x32_bf16 v[50:53], v[188:191], v[216:219], v[50:53]
	v_mfma_f32_16x16x32_bf16 v[38:41], v[180:183], v[224:227], v[38:41]
	v_mfma_f32_16x16x32_bf16 v[34:37], v[188:191], v[224:227], v[34:37]
	v_mfma_f32_16x16x32_bf16 v[22:25], v[180:183], v[232:235], v[22:25]
	v_mfma_f32_16x16x32_bf16 v[18:21], v[188:191], v[232:235], v[18:21]
	v_mfma_f32_16x16x32_bf16 v[70:73], v[184:187], v[200:203], v[70:73]
	v_mfma_f32_16x16x32_bf16 v[66:69], v[192:195], v[200:203], v[66:69]
	v_mfma_f32_16x16x32_bf16 v[54:57], v[184:187], v[220:223], v[54:57]
	v_mfma_f32_16x16x32_bf16 v[50:53], v[192:195], v[220:223], v[50:53]
	v_mfma_f32_16x16x32_bf16 v[38:41], v[184:187], v[228:231], v[38:41]
	v_mfma_f32_16x16x32_bf16 v[34:37], v[192:195], v[228:231], v[34:37]
	v_mfma_f32_16x16x32_bf16 v[22:25], v[184:187], v[236:239], v[22:25]
	v_mfma_f32_16x16x32_bf16 v[18:21], v[192:195], v[236:239], v[18:21]
	s_barrier
	s_add_i32 s64, s64, 2
	s_add_u32 s20, s20, 0x100
	s_addc_u32 s21, s21, 0
	s_add_u32 s62, s62, 0x100
	s_addc_u32 s63, s63, 0
	s_cmp_gt_u32 s64, 13
	s_cbranch_scc0 .LBB0_762
	s_setprio 0
	s_and_b64 vcc, exec, s[10:11]
	s_cbranch_vccz .LBB0_765
	s_barrier
